# v33 + post-MFMA SALU/VALU tail (m0/address/loop-counter prep) moved from before the segment-closing s_barrier to after it; bit-identical
# baseline (speedup 1.0000x reference)
; #define PG8_WAIT_V(n) asm volatile("s_waitcnt vmcnt(" #n ")" ::: "memory")
; #define PG8_WAIT_L(n) asm volatile("s_waitcnt lgkmcnt(" #n ")" ::: "memory")
; #define PG8_BAR __builtin_amdgcn_s_barrier()
; #define PG8_SCHED __builtin_amdgcn_sched_barrier(0)
; template <class Epi, class AddrA, class AddrB>
; __device__ __forceinline__ void gemm_phase(const Sched S, const int lda, const int ldb, const int K, const AddrA addrA,
;                                            const AddrB addrB, const Epi E) {
;     ...
;     const bool has_next = S.next(ui + 1, nxt);
;     const char* nA = has_next ? addrA(nxt) : cA;
;     const char* nB = has_next ? addrB(nxt) : cB;
;     for (int t = 0; t < nt; t += 2) {
;       const bool last = (t == nt - 2);
;       const char* a1 = cA + (size_t)(t + 1) * kstep;
;       const char* a2 = last ? nA : cA + (size_t)(t + 2) * kstep;
;       const char* b2 = last ? nB : cB + (size_t)(t + 2) * kstep;
;       const char* a3 = a2 + kstep;
;       const char* b3 = b2 + kstep;
;       PG8_LDB(B0, 0, 0); PG8_SCHED; PG8_LDA(At, 0, 0); PG8_STAGE(PG8_SA(1, 1), a1 + hstepA, voffA);
;       PG8_WAIT_L(8); PG8_BAR; PG8_WAIT_L(0); PG8_MMA(0, 0, At, B0); PG8_BAR; PG8_SCHED;
;       PG8_LDB(B1, 0, 1); PG8_STAGE(PG8_SB(0, 0), b2, voffB);
;       PG8_BAR; PG8_WAIT_L(0); PG8_MMA(0, 1, At, B1); PG8_BAR;
;       PG8_LDA(At, 0, 1); PG8_STAGE(PG8_SA(0, 0), a2, voffA);
;       PG8_BAR; PG8_WAIT_L(0); PG8_MMA(1, 0, At, B0); PG8_BAR; PG8_SCHED;
;       PG8_STAGE(PG8_SB(0, 1), b2 + hstepB, voffB);
;       PG8_WAIT_V(6); PG8_BAR; PG8_MMA(1, 1, At, B1); PG8_BAR;
;       PG8_LDB(B0, 1, 0); PG8_SCHED; PG8_LDA(At, 1, 0); PG8_STAGE(PG8_SA(0, 1), a2 + hstepA, voffA);
;       PG8_WAIT_L(8); PG8_BAR; PG8_WAIT_L(0); PG8_MMA(0, 0, At, B0); PG8_BAR; PG8_SCHED;
;       PG8_LDB(B1, 1, 1); PG8_STAGE(PG8_SB(1, 0), b3, voffB);
;       PG8_BAR; PG8_WAIT_L(0); PG8_MMA(0, 1, At, B1); PG8_BAR;
;       PG8_LDA(At, 1, 1); PG8_STAGE(PG8_SA(1, 0), a3, voffA);
;       PG8_BAR; PG8_WAIT_L(0); PG8_MMA(1, 0, At, B0); PG8_BAR; PG8_SCHED;
;       PG8_STAGE(PG8_SB(1, 1), b3 + hstepB, voffB);
;       PG8_WAIT_V(6); PG8_BAR; PG8_MMA(1, 1, At, B1); PG8_BAR;
.LBB0_108:
	s_ashr_i32 s1, s0, 31
	s_lshl_b64 s[6:7], s[0:1], 20
	s_add_u32 s6, s20, s6
	s_addc_u32 s7, s21, s7
	s_and_b64 s[8:9], s[16:17], exec
	s_cselect_b32 s1, s7, s15
	s_cselect_b32 s11, s6, s14
	s_ashr_i32 s3, s2, 31
	s_lshl_b64 s[8:9], s[2:3], 20
	s_add_u32 s8, s22, s8
	s_addc_u32 s9, s23, s9
	s_and_b64 s[16:17], s[16:17], exec
	s_cselect_b32 s3, s9, s13
	s_cselect_b32 s36, s8, s12
	s_add_u32 s37, s12, 0x100
	s_addc_u32 s38, s13, 0
	s_add_u32 s12, s14, 0x80080
	s_addc_u32 s13, s15, 0
	s_mov_b32 s39, -2
	s_add_u32 s14, s12, 0xfff80080
	s_addc_u32 s15, s13, -1
	s_add_i32 s40, 0, 0x10000
	v_add_u32_e32 v142, s40, v145
	ds_read_b128 v[148:151], v142
	ds_read_b128 v[152:155], v142 offset:1024
	ds_read_b128 v[156:159], v142 offset:2048
	ds_read_b128 v[160:163], v142 offset:3072
	s_cmp_eq_u32 s39, 28
	s_cselect_b32 s17, s1, s15
	s_cselect_b32 s16, s11, s14
	s_cselect_b32 s15, s3, s38
	s_cselect_b32 s14, s36, s37
	v_lshl_add_u64 v[142:143], s[12:13], 0, v[140:141]
	s_add_i32 m0, s24, 0xc000
	ds_read_b128 v[168:171], v146
	ds_read_b128 v[172:175], v146 offset:1024
	ds_read_b128 v[176:179], v146 offset:2048
	ds_read_b128 v[180:183], v146 offset:3072
	ds_read_b128 v[184:187], v146 offset:4096
	ds_read_b128 v[188:191], v146 offset:5120
	ds_read_b128 v[192:195], v146 offset:6144
	ds_read_b128 v[212:215], v146 offset:7168
	global_load_lds_dwordx4 v[142:143], off
	v_lshl_add_u64 v[142:143], s[12:13], 0, v[138:139]
	s_add_i32 m0, s24, 0xe000
	s_nop 0
	global_load_lds_dwordx4 v[142:143], off
	s_waitcnt lgkmcnt(8)
	s_setprio 1
	s_barrier
	s_waitcnt lgkmcnt(0)
	v_mfma_f32_16x16x32_bf16 v[128:131], v[148:151], v[168:171], 0
	v_mfma_f32_16x16x32_bf16 v[128:131], v[152:155], v[172:175], v[128:131]
	v_mfma_f32_16x16x32_bf16 v[120:123], v[148:151], v[176:179], 0
	v_mfma_f32_16x16x32_bf16 v[120:123], v[152:155], v[180:183], v[120:123]
	v_mfma_f32_16x16x32_bf16 v[104:107], v[148:151], v[184:187], 0
	v_mfma_f32_16x16x32_bf16 v[104:107], v[152:155], v[188:191], v[104:107]
	v_mfma_f32_16x16x32_bf16 v[88:91], v[148:151], v[192:195], 0
	v_mfma_f32_16x16x32_bf16 v[88:91], v[152:155], v[212:215], v[88:91]
	v_mfma_f32_16x16x32_bf16 v[124:127], v[156:159], v[168:171], 0
	v_mfma_f32_16x16x32_bf16 v[124:127], v[160:163], v[172:175], v[124:127]
	v_mfma_f32_16x16x32_bf16 v[112:115], v[156:159], v[176:179], 0
	v_mfma_f32_16x16x32_bf16 v[112:115], v[160:163], v[180:183], v[112:115]
	v_mfma_f32_16x16x32_bf16 v[96:99], v[156:159], v[184:187], 0
	v_mfma_f32_16x16x32_bf16 v[96:99], v[160:163], v[188:191], v[96:99]
	v_mfma_f32_16x16x32_bf16 v[80:83], v[156:159], v[192:195], 0
	v_mfma_f32_16x16x32_bf16 v[80:83], v[160:163], v[212:215], v[80:83]
	s_barrier
	s_setprio 0
	s_add_i32 s42, 0, 0x14000
	v_add_u32_e32 v142, s42, v145
	s_add_i32 s40, s40, s19
	ds_read_b128 v[216:219], v142
	ds_read_b128 v[220:223], v142 offset:1024
	ds_read_b128 v[224:227], v142 offset:2048
	ds_read_b128 v[228:231], v142 offset:3072
	v_lshl_add_u64 v[142:143], s[14:15], 0, v[134:135]
	s_mov_b32 m0, s40
	v_lshl_add_u64 v[196:197], s[14:15], 0, v[0:1]
	global_load_lds_dwordx4 v[142:143], off
	s_add_i32 m0, s40, 0x2000
	s_nop 0
	global_load_lds_dwordx4 v[196:197], off
	s_setprio 1
	s_barrier
	s_waitcnt lgkmcnt(0)
	v_mfma_f32_16x16x32_bf16 v[116:119], v[216:219], v[168:171], 0
	v_mfma_f32_16x16x32_bf16 v[116:119], v[220:223], v[172:175], v[116:119]
	v_mfma_f32_16x16x32_bf16 v[100:103], v[216:219], v[176:179], 0
	v_mfma_f32_16x16x32_bf16 v[100:103], v[220:223], v[180:183], v[100:103]
	v_mfma_f32_16x16x32_bf16 v[84:87], v[216:219], v[184:187], 0
	v_mfma_f32_16x16x32_bf16 v[84:87], v[220:223], v[188:191], v[84:87]
	v_mfma_f32_16x16x32_bf16 v[72:75], v[216:219], v[192:195], 0
	v_mfma_f32_16x16x32_bf16 v[72:75], v[220:223], v[212:215], v[72:75]
	v_mfma_f32_16x16x32_bf16 v[108:111], v[224:227], v[168:171], 0
	v_mfma_f32_16x16x32_bf16 v[108:111], v[228:231], v[172:175], v[108:111]
	v_mfma_f32_16x16x32_bf16 v[92:95], v[224:227], v[176:179], 0
	v_mfma_f32_16x16x32_bf16 v[92:95], v[228:231], v[180:183], v[92:95]
	v_mfma_f32_16x16x32_bf16 v[76:79], v[224:227], v[184:187], 0
	v_mfma_f32_16x16x32_bf16 v[76:79], v[228:231], v[188:191], v[76:79]
	v_mfma_f32_16x16x32_bf16 v[68:71], v[224:227], v[192:195], 0
	v_mfma_f32_16x16x32_bf16 v[68:71], v[228:231], v[212:215], v[68:71]
	s_barrier
	s_setprio 0
	s_mov_b32 m0, s24
	v_lshl_add_u64 v[232:233], s[16:17], 0, v[136:137]
	ds_read_b128 v[168:171], v146 offset:16384
	ds_read_b128 v[172:175], v146 offset:17408
	ds_read_b128 v[176:179], v146 offset:18432
	ds_read_b128 v[180:183], v146 offset:19456
	ds_read_b128 v[184:187], v146 offset:20480
	ds_read_b128 v[188:191], v146 offset:21504
	ds_read_b128 v[192:195], v146 offset:22528
	ds_read_b128 v[212:215], v146 offset:23552
	global_load_lds_dwordx4 v[232:233], off
	v_lshl_add_u64 v[234:235], s[16:17], 0, v[132:133]
	s_mov_b32 m0, s25
	s_nop 0
	global_load_lds_dwordx4 v[234:235], off
	s_setprio 1
	s_barrier
	s_waitcnt lgkmcnt(0)
	v_mfma_f32_16x16x32_bf16 v[64:67], v[148:151], v[168:171], 0
	v_mfma_f32_16x16x32_bf16 v[64:67], v[152:155], v[172:175], v[64:67]
	v_mfma_f32_16x16x32_bf16 v[56:59], v[148:151], v[176:179], 0
	v_mfma_f32_16x16x32_bf16 v[56:59], v[152:155], v[180:183], v[56:59]
	v_mfma_f32_16x16x32_bf16 v[40:43], v[148:151], v[184:187], 0
	v_mfma_f32_16x16x32_bf16 v[40:43], v[152:155], v[188:191], v[40:43]
	v_mfma_f32_16x16x32_bf16 v[24:27], v[148:151], v[192:195], 0
	v_mfma_f32_16x16x32_bf16 v[24:27], v[152:155], v[212:215], v[24:27]
	v_mfma_f32_16x16x32_bf16 v[60:63], v[156:159], v[168:171], 0
	v_mfma_f32_16x16x32_bf16 v[60:63], v[160:163], v[172:175], v[60:63]
	v_mfma_f32_16x16x32_bf16 v[48:51], v[156:159], v[176:179], 0
	v_mfma_f32_16x16x32_bf16 v[48:51], v[160:163], v[180:183], v[48:51]
	v_mfma_f32_16x16x32_bf16 v[32:35], v[156:159], v[184:187], 0
	v_mfma_f32_16x16x32_bf16 v[32:35], v[160:163], v[188:191], v[32:35]
	v_mfma_f32_16x16x32_bf16 v[16:19], v[156:159], v[192:195], 0
	v_mfma_f32_16x16x32_bf16 v[16:19], v[160:163], v[212:215], v[16:19]
	s_barrier
; #define PG8_WAIT_V(n) asm volatile("s_waitcnt vmcnt(" #n ")" ::: "memory")
; #define PG8_WAIT_L(n) asm volatile("s_waitcnt lgkmcnt(" #n ")" ::: "memory")
; #define PG8_BAR __builtin_amdgcn_s_barrier()
; #define PG8_SCHED __builtin_amdgcn_sched_barrier(0)
; template <class Epi, class AddrA, class AddrB>
; __device__ __forceinline__ void gemm_phase(const Sched S, const int lda, const int ldb, const int K, const AddrA addrA,
;                                            const AddrB addrB, const Epi E) {
;     ...
;       PG8_LDB(B0, 0, 0); PG8_SCHED; PG8_LDA(At, 0, 0); PG8_STAGE(PG8_SA(1, 1), a1 + hstepA, voffA);
;       PG8_WAIT_L(8); PG8_BAR; PG8_WAIT_L(0); PG8_MMA(0, 0, At, B0); PG8_BAR; PG8_SCHED;
;       PG8_LDB(B1, 0, 1); PG8_STAGE(PG8_SB(0, 0), b2, voffB);
;       PG8_BAR; PG8_WAIT_L(0); PG8_MMA(0, 1, At, B1); PG8_BAR;
;       PG8_LDA(At, 0, 1); PG8_STAGE(PG8_SA(0, 0), a2, voffA);
;       PG8_BAR; PG8_WAIT_L(0); PG8_MMA(1, 0, At, B0); PG8_BAR; PG8_SCHED;
;       PG8_STAGE(PG8_SB(0, 1), b2 + hstepB, voffB);
;       PG8_WAIT_V(6); PG8_BAR; PG8_MMA(1, 1, At, B1); PG8_BAR;
;       PG8_LDB(B0, 1, 0); PG8_SCHED; PG8_LDA(At, 1, 0); PG8_STAGE(PG8_SA(0, 1), a2 + hstepA, voffA);
;       PG8_WAIT_L(8); PG8_BAR; PG8_WAIT_L(0); PG8_MMA(0, 0, At, B0); PG8_BAR; PG8_SCHED;
;       PG8_LDB(B1, 1, 1); PG8_STAGE(PG8_SB(1, 0), b3, voffB);
;       PG8_BAR; PG8_WAIT_L(0); PG8_MMA(0, 1, At, B1); PG8_BAR;
;       PG8_LDA(At, 1, 1); PG8_STAGE(PG8_SA(1, 0), a3, voffA);
;       PG8_BAR; PG8_WAIT_L(0); PG8_MMA(1, 0, At, B0); PG8_BAR; PG8_SCHED;
;       PG8_STAGE(PG8_SB(1, 1), b3 + hstepB, voffB);
;       PG8_WAIT_V(6); PG8_BAR; PG8_MMA(1, 1, At, B1); PG8_BAR;
	s_setprio 0
	s_add_u32 s40, s14, 0x80000
	s_addc_u32 s41, s15, 0
	s_add_i32 s42, s42, s19
	v_lshl_add_u64 v[148:149], s[40:41], 0, v[134:135]
	s_mov_b32 m0, s42
	s_nop 0
	global_load_lds_dwordx4 v[148:149], off
	v_lshl_add_u64 v[148:149], s[40:41], 0, v[0:1]
	s_add_i32 m0, s42, 0x2000
	s_nop 0
	global_load_lds_dwordx4 v[148:149], off
	s_waitcnt vmcnt(6)
	s_setprio 1
	s_barrier
	v_mfma_f32_16x16x32_bf16 v[52:55], v[216:219], v[168:171], 0
	v_mfma_f32_16x16x32_bf16 v[52:55], v[220:223], v[172:175], v[52:55]
	v_mfma_f32_16x16x32_bf16 v[36:39], v[216:219], v[176:179], 0
	v_mfma_f32_16x16x32_bf16 v[36:39], v[220:223], v[180:183], v[36:39]
	v_mfma_f32_16x16x32_bf16 v[20:23], v[216:219], v[184:187], 0
	v_mfma_f32_16x16x32_bf16 v[20:23], v[220:223], v[188:191], v[20:23]
	v_mfma_f32_16x16x32_bf16 v[8:11], v[216:219], v[192:195], 0
	v_mfma_f32_16x16x32_bf16 v[8:11], v[220:223], v[212:215], v[8:11]
	v_mfma_f32_16x16x32_bf16 v[44:47], v[224:227], v[168:171], 0
	v_mfma_f32_16x16x32_bf16 v[44:47], v[228:231], v[172:175], v[44:47]
	v_mfma_f32_16x16x32_bf16 v[28:31], v[224:227], v[176:179], 0
	v_mfma_f32_16x16x32_bf16 v[28:31], v[228:231], v[180:183], v[28:31]
	v_mfma_f32_16x16x32_bf16 v[12:15], v[224:227], v[184:187], 0
	v_mfma_f32_16x16x32_bf16 v[12:15], v[228:231], v[188:191], v[12:15]
	v_mfma_f32_16x16x32_bf16 v[4:7], v[224:227], v[192:195], 0
	v_mfma_f32_16x16x32_bf16 v[4:7], v[228:231], v[212:215], v[4:7]
	s_barrier
	s_setprio 0
	s_add_i32 s40, 0, 0x18000
	v_add_u32_e32 v147, s40, v145
	ds_read_b128 v[148:151], v147
	ds_read_b128 v[152:155], v147 offset:1024
	ds_read_b128 v[156:159], v147 offset:2048
	ds_read_b128 v[160:163], v147 offset:3072
	s_add_u32 s16, s16, 0x80000
	s_addc_u32 s17, s17, 0
	s_mov_b32 m0, s26
	v_lshl_add_u64 v[216:217], s[16:17], 0, v[136:137]
	ds_read_b128 v[168:171], v146 offset:32768
	ds_read_b128 v[172:175], v146 offset:33792
	ds_read_b128 v[176:179], v146 offset:34816
	ds_read_b128 v[180:183], v146 offset:35840
	ds_read_b128 v[184:187], v146 offset:36864
	ds_read_b128 v[188:191], v146 offset:37888
	ds_read_b128 v[192:195], v146 offset:38912
	ds_read_b128 v[212:215], v146 offset:39936
	global_load_lds_dwordx4 v[216:217], off
	v_lshl_add_u64 v[216:217], s[16:17], 0, v[132:133]
	s_mov_b32 m0, s27
	s_nop 0
	global_load_lds_dwordx4 v[216:217], off
	s_waitcnt lgkmcnt(8)
	s_setprio 1
	s_barrier
	s_waitcnt lgkmcnt(0)
	v_mfma_f32_16x16x32_bf16 v[128:131], v[148:151], v[168:171], v[128:131]
	v_mfma_f32_16x16x32_bf16 v[128:131], v[152:155], v[172:175], v[128:131]
	v_mfma_f32_16x16x32_bf16 v[120:123], v[148:151], v[176:179], v[120:123]
	v_mfma_f32_16x16x32_bf16 v[120:123], v[152:155], v[180:183], v[120:123]
	v_mfma_f32_16x16x32_bf16 v[104:107], v[148:151], v[184:187], v[104:107]
	v_mfma_f32_16x16x32_bf16 v[104:107], v[152:155], v[188:191], v[104:107]
	v_mfma_f32_16x16x32_bf16 v[88:91], v[148:151], v[192:195], v[88:91]
	v_mfma_f32_16x16x32_bf16 v[88:91], v[152:155], v[212:215], v[88:91]
	v_mfma_f32_16x16x32_bf16 v[124:127], v[156:159], v[168:171], v[124:127]
	v_mfma_f32_16x16x32_bf16 v[124:127], v[160:163], v[172:175], v[124:127]
	v_mfma_f32_16x16x32_bf16 v[112:115], v[156:159], v[176:179], v[112:115]
	v_mfma_f32_16x16x32_bf16 v[112:115], v[160:163], v[180:183], v[112:115]
	v_mfma_f32_16x16x32_bf16 v[96:99], v[156:159], v[184:187], v[96:99]
	v_mfma_f32_16x16x32_bf16 v[96:99], v[160:163], v[188:191], v[96:99]
	v_mfma_f32_16x16x32_bf16 v[80:83], v[156:159], v[192:195], v[80:83]
	v_mfma_f32_16x16x32_bf16 v[80:83], v[160:163], v[212:215], v[80:83]
	s_barrier
	s_setprio 0
	s_add_i32 s16, 0, 0x1c000
	s_add_i32 s17, s40, s19
	v_add_u32_e32 v147, s16, v145
	v_lshl_add_u64 v[142:143], v[142:143], 0, s[52:53]
	s_mov_b32 m0, s17
	ds_read_b128 v[216:219], v147
	ds_read_b128 v[220:223], v147 offset:1024
	ds_read_b128 v[224:227], v147 offset:2048
	ds_read_b128 v[228:231], v147 offset:3072
	global_load_lds_dwordx4 v[142:143], off
	v_lshl_add_u64 v[142:143], v[196:197], 0, s[52:53]
	s_add_i32 m0, s17, 0x2000
	s_nop 0
	global_load_lds_dwordx4 v[142:143], off
	s_setprio 1
	s_barrier
	s_waitcnt lgkmcnt(0)
	v_mfma_f32_16x16x32_bf16 v[116:119], v[216:219], v[168:171], v[116:119]
	v_mfma_f32_16x16x32_bf16 v[116:119], v[220:223], v[172:175], v[116:119]
	v_mfma_f32_16x16x32_bf16 v[100:103], v[216:219], v[176:179], v[100:103]
	v_mfma_f32_16x16x32_bf16 v[100:103], v[220:223], v[180:183], v[100:103]
	v_mfma_f32_16x16x32_bf16 v[84:87], v[216:219], v[184:187], v[84:87]
	v_mfma_f32_16x16x32_bf16 v[84:87], v[220:223], v[188:191], v[84:87]
	v_mfma_f32_16x16x32_bf16 v[72:75], v[216:219], v[192:195], v[72:75]
	v_mfma_f32_16x16x32_bf16 v[72:75], v[220:223], v[212:215], v[72:75]
	v_mfma_f32_16x16x32_bf16 v[108:111], v[224:227], v[168:171], v[108:111]
	v_mfma_f32_16x16x32_bf16 v[108:111], v[228:231], v[172:175], v[108:111]
	v_mfma_f32_16x16x32_bf16 v[92:95], v[224:227], v[176:179], v[92:95]
	v_mfma_f32_16x16x32_bf16 v[92:95], v[228:231], v[180:183], v[92:95]
	v_mfma_f32_16x16x32_bf16 v[76:79], v[224:227], v[184:187], v[76:79]
	v_mfma_f32_16x16x32_bf16 v[76:79], v[228:231], v[188:191], v[76:79]
	v_mfma_f32_16x16x32_bf16 v[68:71], v[224:227], v[192:195], v[68:71]
	v_mfma_f32_16x16x32_bf16 v[68:71], v[228:231], v[212:215], v[68:71]
	s_barrier
	s_setprio 0
	s_mov_b32 m0, s30
	v_lshl_add_u64 v[142:143], v[232:233], 0, s[52:53]
	ds_read_b128 v[168:171], v146 offset:49152
	ds_read_b128 v[172:175], v146 offset:50176
	ds_read_b128 v[176:179], v146 offset:51200
	ds_read_b128 v[180:183], v146 offset:52224
	ds_read_b128 v[184:187], v146 offset:53248
	ds_read_b128 v[188:191], v146 offset:54272
	ds_read_b128 v[192:195], v146 offset:55296
	ds_read_b128 v[212:215], v146 offset:56320
	global_load_lds_dwordx4 v[142:143], off
	v_lshl_add_u64 v[142:143], v[234:235], 0, s[52:53]
	s_mov_b32 m0, s31
	s_nop 0
	global_load_lds_dwordx4 v[142:143], off
	s_setprio 1
	s_barrier
; #define PG8_WAIT_V(n) asm volatile("s_waitcnt vmcnt(" #n ")" ::: "memory")
; #define PG8_WAIT_L(n) asm volatile("s_waitcnt lgkmcnt(" #n ")" ::: "memory")
; #define PG8_BAR __builtin_amdgcn_s_barrier()
; #define PG8_SCHED __builtin_amdgcn_sched_barrier(0)
; template <class Epi, class AddrA, class AddrB>
; __device__ __forceinline__ void gemm_phase(const Sched S, const int lda, const int ldb, const int K, const AddrA addrA,
;                                            const AddrB addrB, const Epi E) {
;     ...
;       PG8_LDB(B0, 0, 0); PG8_SCHED; PG8_LDA(At, 0, 0); PG8_STAGE(PG8_SA(1, 1), a1 + hstepA, voffA);
;       PG8_WAIT_L(8); PG8_BAR; PG8_WAIT_L(0); PG8_MMA(0, 0, At, B0); PG8_BAR; PG8_SCHED;
;       PG8_LDB(B1, 0, 1); PG8_STAGE(PG8_SB(0, 0), b2, voffB);
;       PG8_BAR; PG8_WAIT_L(0); PG8_MMA(0, 1, At, B1); PG8_BAR;
;       PG8_LDA(At, 0, 1); PG8_STAGE(PG8_SA(0, 0), a2, voffA);
;       PG8_BAR; PG8_WAIT_L(0); PG8_MMA(1, 0, At, B0); PG8_BAR; PG8_SCHED;
;       PG8_STAGE(PG8_SB(0, 1), b2 + hstepB, voffB);
;       PG8_WAIT_V(6); PG8_BAR; PG8_MMA(1, 1, At, B1); PG8_BAR;
;       PG8_LDB(B0, 1, 0); PG8_SCHED; PG8_LDA(At, 1, 0); PG8_STAGE(PG8_SA(0, 1), a2 + hstepA, voffA);
;       PG8_WAIT_L(8); PG8_BAR; PG8_WAIT_L(0); PG8_MMA(0, 0, At, B0); PG8_BAR; PG8_SCHED;
;       PG8_LDB(B1, 1, 1); PG8_STAGE(PG8_SB(1, 0), b3, voffB);
;       PG8_BAR; PG8_WAIT_L(0); PG8_MMA(0, 1, At, B1); PG8_BAR;
;       PG8_LDA(At, 1, 1); PG8_STAGE(PG8_SA(1, 0), a3, voffA);
;       PG8_BAR; PG8_WAIT_L(0); PG8_MMA(1, 0, At, B0); PG8_BAR; PG8_SCHED;
;       PG8_STAGE(PG8_SB(1, 1), b3 + hstepB, voffB);
;       PG8_WAIT_V(6); PG8_BAR; PG8_MMA(1, 1, At, B1); PG8_BAR;
	s_waitcnt lgkmcnt(0)
	v_mfma_f32_16x16x32_bf16 v[64:67], v[148:151], v[168:171], v[64:67]
	v_mfma_f32_16x16x32_bf16 v[64:67], v[152:155], v[172:175], v[64:67]
	v_mfma_f32_16x16x32_bf16 v[56:59], v[148:151], v[176:179], v[56:59]
	v_mfma_f32_16x16x32_bf16 v[56:59], v[152:155], v[180:183], v[56:59]
	v_mfma_f32_16x16x32_bf16 v[40:43], v[148:151], v[184:187], v[40:43]
	v_mfma_f32_16x16x32_bf16 v[40:43], v[152:155], v[188:191], v[40:43]
	v_mfma_f32_16x16x32_bf16 v[24:27], v[148:151], v[192:195], v[24:27]
	v_mfma_f32_16x16x32_bf16 v[24:27], v[152:155], v[212:215], v[24:27]
	v_mfma_f32_16x16x32_bf16 v[60:63], v[156:159], v[168:171], v[60:63]
	v_mfma_f32_16x16x32_bf16 v[60:63], v[160:163], v[172:175], v[60:63]
	v_mfma_f32_16x16x32_bf16 v[48:51], v[156:159], v[176:179], v[48:51]
	v_mfma_f32_16x16x32_bf16 v[48:51], v[160:163], v[180:183], v[48:51]
	v_mfma_f32_16x16x32_bf16 v[32:35], v[156:159], v[184:187], v[32:35]
	v_mfma_f32_16x16x32_bf16 v[32:35], v[160:163], v[188:191], v[32:35]
	v_mfma_f32_16x16x32_bf16 v[16:19], v[156:159], v[192:195], v[16:19]
	v_mfma_f32_16x16x32_bf16 v[16:19], v[160:163], v[212:215], v[16:19]
	s_barrier
	s_setprio 0
	s_add_u32 s14, s14, 0x80080
	s_addc_u32 s15, s15, 0
	s_add_i32 s16, s16, s19
	v_lshl_add_u64 v[142:143], s[14:15], 0, v[134:135]
	s_mov_b32 m0, s16
	s_nop 0
	global_load_lds_dwordx4 v[142:143], off
	v_lshl_add_u64 v[142:143], s[14:15], 0, v[0:1]
	s_add_i32 m0, s16, 0x2000
	s_nop 0
	global_load_lds_dwordx4 v[142:143], off
	s_waitcnt vmcnt(6)
	s_setprio 1
	s_barrier
	v_mfma_f32_16x16x32_bf16 v[52:55], v[216:219], v[168:171], v[52:55]
	v_mfma_f32_16x16x32_bf16 v[52:55], v[220:223], v[172:175], v[52:55]
	v_mfma_f32_16x16x32_bf16 v[36:39], v[216:219], v[176:179], v[36:39]
	v_mfma_f32_16x16x32_bf16 v[36:39], v[220:223], v[180:183], v[36:39]
	v_mfma_f32_16x16x32_bf16 v[20:23], v[216:219], v[184:187], v[20:23]
	v_mfma_f32_16x16x32_bf16 v[20:23], v[220:223], v[188:191], v[20:23]
	v_mfma_f32_16x16x32_bf16 v[8:11], v[216:219], v[192:195], v[8:11]
	v_mfma_f32_16x16x32_bf16 v[8:11], v[220:223], v[212:215], v[8:11]
	v_mfma_f32_16x16x32_bf16 v[44:47], v[224:227], v[168:171], v[44:47]
	v_mfma_f32_16x16x32_bf16 v[44:47], v[228:231], v[172:175], v[44:47]
	v_mfma_f32_16x16x32_bf16 v[28:31], v[224:227], v[176:179], v[28:31]
	v_mfma_f32_16x16x32_bf16 v[28:31], v[228:231], v[180:183], v[28:31]
	v_mfma_f32_16x16x32_bf16 v[12:15], v[224:227], v[184:187], v[12:15]
	v_mfma_f32_16x16x32_bf16 v[12:15], v[228:231], v[188:191], v[12:15]
	v_mfma_f32_16x16x32_bf16 v[4:7], v[224:227], v[192:195], v[4:7]
	v_mfma_f32_16x16x32_bf16 v[4:7], v[228:231], v[212:215], v[4:7]
	s_barrier
	s_setprio 0
	s_add_i32 s39, s39, 2
	s_add_u32 s37, s37, 0x100
	s_addc_u32 s38, s38, 0
	s_add_u32 s12, s12, 0x100
	s_addc_u32 s13, s13, 0
	s_cmp_gt_u32 s39, 29
.LBB0_109:
	s_add_u32 s14, s12, 0xfff80080
	s_addc_u32 s15, s13, -1
	s_add_i32 s40, 0, 0x10000
	v_add_u32_e32 v142, s40, v145
	ds_read_b128 v[148:151], v142
	ds_read_b128 v[152:155], v142 offset:1024
	ds_read_b128 v[156:159], v142 offset:2048
	ds_read_b128 v[160:163], v142 offset:3072
	s_cmp_eq_u32 s39, 28
	s_cselect_b32 s17, s1, s15
	s_cselect_b32 s16, s11, s14
	s_cselect_b32 s15, s3, s38
	s_cselect_b32 s14, s36, s37
	v_lshl_add_u64 v[142:143], s[12:13], 0, v[140:141]
	s_add_i32 m0, s24, 0xc000
	ds_read_b128 v[168:171], v146
	ds_read_b128 v[172:175], v146 offset:1024
	ds_read_b128 v[176:179], v146 offset:2048
	ds_read_b128 v[180:183], v146 offset:3072
	ds_read_b128 v[184:187], v146 offset:4096
	ds_read_b128 v[188:191], v146 offset:5120
	ds_read_b128 v[192:195], v146 offset:6144
	ds_read_b128 v[212:215], v146 offset:7168
	global_load_lds_dwordx4 v[142:143], off
	v_lshl_add_u64 v[142:143], s[12:13], 0, v[138:139]
	s_add_i32 m0, s24, 0xe000
	s_nop 0
	global_load_lds_dwordx4 v[142:143], off
	s_waitcnt lgkmcnt(8)
	s_setprio 1
	s_barrier
	s_waitcnt lgkmcnt(0)
	v_mfma_f32_16x16x32_bf16 v[128:131], v[148:151], v[168:171], v[128:131]
	v_mfma_f32_16x16x32_bf16 v[128:131], v[152:155], v[172:175], v[128:131]
	v_mfma_f32_16x16x32_bf16 v[120:123], v[148:151], v[176:179], v[120:123]
	v_mfma_f32_16x16x32_bf16 v[120:123], v[152:155], v[180:183], v[120:123]
	v_mfma_f32_16x16x32_bf16 v[104:107], v[148:151], v[184:187], v[104:107]
	v_mfma_f32_16x16x32_bf16 v[104:107], v[152:155], v[188:191], v[104:107]
	v_mfma_f32_16x16x32_bf16 v[88:91], v[148:151], v[192:195], v[88:91]
	v_mfma_f32_16x16x32_bf16 v[88:91], v[152:155], v[212:215], v[88:91]
	v_mfma_f32_16x16x32_bf16 v[124:127], v[156:159], v[168:171], v[124:127]
	v_mfma_f32_16x16x32_bf16 v[124:127], v[160:163], v[172:175], v[124:127]
	v_mfma_f32_16x16x32_bf16 v[112:115], v[156:159], v[176:179], v[112:115]
	v_mfma_f32_16x16x32_bf16 v[112:115], v[160:163], v[180:183], v[112:115]
	v_mfma_f32_16x16x32_bf16 v[96:99], v[156:159], v[184:187], v[96:99]
	v_mfma_f32_16x16x32_bf16 v[96:99], v[160:163], v[188:191], v[96:99]
	v_mfma_f32_16x16x32_bf16 v[80:83], v[156:159], v[192:195], v[80:83]
	v_mfma_f32_16x16x32_bf16 v[80:83], v[160:163], v[212:215], v[80:83]
	s_barrier
	s_setprio 0
	s_add_i32 s42, 0, 0x14000
	v_add_u32_e32 v142, s42, v145
	s_add_i32 s40, s40, s19
	ds_read_b128 v[216:219], v142
	ds_read_b128 v[220:223], v142 offset:1024
	ds_read_b128 v[224:227], v142 offset:2048
	ds_read_b128 v[228:231], v142 offset:3072
	v_lshl_add_u64 v[142:143], s[14:15], 0, v[134:135]
	s_mov_b32 m0, s40
	v_lshl_add_u64 v[196:197], s[14:15], 0, v[0:1]
	global_load_lds_dwordx4 v[142:143], off
	s_add_i32 m0, s40, 0x2000
	s_nop 0
	global_load_lds_dwordx4 v[196:197], off
	s_setprio 1
	s_barrier
; #define PG8_WAIT_V(n) asm volatile("s_waitcnt vmcnt(" #n ")" ::: "memory")
; #define PG8_WAIT_L(n) asm volatile("s_waitcnt lgkmcnt(" #n ")" ::: "memory")
; #define PG8_BAR __builtin_amdgcn_s_barrier()
; #define PG8_SCHED __builtin_amdgcn_sched_barrier(0)
; template <class Epi, class AddrA, class AddrB>
; __device__ __forceinline__ void gemm_phase(const Sched S, const int lda, const int ldb, const int K, const AddrA addrA,
;                                            const AddrB addrB, const Epi E) {
;     ...
;       PG8_LDB(B0, 0, 0); PG8_SCHED; PG8_LDA(At, 0, 0); PG8_STAGE(PG8_SA(1, 1), a1 + hstepA, voffA);
;       PG8_WAIT_L(8); PG8_BAR; PG8_WAIT_L(0); PG8_MMA(0, 0, At, B0); PG8_BAR; PG8_SCHED;
;       PG8_LDB(B1, 0, 1); PG8_STAGE(PG8_SB(0, 0), b2, voffB);
;       PG8_BAR; PG8_WAIT_L(0); PG8_MMA(0, 1, At, B1); PG8_BAR;
;       PG8_LDA(At, 0, 1); PG8_STAGE(PG8_SA(0, 0), a2, voffA);
;       PG8_BAR; PG8_WAIT_L(0); PG8_MMA(1, 0, At, B0); PG8_BAR; PG8_SCHED;
;       PG8_STAGE(PG8_SB(0, 1), b2 + hstepB, voffB);
;       PG8_WAIT_V(6); PG8_BAR; PG8_MMA(1, 1, At, B1); PG8_BAR;
;       PG8_LDB(B0, 1, 0); PG8_SCHED; PG8_LDA(At, 1, 0); PG8_STAGE(PG8_SA(0, 1), a2 + hstepA, voffA);
;       PG8_WAIT_L(8); PG8_BAR; PG8_WAIT_L(0); PG8_MMA(0, 0, At, B0); PG8_BAR; PG8_SCHED;
;       PG8_LDB(B1, 1, 1); PG8_STAGE(PG8_SB(1, 0), b3, voffB);
;       PG8_BAR; PG8_WAIT_L(0); PG8_MMA(0, 1, At, B1); PG8_BAR;
;       PG8_LDA(At, 1, 1); PG8_STAGE(PG8_SA(1, 0), a3, voffA);
;       PG8_BAR; PG8_WAIT_L(0); PG8_MMA(1, 0, At, B0); PG8_BAR; PG8_SCHED;
;       PG8_STAGE(PG8_SB(1, 1), b3 + hstepB, voffB);
;       PG8_WAIT_V(6); PG8_BAR; PG8_MMA(1, 1, At, B1); PG8_BAR;
	s_waitcnt lgkmcnt(0)
	v_mfma_f32_16x16x32_bf16 v[116:119], v[216:219], v[168:171], v[116:119]
	v_mfma_f32_16x16x32_bf16 v[116:119], v[220:223], v[172:175], v[116:119]
	v_mfma_f32_16x16x32_bf16 v[100:103], v[216:219], v[176:179], v[100:103]
	v_mfma_f32_16x16x32_bf16 v[100:103], v[220:223], v[180:183], v[100:103]
	v_mfma_f32_16x16x32_bf16 v[84:87], v[216:219], v[184:187], v[84:87]
	v_mfma_f32_16x16x32_bf16 v[84:87], v[220:223], v[188:191], v[84:87]
	v_mfma_f32_16x16x32_bf16 v[72:75], v[216:219], v[192:195], v[72:75]
	v_mfma_f32_16x16x32_bf16 v[72:75], v[220:223], v[212:215], v[72:75]
	v_mfma_f32_16x16x32_bf16 v[108:111], v[224:227], v[168:171], v[108:111]
	v_mfma_f32_16x16x32_bf16 v[108:111], v[228:231], v[172:175], v[108:111]
	v_mfma_f32_16x16x32_bf16 v[92:95], v[224:227], v[176:179], v[92:95]
	v_mfma_f32_16x16x32_bf16 v[92:95], v[228:231], v[180:183], v[92:95]
	v_mfma_f32_16x16x32_bf16 v[76:79], v[224:227], v[184:187], v[76:79]
	v_mfma_f32_16x16x32_bf16 v[76:79], v[228:231], v[188:191], v[76:79]
	v_mfma_f32_16x16x32_bf16 v[68:71], v[224:227], v[192:195], v[68:71]
	v_mfma_f32_16x16x32_bf16 v[68:71], v[228:231], v[212:215], v[68:71]
	s_barrier
	s_setprio 0
	s_mov_b32 m0, s24
	v_lshl_add_u64 v[232:233], s[16:17], 0, v[136:137]
	ds_read_b128 v[168:171], v146 offset:16384
	ds_read_b128 v[172:175], v146 offset:17408
	ds_read_b128 v[176:179], v146 offset:18432
	ds_read_b128 v[180:183], v146 offset:19456
	ds_read_b128 v[184:187], v146 offset:20480
	ds_read_b128 v[188:191], v146 offset:21504
	ds_read_b128 v[192:195], v146 offset:22528
	ds_read_b128 v[212:215], v146 offset:23552
	global_load_lds_dwordx4 v[232:233], off
	v_lshl_add_u64 v[234:235], s[16:17], 0, v[132:133]
	s_mov_b32 m0, s25
	s_nop 0
	global_load_lds_dwordx4 v[234:235], off
	s_setprio 1
	s_barrier
	s_waitcnt lgkmcnt(0)
	v_mfma_f32_16x16x32_bf16 v[64:67], v[148:151], v[168:171], v[64:67]
	v_mfma_f32_16x16x32_bf16 v[64:67], v[152:155], v[172:175], v[64:67]
	v_mfma_f32_16x16x32_bf16 v[56:59], v[148:151], v[176:179], v[56:59]
	v_mfma_f32_16x16x32_bf16 v[56:59], v[152:155], v[180:183], v[56:59]
	v_mfma_f32_16x16x32_bf16 v[40:43], v[148:151], v[184:187], v[40:43]
	v_mfma_f32_16x16x32_bf16 v[40:43], v[152:155], v[188:191], v[40:43]
	v_mfma_f32_16x16x32_bf16 v[24:27], v[148:151], v[192:195], v[24:27]
	v_mfma_f32_16x16x32_bf16 v[24:27], v[152:155], v[212:215], v[24:27]
	v_mfma_f32_16x16x32_bf16 v[60:63], v[156:159], v[168:171], v[60:63]
	v_mfma_f32_16x16x32_bf16 v[60:63], v[160:163], v[172:175], v[60:63]
	v_mfma_f32_16x16x32_bf16 v[48:51], v[156:159], v[176:179], v[48:51]
	v_mfma_f32_16x16x32_bf16 v[48:51], v[160:163], v[180:183], v[48:51]
	v_mfma_f32_16x16x32_bf16 v[32:35], v[156:159], v[184:187], v[32:35]
	v_mfma_f32_16x16x32_bf16 v[32:35], v[160:163], v[188:191], v[32:35]
	v_mfma_f32_16x16x32_bf16 v[16:19], v[156:159], v[192:195], v[16:19]
	v_mfma_f32_16x16x32_bf16 v[16:19], v[160:163], v[212:215], v[16:19]
	s_barrier
	s_setprio 0
	s_add_u32 s40, s14, 0x80000
	s_addc_u32 s41, s15, 0
	s_add_i32 s42, s42, s19
	v_lshl_add_u64 v[148:149], s[40:41], 0, v[134:135]
	s_mov_b32 m0, s42
	s_nop 0
	global_load_lds_dwordx4 v[148:149], off
	v_lshl_add_u64 v[148:149], s[40:41], 0, v[0:1]
	s_add_i32 m0, s42, 0x2000
	s_nop 0
	global_load_lds_dwordx4 v[148:149], off
	s_waitcnt vmcnt(6)
	s_setprio 1
	s_barrier
	v_mfma_f32_16x16x32_bf16 v[52:55], v[216:219], v[168:171], v[52:55]
	v_mfma_f32_16x16x32_bf16 v[52:55], v[220:223], v[172:175], v[52:55]
	v_mfma_f32_16x16x32_bf16 v[36:39], v[216:219], v[176:179], v[36:39]
	v_mfma_f32_16x16x32_bf16 v[36:39], v[220:223], v[180:183], v[36:39]
	v_mfma_f32_16x16x32_bf16 v[20:23], v[216:219], v[184:187], v[20:23]
	v_mfma_f32_16x16x32_bf16 v[20:23], v[220:223], v[188:191], v[20:23]
	v_mfma_f32_16x16x32_bf16 v[8:11], v[216:219], v[192:195], v[8:11]
	v_mfma_f32_16x16x32_bf16 v[8:11], v[220:223], v[212:215], v[8:11]
	v_mfma_f32_16x16x32_bf16 v[44:47], v[224:227], v[168:171], v[44:47]
	v_mfma_f32_16x16x32_bf16 v[44:47], v[228:231], v[172:175], v[44:47]
	v_mfma_f32_16x16x32_bf16 v[28:31], v[224:227], v[176:179], v[28:31]
	v_mfma_f32_16x16x32_bf16 v[28:31], v[228:231], v[180:183], v[28:31]
	v_mfma_f32_16x16x32_bf16 v[12:15], v[224:227], v[184:187], v[12:15]
	v_mfma_f32_16x16x32_bf16 v[12:15], v[228:231], v[188:191], v[12:15]
	v_mfma_f32_16x16x32_bf16 v[4:7], v[224:227], v[192:195], v[4:7]
	v_mfma_f32_16x16x32_bf16 v[4:7], v[228:231], v[212:215], v[4:7]
	s_barrier
	s_setprio 0
	s_add_i32 s40, 0, 0x18000
	v_add_u32_e32 v147, s40, v145
	ds_read_b128 v[148:151], v147
	ds_read_b128 v[152:155], v147 offset:1024
	ds_read_b128 v[156:159], v147 offset:2048
	ds_read_b128 v[160:163], v147 offset:3072
	s_add_u32 s16, s16, 0x80000
	s_addc_u32 s17, s17, 0
	s_mov_b32 m0, s26
	v_lshl_add_u64 v[216:217], s[16:17], 0, v[136:137]
	ds_read_b128 v[168:171], v146 offset:32768
	ds_read_b128 v[172:175], v146 offset:33792
	ds_read_b128 v[176:179], v146 offset:34816
	ds_read_b128 v[180:183], v146 offset:35840
	ds_read_b128 v[184:187], v146 offset:36864
	ds_read_b128 v[188:191], v146 offset:37888
	ds_read_b128 v[192:195], v146 offset:38912
	ds_read_b128 v[212:215], v146 offset:39936
	global_load_lds_dwordx4 v[216:217], off
	v_lshl_add_u64 v[216:217], s[16:17], 0, v[132:133]
	s_mov_b32 m0, s27
	s_nop 0
	global_load_lds_dwordx4 v[216:217], off
	s_waitcnt lgkmcnt(8)
	s_setprio 1
	s_barrier
; #define PG8_WAIT_V(n) asm volatile("s_waitcnt vmcnt(" #n ")" ::: "memory")
; #define PG8_WAIT_L(n) asm volatile("s_waitcnt lgkmcnt(" #n ")" ::: "memory")
; #define PG8_BAR __builtin_amdgcn_s_barrier()
; #define PG8_SCHED __builtin_amdgcn_sched_barrier(0)
; template <class Epi, class AddrA, class AddrB>
; __device__ __forceinline__ void gemm_phase(const Sched S, const int lda, const int ldb, const int K, const AddrA addrA,
;                                            const AddrB addrB, const Epi E) {
;     ...
;       PG8_LDB(B0, 0, 0); PG8_SCHED; PG8_LDA(At, 0, 0); PG8_STAGE(PG8_SA(1, 1), a1 + hstepA, voffA);
;       PG8_WAIT_L(8); PG8_BAR; PG8_WAIT_L(0); PG8_MMA(0, 0, At, B0); PG8_BAR; PG8_SCHED;
;       PG8_LDB(B1, 0, 1); PG8_STAGE(PG8_SB(0, 0), b2, voffB);
;       PG8_BAR; PG8_WAIT_L(0); PG8_MMA(0, 1, At, B1); PG8_BAR;
;       PG8_LDA(At, 0, 1); PG8_STAGE(PG8_SA(0, 0), a2, voffA);
;       PG8_BAR; PG8_WAIT_L(0); PG8_MMA(1, 0, At, B0); PG8_BAR; PG8_SCHED;
;       PG8_STAGE(PG8_SB(0, 1), b2 + hstepB, voffB);
;       PG8_WAIT_V(6); PG8_BAR; PG8_MMA(1, 1, At, B1); PG8_BAR;
;       PG8_LDB(B0, 1, 0); PG8_SCHED; PG8_LDA(At, 1, 0); PG8_STAGE(PG8_SA(0, 1), a2 + hstepA, voffA);
;       PG8_WAIT_L(8); PG8_BAR; PG8_WAIT_L(0); PG8_MMA(0, 0, At, B0); PG8_BAR; PG8_SCHED;
;       PG8_LDB(B1, 1, 1); PG8_STAGE(PG8_SB(1, 0), b3, voffB);
;       PG8_BAR; PG8_WAIT_L(0); PG8_MMA(0, 1, At, B1); PG8_BAR;
;       PG8_LDA(At, 1, 1); PG8_STAGE(PG8_SA(1, 0), a3, voffA);
;       PG8_BAR; PG8_WAIT_L(0); PG8_MMA(1, 0, At, B0); PG8_BAR; PG8_SCHED;
;       PG8_STAGE(PG8_SB(1, 1), b3 + hstepB, voffB);
;       PG8_WAIT_V(6); PG8_BAR; PG8_MMA(1, 1, At, B1); PG8_BAR;
	s_waitcnt lgkmcnt(0)
	v_mfma_f32_16x16x32_bf16 v[128:131], v[148:151], v[168:171], v[128:131]
	v_mfma_f32_16x16x32_bf16 v[128:131], v[152:155], v[172:175], v[128:131]
	v_mfma_f32_16x16x32_bf16 v[120:123], v[148:151], v[176:179], v[120:123]
	v_mfma_f32_16x16x32_bf16 v[120:123], v[152:155], v[180:183], v[120:123]
	v_mfma_f32_16x16x32_bf16 v[104:107], v[148:151], v[184:187], v[104:107]
	v_mfma_f32_16x16x32_bf16 v[104:107], v[152:155], v[188:191], v[104:107]
	v_mfma_f32_16x16x32_bf16 v[88:91], v[148:151], v[192:195], v[88:91]
	v_mfma_f32_16x16x32_bf16 v[88:91], v[152:155], v[212:215], v[88:91]
	v_mfma_f32_16x16x32_bf16 v[124:127], v[156:159], v[168:171], v[124:127]
	v_mfma_f32_16x16x32_bf16 v[124:127], v[160:163], v[172:175], v[124:127]
	v_mfma_f32_16x16x32_bf16 v[112:115], v[156:159], v[176:179], v[112:115]
	v_mfma_f32_16x16x32_bf16 v[112:115], v[160:163], v[180:183], v[112:115]
	v_mfma_f32_16x16x32_bf16 v[96:99], v[156:159], v[184:187], v[96:99]
	v_mfma_f32_16x16x32_bf16 v[96:99], v[160:163], v[188:191], v[96:99]
	v_mfma_f32_16x16x32_bf16 v[80:83], v[156:159], v[192:195], v[80:83]
	v_mfma_f32_16x16x32_bf16 v[80:83], v[160:163], v[212:215], v[80:83]
	s_barrier
	s_setprio 0
	s_add_i32 s16, 0, 0x1c000
	s_add_i32 s17, s40, s19
	v_add_u32_e32 v147, s16, v145
	v_lshl_add_u64 v[142:143], v[142:143], 0, s[52:53]
	s_mov_b32 m0, s17
	ds_read_b128 v[216:219], v147
	ds_read_b128 v[220:223], v147 offset:1024
	ds_read_b128 v[224:227], v147 offset:2048
	ds_read_b128 v[228:231], v147 offset:3072
	global_load_lds_dwordx4 v[142:143], off
	v_lshl_add_u64 v[142:143], v[196:197], 0, s[52:53]
	s_add_i32 m0, s17, 0x2000
	s_nop 0
	global_load_lds_dwordx4 v[142:143], off
	s_setprio 1
	s_barrier
	s_waitcnt lgkmcnt(0)
	v_mfma_f32_16x16x32_bf16 v[116:119], v[216:219], v[168:171], v[116:119]
	v_mfma_f32_16x16x32_bf16 v[116:119], v[220:223], v[172:175], v[116:119]
	v_mfma_f32_16x16x32_bf16 v[100:103], v[216:219], v[176:179], v[100:103]
	v_mfma_f32_16x16x32_bf16 v[100:103], v[220:223], v[180:183], v[100:103]
	v_mfma_f32_16x16x32_bf16 v[84:87], v[216:219], v[184:187], v[84:87]
	v_mfma_f32_16x16x32_bf16 v[84:87], v[220:223], v[188:191], v[84:87]
	v_mfma_f32_16x16x32_bf16 v[72:75], v[216:219], v[192:195], v[72:75]
	v_mfma_f32_16x16x32_bf16 v[72:75], v[220:223], v[212:215], v[72:75]
	v_mfma_f32_16x16x32_bf16 v[108:111], v[224:227], v[168:171], v[108:111]
	v_mfma_f32_16x16x32_bf16 v[108:111], v[228:231], v[172:175], v[108:111]
	v_mfma_f32_16x16x32_bf16 v[92:95], v[224:227], v[176:179], v[92:95]
	v_mfma_f32_16x16x32_bf16 v[92:95], v[228:231], v[180:183], v[92:95]
	v_mfma_f32_16x16x32_bf16 v[76:79], v[224:227], v[184:187], v[76:79]
	v_mfma_f32_16x16x32_bf16 v[76:79], v[228:231], v[188:191], v[76:79]
	v_mfma_f32_16x16x32_bf16 v[68:71], v[224:227], v[192:195], v[68:71]
	v_mfma_f32_16x16x32_bf16 v[68:71], v[228:231], v[212:215], v[68:71]
	s_barrier
	s_setprio 0
	s_mov_b32 m0, s30
	v_lshl_add_u64 v[142:143], v[232:233], 0, s[52:53]
	ds_read_b128 v[168:171], v146 offset:49152
	ds_read_b128 v[172:175], v146 offset:50176
	ds_read_b128 v[176:179], v146 offset:51200
	ds_read_b128 v[180:183], v146 offset:52224
	ds_read_b128 v[184:187], v146 offset:53248
	ds_read_b128 v[188:191], v146 offset:54272
	ds_read_b128 v[192:195], v146 offset:55296
	ds_read_b128 v[212:215], v146 offset:56320
	global_load_lds_dwordx4 v[142:143], off
	v_lshl_add_u64 v[142:143], v[234:235], 0, s[52:53]
	s_mov_b32 m0, s31
	s_nop 0
	global_load_lds_dwordx4 v[142:143], off
	s_setprio 1
	s_barrier
	s_waitcnt lgkmcnt(0)
	v_mfma_f32_16x16x32_bf16 v[64:67], v[148:151], v[168:171], v[64:67]
	v_mfma_f32_16x16x32_bf16 v[64:67], v[152:155], v[172:175], v[64:67]
	v_mfma_f32_16x16x32_bf16 v[56:59], v[148:151], v[176:179], v[56:59]
	v_mfma_f32_16x16x32_bf16 v[56:59], v[152:155], v[180:183], v[56:59]
	v_mfma_f32_16x16x32_bf16 v[40:43], v[148:151], v[184:187], v[40:43]
	v_mfma_f32_16x16x32_bf16 v[40:43], v[152:155], v[188:191], v[40:43]
	v_mfma_f32_16x16x32_bf16 v[24:27], v[148:151], v[192:195], v[24:27]
	v_mfma_f32_16x16x32_bf16 v[24:27], v[152:155], v[212:215], v[24:27]
	v_mfma_f32_16x16x32_bf16 v[60:63], v[156:159], v[168:171], v[60:63]
	v_mfma_f32_16x16x32_bf16 v[60:63], v[160:163], v[172:175], v[60:63]
	v_mfma_f32_16x16x32_bf16 v[48:51], v[156:159], v[176:179], v[48:51]
	v_mfma_f32_16x16x32_bf16 v[48:51], v[160:163], v[180:183], v[48:51]
	v_mfma_f32_16x16x32_bf16 v[32:35], v[156:159], v[184:187], v[32:35]
	v_mfma_f32_16x16x32_bf16 v[32:35], v[160:163], v[188:191], v[32:35]
	v_mfma_f32_16x16x32_bf16 v[16:19], v[156:159], v[192:195], v[16:19]
	v_mfma_f32_16x16x32_bf16 v[16:19], v[160:163], v[212:215], v[16:19]
	s_barrier
	s_setprio 0
	s_add_u32 s14, s14, 0x80080
	s_addc_u32 s15, s15, 0
	s_add_i32 s16, s16, s19
	v_lshl_add_u64 v[142:143], s[14:15], 0, v[134:135]
	s_mov_b32 m0, s16
	s_nop 0
	global_load_lds_dwordx4 v[142:143], off
	v_lshl_add_u64 v[142:143], s[14:15], 0, v[0:1]
	s_add_i32 m0, s16, 0x2000
	s_nop 0
	global_load_lds_dwordx4 v[142:143], off
	s_waitcnt vmcnt(6)
	s_setprio 1
	s_barrier
; #define PG8_WAIT_V(n) asm volatile("s_waitcnt vmcnt(" #n ")" ::: "memory")
; #define PG8_WAIT_L(n) asm volatile("s_waitcnt lgkmcnt(" #n ")" ::: "memory")
; #define PG8_BAR __builtin_amdgcn_s_barrier()
; #define PG8_SCHED __builtin_amdgcn_sched_barrier(0)
; template <class Epi, class AddrA, class AddrB>
; __device__ __forceinline__ void gemm_phase(const Sched S, const int lda, const int ldb, const int K, const AddrA addrA,
;                                            const AddrB addrB, const Epi E) {
;     ...
;       PG8_WAIT_V(6); PG8_BAR; PG8_MMA(1, 1, At, B1); PG8_BAR;
;       PG8_LDB(B0, 1, 0); PG8_SCHED; PG8_LDA(At, 1, 0); PG8_STAGE(PG8_SA(0, 1), a2 + hstepA, voffA);
;       PG8_WAIT_L(8); PG8_BAR; PG8_WAIT_L(0); PG8_MMA(0, 0, At, B0); PG8_BAR; PG8_SCHED;
;       PG8_LDB(B1, 1, 1); PG8_STAGE(PG8_SB(1, 0), b3, voffB);
;       PG8_BAR; PG8_WAIT_L(0); PG8_MMA(0, 1, At, B1); PG8_BAR;
;       PG8_LDA(At, 1, 1); PG8_STAGE(PG8_SA(1, 0), a3, voffA);
;       PG8_BAR; PG8_WAIT_L(0); PG8_MMA(1, 0, At, B0); PG8_BAR; PG8_SCHED;
;       PG8_STAGE(PG8_SB(1, 1), b3 + hstepB, voffB);
;       PG8_WAIT_V(6); PG8_BAR; PG8_MMA(1, 1, At, B1); PG8_BAR;
;   __device__ __forceinline__ void operator()(EPI_ARGS) const {
;     bf16_t* base = proj + ((size_t)u.pn * MTOK + (size_t)(u.pm * 256 + wr * 64 + fr)) * PLD + wc * 32 + 8 * fq;
; #pragma unroll
;     for (int ai = 0; ai < 2; ++ai)
; #pragma unroll
;       for (int m = 0; m < 4; ++m) {
;         bf16_t* rowp = base + (size_t)(ai * HALF + m * 16) * PLD;
; #pragma unroll
;         for (int bj = 0; bj < 2; ++bj) {
;           const f32x4 v0 = acc[ai][bj][m][0], v1 = acc[ai][bj][m][1];
;           u32x4 o;
;           o.x = pack2(v0[0], v0[1]); o.y = pack2(v0[2], v0[3]); o.z = pack2(v1[0], v1[1]); o.w = pack2(v1[2], v1[3]);
;           *(u32x4*)(rowp + bj * HALF) = o;
;         }
;       }
	v_mfma_f32_16x16x32_bf16 v[52:55], v[216:219], v[168:171], v[52:55]
	v_mfma_f32_16x16x32_bf16 v[52:55], v[220:223], v[172:175], v[52:55]
	v_mfma_f32_16x16x32_bf16 v[36:39], v[216:219], v[176:179], v[36:39]
	v_mfma_f32_16x16x32_bf16 v[36:39], v[220:223], v[180:183], v[36:39]
	v_mfma_f32_16x16x32_bf16 v[20:23], v[216:219], v[184:187], v[20:23]
	v_mfma_f32_16x16x32_bf16 v[20:23], v[220:223], v[188:191], v[20:23]
	v_mfma_f32_16x16x32_bf16 v[8:11], v[216:219], v[192:195], v[8:11]
	v_mfma_f32_16x16x32_bf16 v[8:11], v[220:223], v[212:215], v[8:11]
	v_mfma_f32_16x16x32_bf16 v[44:47], v[224:227], v[168:171], v[44:47]
	v_mfma_f32_16x16x32_bf16 v[44:47], v[228:231], v[172:175], v[44:47]
	v_mfma_f32_16x16x32_bf16 v[28:31], v[224:227], v[176:179], v[28:31]
	v_mfma_f32_16x16x32_bf16 v[28:31], v[228:231], v[180:183], v[28:31]
	v_mfma_f32_16x16x32_bf16 v[12:15], v[224:227], v[184:187], v[12:15]
	v_mfma_f32_16x16x32_bf16 v[12:15], v[228:231], v[188:191], v[12:15]
	v_mfma_f32_16x16x32_bf16 v[4:7], v[224:227], v[192:195], v[4:7]
	v_mfma_f32_16x16x32_bf16 v[4:7], v[228:231], v[212:215], v[4:7]
	s_barrier
	s_setprio 0
	s_add_i32 s39, s39, 2
	s_add_u32 s37, s37, 0x100
	s_addc_u32 s38, s38, 0
	s_add_u32 s12, s12, 0x100
	s_addc_u32 s13, s13, 0
	s_cmp_gt_u32 s39, 29
	s_cbranch_scc0 .LBB0_109
	s_ashr_i32 s11, s10, 31
	v_lshl_add_u32 v142, s35, 8, v144
	s_lshl_b64 s[10:11], s[10:11], 23
	v_ashrrev_i32_e32 v143, 31, v142
	s_add_u32 s10, s28, s10
	s_addc_u32 s11, s29, s11
	v_lshlrev_b64 v[142:143], 9, v[142:143]
	v_lshl_add_u64 v[142:143], s[10:11], 0, v[142:143]
	v_lshl_add_u64 v[142:143], v[142:143], 0, s[72:73]
	v_lshl_add_u64 v[142:143], v[142:143], 0, v[2:3]
	v_cvt_pk_bf16_f32 v116, v116, v117
	v_cvt_pk_bf16_f32 v117, v118, v119
	v_cvt_pk_bf16_f32 v119, v110, v111
	v_cvt_pk_bf16_f32 v110, v112, v113
	v_add_co_u32_e32 v112, vcc, s96, v142
	s_movk_i32 s1, 0x4000
	s_nop 0
	v_addc_co_u32_e32 v113, vcc, 0, v143, vcc
	v_cvt_pk_bf16_f32 v100, v100, v101
	v_cvt_pk_bf16_f32 v101, v102, v103
	v_cvt_pk_bf16_f32 v103, v94, v95
	v_cvt_pk_bf16_f32 v94, v96, v97
	v_add_co_u32_e32 v96, vcc, s1, v142
	s_movk_i32 s1, 0x6000
	s_nop 0
	v_addc_co_u32_e32 v97, vcc, 0, v143, vcc
	v_cvt_pk_bf16_f32 v84, v84, v85
	v_cvt_pk_bf16_f32 v85, v86, v87
	v_cvt_pk_bf16_f32 v87, v78, v79
	v_cvt_pk_bf16_f32 v78, v80, v81
	v_add_co_u32_e32 v80, vcc, s1, v142
	v_cvt_pk_bf16_f32 v64, v64, v65
	v_cvt_pk_bf16_f32 v65, v66, v67
	v_cvt_pk_bf16_f32 v66, v60, v61
	s_mov_b32 s1, 0x12000
	s_nop 0
	v_addc_co_u32_e32 v81, vcc, 0, v143, vcc
	v_add_co_u32_e32 v60, vcc, s67, v142
	v_cvt_pk_bf16_f32 v52, v52, v53
	v_cvt_pk_bf16_f32 v53, v54, v55
	v_cvt_pk_bf16_f32 v55, v46, v47
	v_cvt_pk_bf16_f32 v46, v48, v49
	s_nop 1
	v_addc_co_u32_e32 v61, vcc, 0, v143, vcc
	v_add_co_u32_e32 v48, vcc, s1, v142
	s_mov_b32 s1, 0x14000
	s_nop 0
	v_addc_co_u32_e32 v49, vcc, 0, v143, vcc
	v_cvt_pk_bf16_f32 v36, v36, v37
	v_cvt_pk_bf16_f32 v37, v38, v39
	v_cvt_pk_bf16_f32 v39, v30, v31
	v_cvt_pk_bf16_f32 v30, v32, v33
	v_add_co_u32_e32 v32, vcc, s1, v142
	s_mov_b32 s1, 0x16000
	s_nop 0
	v_addc_co_u32_e32 v33, vcc, 0, v143, vcc
	v_cvt_pk_bf16_f32 v20, v20, v21
	v_cvt_pk_bf16_f32 v21, v22, v23
	v_cvt_pk_bf16_f32 v23, v14, v15
	v_cvt_pk_bf16_f32 v14, v16, v17
	v_add_co_u32_e32 v16, vcc, s1, v142
	s_mov_b32 s10, s2
	s_nop 0
	v_addc_co_u32_e32 v17, vcc, 0, v143, vcc
	s_and_b64 vcc, exec, s[4:5]
	s_mov_b32 s35, s0
	s_mov_b64 s[12:13], s[8:9]
	s_mov_b64 s[14:15], s[6:7]
	v_cvt_pk_bf16_f32 v128, v128, v129
	v_cvt_pk_bf16_f32 v129, v130, v131
	v_cvt_pk_bf16_f32 v130, v124, v125
	v_cvt_pk_bf16_f32 v131, v126, v127
	flat_store_dwordx4 v[142:143], v[128:131]
	v_cvt_pk_bf16_f32 v118, v108, v109
	flat_store_dwordx4 v[142:143], v[116:119] offset:256
	v_cvt_pk_bf16_f32 v108, v120, v121
	v_cvt_pk_bf16_f32 v109, v122, v123
	v_cvt_pk_bf16_f32 v111, v114, v115
	flat_store_dwordx4 v[112:113], v[108:111]
	v_cvt_pk_bf16_f32 v102, v92, v93
	flat_store_dwordx4 v[112:113], v[100:103] offset:256
	v_cvt_pk_bf16_f32 v92, v104, v105
	v_cvt_pk_bf16_f32 v93, v106, v107
	v_cvt_pk_bf16_f32 v95, v98, v99
	flat_store_dwordx4 v[96:97], v[92:95]
	v_cvt_pk_bf16_f32 v86, v76, v77
	flat_store_dwordx4 v[96:97], v[84:87] offset:256
	v_cvt_pk_bf16_f32 v76, v88, v89
	v_cvt_pk_bf16_f32 v77, v90, v91
	v_cvt_pk_bf16_f32 v79, v82, v83
	flat_store_dwordx4 v[80:81], v[76:79]
	v_cvt_pk_bf16_f32 v72, v72, v73
	v_cvt_pk_bf16_f32 v73, v74, v75
	v_cvt_pk_bf16_f32 v74, v68, v69
	v_cvt_pk_bf16_f32 v75, v70, v71
	flat_store_dwordx4 v[80:81], v[72:75] offset:256
	v_cvt_pk_bf16_f32 v67, v62, v63
	flat_store_dwordx4 v[60:61], v[64:67]
	v_cvt_pk_bf16_f32 v54, v44, v45
	flat_store_dwordx4 v[60:61], v[52:55] offset:256
	v_cvt_pk_bf16_f32 v44, v56, v57
	v_cvt_pk_bf16_f32 v45, v58, v59
	v_cvt_pk_bf16_f32 v47, v50, v51
	flat_store_dwordx4 v[48:49], v[44:47]
	v_cvt_pk_bf16_f32 v38, v28, v29
	flat_store_dwordx4 v[48:49], v[36:39] offset:256
	v_cvt_pk_bf16_f32 v28, v40, v41
	v_cvt_pk_bf16_f32 v29, v42, v43
	v_cvt_pk_bf16_f32 v31, v34, v35
	flat_store_dwordx4 v[32:33], v[28:31]
	v_cvt_pk_bf16_f32 v22, v12, v13
	flat_store_dwordx4 v[32:33], v[20:23] offset:256
	v_cvt_pk_bf16_f32 v12, v24, v25
	v_cvt_pk_bf16_f32 v13, v26, v27
	v_cvt_pk_bf16_f32 v15, v18, v19
	flat_store_dwordx4 v[16:17], v[12:15]
	v_cvt_pk_bf16_f32 v8, v8, v9
	v_cvt_pk_bf16_f32 v9, v10, v11
	v_cvt_pk_bf16_f32 v10, v4, v5
	v_cvt_pk_bf16_f32 v11, v6, v7
	flat_store_dwordx4 v[16:17], v[8:11] offset:256
	s_cbranch_vccz .LBB0_106
	s_waitcnt vmcnt(0)
	s_cmpk_gt_u32 s18, 0xff
	s_cbranch_scc1 .LBB0_113
	s_barrier

; #define PG8_WAIT_V(n) asm volatile("s_waitcnt vmcnt(" #n ")" ::: "memory")
; #define PG8_WAIT_L(n) asm volatile("s_waitcnt lgkmcnt(" #n ")" ::: "memory")
; #define PG8_BAR __builtin_amdgcn_s_barrier()
; #define PG8_SCHED __builtin_amdgcn_sched_barrier(0)
; template <class Epi, class AddrA, class AddrB>
; __device__ __forceinline__ void gemm_phase(const Sched S, const int lda, const int ldb, const int K, const AddrA addrA,
;                                            const AddrB addrB, const Epi E) {
;     ...
;     const bool has_next = S.next(ui + 1, nxt);
;     const char* nA = has_next ? addrA(nxt) : cA;
;     const char* nB = has_next ? addrB(nxt) : cB;
;     for (int t = 0; t < nt; t += 2) {
;       const bool last = (t == nt - 2);
;       const char* a1 = cA + (size_t)(t + 1) * kstep;
;       const char* a2 = last ? nA : cA + (size_t)(t + 2) * kstep;
;       const char* b2 = last ? nB : cB + (size_t)(t + 2) * kstep;
;       const char* a3 = a2 + kstep;
;       const char* b3 = b2 + kstep;
;       PG8_LDB(B0, 0, 0); PG8_SCHED; PG8_LDA(At, 0, 0); PG8_STAGE(PG8_SA(1, 1), a1 + hstepA, voffA);
;       PG8_WAIT_L(8); PG8_BAR; PG8_WAIT_L(0); PG8_MMA(0, 0, At, B0); PG8_BAR; PG8_SCHED;
;       PG8_LDB(B1, 0, 1); PG8_STAGE(PG8_SB(0, 0), b2, voffB);
;       PG8_BAR; PG8_WAIT_L(0); PG8_MMA(0, 1, At, B1); PG8_BAR;
;       PG8_LDA(At, 0, 1); PG8_STAGE(PG8_SA(0, 0), a2, voffA);
;       PG8_BAR; PG8_WAIT_L(0); PG8_MMA(1, 0, At, B0); PG8_BAR; PG8_SCHED;
;       PG8_STAGE(PG8_SB(0, 1), b2 + hstepB, voffB);
;       PG8_WAIT_V(6); PG8_BAR; PG8_MMA(1, 1, At, B1); PG8_BAR;
;       PG8_LDB(B0, 1, 0); PG8_SCHED; PG8_LDA(At, 1, 0); PG8_STAGE(PG8_SA(0, 1), a2 + hstepA, voffA);
;       PG8_WAIT_L(8); PG8_BAR; PG8_WAIT_L(0); PG8_MMA(0, 0, At, B0); PG8_BAR; PG8_SCHED;
;       PG8_LDB(B1, 1, 1); PG8_STAGE(PG8_SB(1, 0), b3, voffB);
;       PG8_BAR; PG8_WAIT_L(0); PG8_MMA(0, 1, At, B1); PG8_BAR;
;       PG8_LDA(At, 1, 1); PG8_STAGE(PG8_SA(1, 0), a3, voffA);
;       PG8_BAR; PG8_WAIT_L(0); PG8_MMA(1, 0, At, B0); PG8_BAR; PG8_SCHED;
;       PG8_STAGE(PG8_SB(1, 1), b3 + hstepB, voffB);
;       PG8_WAIT_V(6); PG8_BAR; PG8_MMA(1, 1, At, B1); PG8_BAR;
.LBB0_484:
	s_ashr_i32 s15, s14, 31
	s_lshl_b64 s[20:21], s[14:15], 20
	s_add_u32 s3, s25, s20
	s_addc_u32 s15, s26, s21
	s_lshl_b32 s17, s16, 8
	s_and_b32 s20, s17, 0xfffffe00
	s_ashr_i32 s21, s20, 31
	s_lshl_b64 s[20:21], s[20:21], 1
	s_add_u32 s20, s3, s20
	s_addc_u32 s21, s15, s21
	s_and_b64 s[22:23], s[10:11], exec
	s_cselect_b32 s3, s21, s7
	s_cselect_b32 s15, s20, s6
	s_ashr_i32 s17, s16, 31
	s_lshl_b64 s[22:23], s[16:17], 18
	s_add_u32 s22, s27, s22
	s_addc_u32 s23, s28, s23
	s_and_b64 s[10:11], s[10:11], exec
	s_cselect_b32 s17, s23, s5
	s_cselect_b32 s40, s22, s4
	s_add_u32 s41, s4, 0x100
	s_addc_u32 s42, s5, 0
	s_add_u32 s4, s6, 0x80080
	s_addc_u32 s5, s7, 0
	s_mov_b32 s43, -2
	s_add_u32 s6, s4, 0xfff80080
	s_addc_u32 s7, s5, -1
	s_add_i32 s44, 0, 0x10000
	v_add_u32_e32 v2, s44, v167
	ds_read_b128 v[92:95], v2
	ds_read_b128 v[100:103], v2 offset:1024
	ds_read_b128 v[132:135], v2 offset:2048
	ds_read_b128 v[144:147], v2 offset:3072
	s_cmp_eq_u32 s43, 4
	s_cselect_b32 s11, s3, s7
	s_cselect_b32 s10, s15, s6
	s_cselect_b32 s7, s17, s42
	s_cselect_b32 s6, s40, s41
	v_lshl_add_u64 v[196:197], s[4:5], 0, v[172:173]
	s_add_i32 m0, s30, 0xc000
	ds_read_b128 v[148:151], v169
	ds_read_b128 v[152:155], v169 offset:1024
	ds_read_b128 v[176:179], v169 offset:2048
	ds_read_b128 v[180:183], v169 offset:3072
	ds_read_b128 v[184:187], v169 offset:4096
	ds_read_b128 v[188:191], v169 offset:5120
	ds_read_b128 v[192:195], v169 offset:6144
	ds_read_b128 v[212:215], v169 offset:7168
	global_load_lds_dwordx4 v[196:197], off
	v_lshl_add_u64 v[196:197], s[4:5], 0, v[170:171]
	s_add_i32 m0, s30, 0xe000
	s_nop 0
	global_load_lds_dwordx4 v[196:197], off
	s_waitcnt lgkmcnt(8)
	s_setprio 1
	s_barrier
	s_waitcnt lgkmcnt(0)
	v_mfma_f32_16x16x32_bf16 v[140:143], v[92:95], v[148:151], 0
	v_mfma_f32_16x16x32_bf16 v[140:143], v[100:103], v[152:155], v[140:143]
	v_mfma_f32_16x16x32_bf16 v[128:131], v[92:95], v[176:179], 0
	v_mfma_f32_16x16x32_bf16 v[128:131], v[100:103], v[180:183], v[128:131]
	v_mfma_f32_16x16x32_bf16 v[120:123], v[92:95], v[184:187], 0
	v_mfma_f32_16x16x32_bf16 v[120:123], v[100:103], v[188:191], v[120:123]
	v_mfma_f32_16x16x32_bf16 v[112:115], v[92:95], v[192:195], 0
	v_mfma_f32_16x16x32_bf16 v[112:115], v[100:103], v[212:215], v[112:115]
	v_mfma_f32_16x16x32_bf16 v[136:139], v[132:135], v[148:151], 0
	v_mfma_f32_16x16x32_bf16 v[136:139], v[144:147], v[152:155], v[136:139]
	v_mfma_f32_16x16x32_bf16 v[124:127], v[132:135], v[176:179], 0
	v_mfma_f32_16x16x32_bf16 v[124:127], v[144:147], v[180:183], v[124:127]
	v_mfma_f32_16x16x32_bf16 v[116:119], v[132:135], v[184:187], 0
	v_mfma_f32_16x16x32_bf16 v[116:119], v[144:147], v[188:191], v[116:119]
	v_mfma_f32_16x16x32_bf16 v[108:111], v[132:135], v[192:195], 0
	v_mfma_f32_16x16x32_bf16 v[108:111], v[144:147], v[212:215], v[108:111]
	s_barrier
	s_setprio 0
	s_add_i32 s46, 0, 0x14000
	s_add_i32 s44, s44, s29
	v_add_u32_e32 v2, s46, v167
	v_lshl_add_u64 v[196:197], s[6:7], 0, v[158:159]
	s_mov_b32 m0, s44
	ds_read_b128 v[216:219], v2
	ds_read_b128 v[220:223], v2 offset:1024
	ds_read_b128 v[224:227], v2 offset:2048
	ds_read_b128 v[228:231], v2 offset:3072
	global_load_lds_dwordx4 v[196:197], off
	v_lshl_add_u64 v[232:233], s[6:7], 0, v[0:1]
	s_add_i32 m0, s44, 0x2000
	s_nop 0
	global_load_lds_dwordx4 v[232:233], off
	s_setprio 1
	s_barrier
	s_waitcnt lgkmcnt(0)
	v_mfma_f32_16x16x32_bf16 v[64:67], v[216:219], v[148:151], 0
	v_mfma_f32_16x16x32_bf16 v[64:67], v[220:223], v[152:155], v[64:67]
	v_mfma_f32_16x16x32_bf16 v[56:59], v[216:219], v[176:179], 0
	v_mfma_f32_16x16x32_bf16 v[56:59], v[220:223], v[180:183], v[56:59]
	v_mfma_f32_16x16x32_bf16 v[48:51], v[216:219], v[184:187], 0
	v_mfma_f32_16x16x32_bf16 v[48:51], v[220:223], v[188:191], v[48:51]
	v_mfma_f32_16x16x32_bf16 v[40:43], v[216:219], v[192:195], 0
	v_mfma_f32_16x16x32_bf16 v[40:43], v[220:223], v[212:215], v[40:43]
	v_mfma_f32_16x16x32_bf16 v[60:63], v[224:227], v[148:151], 0
	v_mfma_f32_16x16x32_bf16 v[60:63], v[228:231], v[152:155], v[60:63]
	v_mfma_f32_16x16x32_bf16 v[52:55], v[224:227], v[176:179], 0
	v_mfma_f32_16x16x32_bf16 v[52:55], v[228:231], v[180:183], v[52:55]
	v_mfma_f32_16x16x32_bf16 v[44:47], v[224:227], v[184:187], 0
	v_mfma_f32_16x16x32_bf16 v[44:47], v[228:231], v[188:191], v[44:47]
	v_mfma_f32_16x16x32_bf16 v[36:39], v[224:227], v[192:195], 0
	v_mfma_f32_16x16x32_bf16 v[36:39], v[228:231], v[212:215], v[36:39]
	s_barrier
	s_setprio 0
	s_mov_b32 m0, s30
	v_lshl_add_u64 v[234:235], s[10:11], 0, v[160:161]
	ds_read_b128 v[148:151], v169 offset:16384
	ds_read_b128 v[152:155], v169 offset:17408
	ds_read_b128 v[176:179], v169 offset:18432
	ds_read_b128 v[180:183], v169 offset:19456
	ds_read_b128 v[184:187], v169 offset:20480
	ds_read_b128 v[188:191], v169 offset:21504
	ds_read_b128 v[192:195], v169 offset:22528
	ds_read_b128 v[212:215], v169 offset:23552
	global_load_lds_dwordx4 v[234:235], off
	v_lshl_add_u64 v[236:237], s[10:11], 0, v[156:157]
	s_mov_b32 m0, s31
	s_nop 0
	global_load_lds_dwordx4 v[236:237], off
	s_setprio 1
	s_barrier
	s_waitcnt lgkmcnt(0)
	v_mfma_f32_16x16x32_bf16 v[104:107], v[92:95], v[148:151], 0
	v_mfma_f32_16x16x32_bf16 v[104:107], v[100:103], v[152:155], v[104:107]
	v_mfma_f32_16x16x32_bf16 v[88:91], v[92:95], v[176:179], 0
	v_mfma_f32_16x16x32_bf16 v[88:91], v[100:103], v[180:183], v[88:91]
	v_mfma_f32_16x16x32_bf16 v[80:83], v[92:95], v[184:187], 0
	v_mfma_f32_16x16x32_bf16 v[80:83], v[100:103], v[188:191], v[80:83]
	v_mfma_f32_16x16x32_bf16 v[72:75], v[92:95], v[192:195], 0
	v_mfma_f32_16x16x32_bf16 v[72:75], v[100:103], v[212:215], v[72:75]
	v_mfma_f32_16x16x32_bf16 v[96:99], v[132:135], v[148:151], 0
	v_mfma_f32_16x16x32_bf16 v[96:99], v[144:147], v[152:155], v[96:99]
	v_mfma_f32_16x16x32_bf16 v[84:87], v[132:135], v[176:179], 0
	v_mfma_f32_16x16x32_bf16 v[84:87], v[144:147], v[180:183], v[84:87]
	v_mfma_f32_16x16x32_bf16 v[76:79], v[132:135], v[184:187], 0
	v_mfma_f32_16x16x32_bf16 v[76:79], v[144:147], v[188:191], v[76:79]
	v_mfma_f32_16x16x32_bf16 v[68:71], v[132:135], v[192:195], 0
	v_mfma_f32_16x16x32_bf16 v[68:71], v[144:147], v[212:215], v[68:71]
	s_barrier
; #define PG8_WAIT_V(n) asm volatile("s_waitcnt vmcnt(" #n ")" ::: "memory")
; #define PG8_WAIT_L(n) asm volatile("s_waitcnt lgkmcnt(" #n ")" ::: "memory")
; #define PG8_BAR __builtin_amdgcn_s_barrier()
; #define PG8_SCHED __builtin_amdgcn_sched_barrier(0)
; template <class Epi, class AddrA, class AddrB>
; __device__ __forceinline__ void gemm_phase(const Sched S, const int lda, const int ldb, const int K, const AddrA addrA,
;                                            const AddrB addrB, const Epi E) {
;     ...
;       PG8_LDB(B0, 0, 0); PG8_SCHED; PG8_LDA(At, 0, 0); PG8_STAGE(PG8_SA(1, 1), a1 + hstepA, voffA);
;       PG8_WAIT_L(8); PG8_BAR; PG8_WAIT_L(0); PG8_MMA(0, 0, At, B0); PG8_BAR; PG8_SCHED;
;       PG8_LDB(B1, 0, 1); PG8_STAGE(PG8_SB(0, 0), b2, voffB);
;       PG8_BAR; PG8_WAIT_L(0); PG8_MMA(0, 1, At, B1); PG8_BAR;
;       PG8_LDA(At, 0, 1); PG8_STAGE(PG8_SA(0, 0), a2, voffA);
;       PG8_BAR; PG8_WAIT_L(0); PG8_MMA(1, 0, At, B0); PG8_BAR; PG8_SCHED;
;       PG8_STAGE(PG8_SB(0, 1), b2 + hstepB, voffB);
;       PG8_WAIT_V(6); PG8_BAR; PG8_MMA(1, 1, At, B1); PG8_BAR;
;       PG8_LDB(B0, 1, 0); PG8_SCHED; PG8_LDA(At, 1, 0); PG8_STAGE(PG8_SA(0, 1), a2 + hstepA, voffA);
;       PG8_WAIT_L(8); PG8_BAR; PG8_WAIT_L(0); PG8_MMA(0, 0, At, B0); PG8_BAR; PG8_SCHED;
;       PG8_LDB(B1, 1, 1); PG8_STAGE(PG8_SB(1, 0), b3, voffB);
;       PG8_BAR; PG8_WAIT_L(0); PG8_MMA(0, 1, At, B1); PG8_BAR;
;       PG8_LDA(At, 1, 1); PG8_STAGE(PG8_SA(1, 0), a3, voffA);
;       PG8_BAR; PG8_WAIT_L(0); PG8_MMA(1, 0, At, B0); PG8_BAR; PG8_SCHED;
;       PG8_STAGE(PG8_SB(1, 1), b3 + hstepB, voffB);
;       PG8_WAIT_V(6); PG8_BAR; PG8_MMA(1, 1, At, B1); PG8_BAR;
	s_setprio 0
	s_add_u32 s44, s6, 0x20000
	s_addc_u32 s45, s7, 0
	s_add_i32 s46, s46, s29
	v_lshl_add_u64 v[92:93], s[44:45], 0, v[158:159]
	s_mov_b32 m0, s46
	s_nop 0
	global_load_lds_dwordx4 v[92:93], off
	v_lshl_add_u64 v[92:93], s[44:45], 0, v[0:1]
	s_add_i32 m0, s46, 0x2000
	s_nop 0
	global_load_lds_dwordx4 v[92:93], off
	s_waitcnt vmcnt(6)
	s_setprio 1
	s_barrier
	v_mfma_f32_16x16x32_bf16 v[32:35], v[216:219], v[148:151], 0
	v_mfma_f32_16x16x32_bf16 v[32:35], v[220:223], v[152:155], v[32:35]
	v_mfma_f32_16x16x32_bf16 v[24:27], v[216:219], v[176:179], 0
	v_mfma_f32_16x16x32_bf16 v[24:27], v[220:223], v[180:183], v[24:27]
	v_mfma_f32_16x16x32_bf16 v[16:19], v[216:219], v[184:187], 0
	v_mfma_f32_16x16x32_bf16 v[16:19], v[220:223], v[188:191], v[16:19]
	v_mfma_f32_16x16x32_bf16 v[8:11], v[216:219], v[192:195], 0
	v_mfma_f32_16x16x32_bf16 v[8:11], v[220:223], v[212:215], v[8:11]
	v_mfma_f32_16x16x32_bf16 v[28:31], v[224:227], v[148:151], 0
	v_mfma_f32_16x16x32_bf16 v[28:31], v[228:231], v[152:155], v[28:31]
	v_mfma_f32_16x16x32_bf16 v[20:23], v[224:227], v[176:179], 0
	v_mfma_f32_16x16x32_bf16 v[20:23], v[228:231], v[180:183], v[20:23]
	v_mfma_f32_16x16x32_bf16 v[12:15], v[224:227], v[184:187], 0
	v_mfma_f32_16x16x32_bf16 v[12:15], v[228:231], v[188:191], v[12:15]
	v_mfma_f32_16x16x32_bf16 v[4:7], v[224:227], v[192:195], 0
	v_mfma_f32_16x16x32_bf16 v[4:7], v[228:231], v[212:215], v[4:7]
	s_barrier
	s_setprio 0
	s_add_i32 s44, 0, 0x18000
	v_add_u32_e32 v2, s44, v167
	ds_read_b128 v[92:95], v2
	ds_read_b128 v[100:103], v2 offset:1024
	ds_read_b128 v[132:135], v2 offset:2048
	ds_read_b128 v[144:147], v2 offset:3072
	s_add_u32 s10, s10, 0x80000
	s_addc_u32 s11, s11, 0
	s_mov_b32 m0, s34
	v_lshl_add_u64 v[216:217], s[10:11], 0, v[160:161]
	ds_read_b128 v[148:151], v169 offset:32768
	ds_read_b128 v[152:155], v169 offset:33792
	ds_read_b128 v[176:179], v169 offset:34816
	ds_read_b128 v[180:183], v169 offset:35840
	ds_read_b128 v[184:187], v169 offset:36864
	ds_read_b128 v[188:191], v169 offset:37888
	ds_read_b128 v[192:195], v169 offset:38912
	ds_read_b128 v[212:215], v169 offset:39936
	global_load_lds_dwordx4 v[216:217], off
	v_lshl_add_u64 v[216:217], s[10:11], 0, v[156:157]
	s_mov_b32 m0, s35
	s_nop 0
	global_load_lds_dwordx4 v[216:217], off
	s_waitcnt lgkmcnt(8)
	s_setprio 1
	s_barrier
	s_waitcnt lgkmcnt(0)
	v_mfma_f32_16x16x32_bf16 v[140:143], v[92:95], v[148:151], v[140:143]
	v_mfma_f32_16x16x32_bf16 v[140:143], v[100:103], v[152:155], v[140:143]
	v_mfma_f32_16x16x32_bf16 v[128:131], v[92:95], v[176:179], v[128:131]
	v_mfma_f32_16x16x32_bf16 v[128:131], v[100:103], v[180:183], v[128:131]
	v_mfma_f32_16x16x32_bf16 v[120:123], v[92:95], v[184:187], v[120:123]
	v_mfma_f32_16x16x32_bf16 v[120:123], v[100:103], v[188:191], v[120:123]
	v_mfma_f32_16x16x32_bf16 v[112:115], v[92:95], v[192:195], v[112:115]
	v_mfma_f32_16x16x32_bf16 v[112:115], v[100:103], v[212:215], v[112:115]
	v_mfma_f32_16x16x32_bf16 v[136:139], v[132:135], v[148:151], v[136:139]
	v_mfma_f32_16x16x32_bf16 v[136:139], v[144:147], v[152:155], v[136:139]
	v_mfma_f32_16x16x32_bf16 v[124:127], v[132:135], v[176:179], v[124:127]
	v_mfma_f32_16x16x32_bf16 v[124:127], v[144:147], v[180:183], v[124:127]
	v_mfma_f32_16x16x32_bf16 v[116:119], v[132:135], v[184:187], v[116:119]
	v_mfma_f32_16x16x32_bf16 v[116:119], v[144:147], v[188:191], v[116:119]
	v_mfma_f32_16x16x32_bf16 v[108:111], v[132:135], v[192:195], v[108:111]
	v_mfma_f32_16x16x32_bf16 v[108:111], v[144:147], v[212:215], v[108:111]
	s_barrier
	s_setprio 0
	s_add_i32 s10, 0, 0x1c000
	s_add_i32 s11, s44, s29
	v_add_u32_e32 v2, s10, v167
	v_lshl_add_u64 v[196:197], v[196:197], 0, s[52:53]
	s_mov_b32 m0, s11
	ds_read_b128 v[216:219], v2
	ds_read_b128 v[220:223], v2 offset:1024
	ds_read_b128 v[224:227], v2 offset:2048
	ds_read_b128 v[228:231], v2 offset:3072
	global_load_lds_dwordx4 v[196:197], off
	v_lshl_add_u64 v[196:197], v[232:233], 0, s[52:53]
	s_add_i32 m0, s11, 0x2000
	s_nop 0
	global_load_lds_dwordx4 v[196:197], off
	s_setprio 1
	s_barrier
	s_waitcnt lgkmcnt(0)
	v_mfma_f32_16x16x32_bf16 v[64:67], v[216:219], v[148:151], v[64:67]
	v_mfma_f32_16x16x32_bf16 v[64:67], v[220:223], v[152:155], v[64:67]
	v_mfma_f32_16x16x32_bf16 v[56:59], v[216:219], v[176:179], v[56:59]
	v_mfma_f32_16x16x32_bf16 v[56:59], v[220:223], v[180:183], v[56:59]
	v_mfma_f32_16x16x32_bf16 v[48:51], v[216:219], v[184:187], v[48:51]
	v_mfma_f32_16x16x32_bf16 v[48:51], v[220:223], v[188:191], v[48:51]
	v_mfma_f32_16x16x32_bf16 v[40:43], v[216:219], v[192:195], v[40:43]
	v_mfma_f32_16x16x32_bf16 v[40:43], v[220:223], v[212:215], v[40:43]
	v_mfma_f32_16x16x32_bf16 v[60:63], v[224:227], v[148:151], v[60:63]
	v_mfma_f32_16x16x32_bf16 v[60:63], v[228:231], v[152:155], v[60:63]
	v_mfma_f32_16x16x32_bf16 v[52:55], v[224:227], v[176:179], v[52:55]
	v_mfma_f32_16x16x32_bf16 v[52:55], v[228:231], v[180:183], v[52:55]
	v_mfma_f32_16x16x32_bf16 v[44:47], v[224:227], v[184:187], v[44:47]
	v_mfma_f32_16x16x32_bf16 v[44:47], v[228:231], v[188:191], v[44:47]
	v_mfma_f32_16x16x32_bf16 v[36:39], v[224:227], v[192:195], v[36:39]
	v_mfma_f32_16x16x32_bf16 v[36:39], v[228:231], v[212:215], v[36:39]
	s_barrier
	s_setprio 0
	s_mov_b32 m0, s37
	v_lshl_add_u64 v[196:197], v[234:235], 0, s[52:53]
	ds_read_b128 v[148:151], v169 offset:49152
	ds_read_b128 v[152:155], v169 offset:50176
	ds_read_b128 v[176:179], v169 offset:51200
	ds_read_b128 v[180:183], v169 offset:52224
	ds_read_b128 v[184:187], v169 offset:53248
	ds_read_b128 v[188:191], v169 offset:54272
	ds_read_b128 v[192:195], v169 offset:55296
	ds_read_b128 v[212:215], v169 offset:56320
	global_load_lds_dwordx4 v[196:197], off
	v_lshl_add_u64 v[196:197], v[236:237], 0, s[52:53]
	s_mov_b32 m0, s38
	s_nop 0
	global_load_lds_dwordx4 v[196:197], off
	s_setprio 1
	s_barrier
; #define PG8_WAIT_V(n) asm volatile("s_waitcnt vmcnt(" #n ")" ::: "memory")
; #define PG8_WAIT_L(n) asm volatile("s_waitcnt lgkmcnt(" #n ")" ::: "memory")
; #define PG8_BAR __builtin_amdgcn_s_barrier()
; #define PG8_SCHED __builtin_amdgcn_sched_barrier(0)
; template <class Epi, class AddrA, class AddrB>
; __device__ __forceinline__ void gemm_phase(const Sched S, const int lda, const int ldb, const int K, const AddrA addrA,
;                                            const AddrB addrB, const Epi E) {
;     ...
;       PG8_LDB(B0, 0, 0); PG8_SCHED; PG8_LDA(At, 0, 0); PG8_STAGE(PG8_SA(1, 1), a1 + hstepA, voffA);
;       PG8_WAIT_L(8); PG8_BAR; PG8_WAIT_L(0); PG8_MMA(0, 0, At, B0); PG8_BAR; PG8_SCHED;
;       PG8_LDB(B1, 0, 1); PG8_STAGE(PG8_SB(0, 0), b2, voffB);
;       PG8_BAR; PG8_WAIT_L(0); PG8_MMA(0, 1, At, B1); PG8_BAR;
;       PG8_LDA(At, 0, 1); PG8_STAGE(PG8_SA(0, 0), a2, voffA);
;       PG8_BAR; PG8_WAIT_L(0); PG8_MMA(1, 0, At, B0); PG8_BAR; PG8_SCHED;
;       PG8_STAGE(PG8_SB(0, 1), b2 + hstepB, voffB);
;       PG8_WAIT_V(6); PG8_BAR; PG8_MMA(1, 1, At, B1); PG8_BAR;
;       PG8_LDB(B0, 1, 0); PG8_SCHED; PG8_LDA(At, 1, 0); PG8_STAGE(PG8_SA(0, 1), a2 + hstepA, voffA);
;       PG8_WAIT_L(8); PG8_BAR; PG8_WAIT_L(0); PG8_MMA(0, 0, At, B0); PG8_BAR; PG8_SCHED;
;       PG8_LDB(B1, 1, 1); PG8_STAGE(PG8_SB(1, 0), b3, voffB);
;       PG8_BAR; PG8_WAIT_L(0); PG8_MMA(0, 1, At, B1); PG8_BAR;
;       PG8_LDA(At, 1, 1); PG8_STAGE(PG8_SA(1, 0), a3, voffA);
;       PG8_BAR; PG8_WAIT_L(0); PG8_MMA(1, 0, At, B0); PG8_BAR; PG8_SCHED;
;       PG8_STAGE(PG8_SB(1, 1), b3 + hstepB, voffB);
;       PG8_WAIT_V(6); PG8_BAR; PG8_MMA(1, 1, At, B1); PG8_BAR;
	s_waitcnt lgkmcnt(0)
	v_mfma_f32_16x16x32_bf16 v[104:107], v[92:95], v[148:151], v[104:107]
	v_mfma_f32_16x16x32_bf16 v[104:107], v[100:103], v[152:155], v[104:107]
	v_mfma_f32_16x16x32_bf16 v[88:91], v[92:95], v[176:179], v[88:91]
	v_mfma_f32_16x16x32_bf16 v[88:91], v[100:103], v[180:183], v[88:91]
	v_mfma_f32_16x16x32_bf16 v[80:83], v[92:95], v[184:187], v[80:83]
	v_mfma_f32_16x16x32_bf16 v[80:83], v[100:103], v[188:191], v[80:83]
	v_mfma_f32_16x16x32_bf16 v[72:75], v[92:95], v[192:195], v[72:75]
	v_mfma_f32_16x16x32_bf16 v[72:75], v[100:103], v[212:215], v[72:75]
	v_mfma_f32_16x16x32_bf16 v[96:99], v[132:135], v[148:151], v[96:99]
	v_mfma_f32_16x16x32_bf16 v[96:99], v[144:147], v[152:155], v[96:99]
	v_mfma_f32_16x16x32_bf16 v[84:87], v[132:135], v[176:179], v[84:87]
	v_mfma_f32_16x16x32_bf16 v[84:87], v[144:147], v[180:183], v[84:87]
	v_mfma_f32_16x16x32_bf16 v[76:79], v[132:135], v[184:187], v[76:79]
	v_mfma_f32_16x16x32_bf16 v[76:79], v[144:147], v[188:191], v[76:79]
	v_mfma_f32_16x16x32_bf16 v[68:71], v[132:135], v[192:195], v[68:71]
	v_mfma_f32_16x16x32_bf16 v[68:71], v[144:147], v[212:215], v[68:71]
	s_barrier
	s_setprio 0
	s_add_u32 s6, s6, 0x20080
	s_addc_u32 s7, s7, 0
	s_add_i32 s10, s10, s29
	v_lshl_add_u64 v[92:93], s[6:7], 0, v[158:159]
	s_mov_b32 m0, s10
	s_nop 0
	global_load_lds_dwordx4 v[92:93], off
	v_lshl_add_u64 v[92:93], s[6:7], 0, v[0:1]
	s_add_i32 m0, s10, 0x2000
	s_nop 0
	global_load_lds_dwordx4 v[92:93], off
	s_waitcnt vmcnt(6)
	s_setprio 1
	s_barrier
	v_mfma_f32_16x16x32_bf16 v[32:35], v[216:219], v[148:151], v[32:35]
	v_mfma_f32_16x16x32_bf16 v[32:35], v[220:223], v[152:155], v[32:35]
	v_mfma_f32_16x16x32_bf16 v[24:27], v[216:219], v[176:179], v[24:27]
	v_mfma_f32_16x16x32_bf16 v[24:27], v[220:223], v[180:183], v[24:27]
	v_mfma_f32_16x16x32_bf16 v[16:19], v[216:219], v[184:187], v[16:19]
	v_mfma_f32_16x16x32_bf16 v[16:19], v[220:223], v[188:191], v[16:19]
	v_mfma_f32_16x16x32_bf16 v[8:11], v[216:219], v[192:195], v[8:11]
	v_mfma_f32_16x16x32_bf16 v[8:11], v[220:223], v[212:215], v[8:11]
	v_mfma_f32_16x16x32_bf16 v[28:31], v[224:227], v[148:151], v[28:31]
	v_mfma_f32_16x16x32_bf16 v[28:31], v[228:231], v[152:155], v[28:31]
	v_mfma_f32_16x16x32_bf16 v[20:23], v[224:227], v[176:179], v[20:23]
	v_mfma_f32_16x16x32_bf16 v[20:23], v[228:231], v[180:183], v[20:23]
	v_mfma_f32_16x16x32_bf16 v[12:15], v[224:227], v[184:187], v[12:15]
	v_mfma_f32_16x16x32_bf16 v[12:15], v[228:231], v[188:191], v[12:15]
	v_mfma_f32_16x16x32_bf16 v[4:7], v[224:227], v[192:195], v[4:7]
	v_mfma_f32_16x16x32_bf16 v[4:7], v[228:231], v[212:215], v[4:7]
	s_barrier
	s_setprio 0
	s_add_i32 s43, s43, 2
	s_add_u32 s41, s41, 0x100
	s_addc_u32 s42, s42, 0
	s_add_u32 s4, s4, 0x100
	s_addc_u32 s5, s5, 0
	s_cmp_gt_u32 s43, 5
.LBB0_485:
	s_add_u32 s6, s4, 0xfff80080
	s_addc_u32 s7, s5, -1
	s_add_i32 s44, 0, 0x10000
	v_add_u32_e32 v2, s44, v167
	ds_read_b128 v[92:95], v2
	ds_read_b128 v[100:103], v2 offset:1024
	ds_read_b128 v[132:135], v2 offset:2048
	ds_read_b128 v[144:147], v2 offset:3072
	s_cmp_eq_u32 s43, 4
	s_cselect_b32 s11, s3, s7
	s_cselect_b32 s10, s15, s6
	s_cselect_b32 s7, s17, s42
	s_cselect_b32 s6, s40, s41
	v_lshl_add_u64 v[196:197], s[4:5], 0, v[172:173]
	s_add_i32 m0, s30, 0xc000
	ds_read_b128 v[148:151], v169
	ds_read_b128 v[152:155], v169 offset:1024
	ds_read_b128 v[176:179], v169 offset:2048
	ds_read_b128 v[180:183], v169 offset:3072
	ds_read_b128 v[184:187], v169 offset:4096
	ds_read_b128 v[188:191], v169 offset:5120
	ds_read_b128 v[192:195], v169 offset:6144
	ds_read_b128 v[212:215], v169 offset:7168
	global_load_lds_dwordx4 v[196:197], off
	v_lshl_add_u64 v[196:197], s[4:5], 0, v[170:171]
	s_add_i32 m0, s30, 0xe000
	s_nop 0
	global_load_lds_dwordx4 v[196:197], off
	s_waitcnt lgkmcnt(8)
	s_setprio 1
	s_barrier
	s_waitcnt lgkmcnt(0)
	v_mfma_f32_16x16x32_bf16 v[140:143], v[92:95], v[148:151], v[140:143]
	v_mfma_f32_16x16x32_bf16 v[140:143], v[100:103], v[152:155], v[140:143]
	v_mfma_f32_16x16x32_bf16 v[128:131], v[92:95], v[176:179], v[128:131]
	v_mfma_f32_16x16x32_bf16 v[128:131], v[100:103], v[180:183], v[128:131]
	v_mfma_f32_16x16x32_bf16 v[120:123], v[92:95], v[184:187], v[120:123]
	v_mfma_f32_16x16x32_bf16 v[120:123], v[100:103], v[188:191], v[120:123]
	v_mfma_f32_16x16x32_bf16 v[112:115], v[92:95], v[192:195], v[112:115]
	v_mfma_f32_16x16x32_bf16 v[112:115], v[100:103], v[212:215], v[112:115]
	v_mfma_f32_16x16x32_bf16 v[136:139], v[132:135], v[148:151], v[136:139]
	v_mfma_f32_16x16x32_bf16 v[136:139], v[144:147], v[152:155], v[136:139]
	v_mfma_f32_16x16x32_bf16 v[124:127], v[132:135], v[176:179], v[124:127]
	v_mfma_f32_16x16x32_bf16 v[124:127], v[144:147], v[180:183], v[124:127]
	v_mfma_f32_16x16x32_bf16 v[116:119], v[132:135], v[184:187], v[116:119]
	v_mfma_f32_16x16x32_bf16 v[116:119], v[144:147], v[188:191], v[116:119]
	v_mfma_f32_16x16x32_bf16 v[108:111], v[132:135], v[192:195], v[108:111]
	v_mfma_f32_16x16x32_bf16 v[108:111], v[144:147], v[212:215], v[108:111]
	s_barrier
	s_setprio 0
	s_add_i32 s46, 0, 0x14000
	s_add_i32 s44, s44, s29
	v_add_u32_e32 v2, s46, v167
	v_lshl_add_u64 v[196:197], s[6:7], 0, v[158:159]
	s_mov_b32 m0, s44
	ds_read_b128 v[216:219], v2
	ds_read_b128 v[220:223], v2 offset:1024
	ds_read_b128 v[224:227], v2 offset:2048
	ds_read_b128 v[228:231], v2 offset:3072
	global_load_lds_dwordx4 v[196:197], off
	v_lshl_add_u64 v[232:233], s[6:7], 0, v[0:1]
	s_add_i32 m0, s44, 0x2000
	s_nop 0
	global_load_lds_dwordx4 v[232:233], off
	s_setprio 1
	s_barrier
; #define PG8_WAIT_V(n) asm volatile("s_waitcnt vmcnt(" #n ")" ::: "memory")
; #define PG8_WAIT_L(n) asm volatile("s_waitcnt lgkmcnt(" #n ")" ::: "memory")
; #define PG8_BAR __builtin_amdgcn_s_barrier()
; #define PG8_SCHED __builtin_amdgcn_sched_barrier(0)
; template <class Epi, class AddrA, class AddrB>
; __device__ __forceinline__ void gemm_phase(const Sched S, const int lda, const int ldb, const int K, const AddrA addrA,
;                                            const AddrB addrB, const Epi E) {
;     ...
;       PG8_LDB(B0, 0, 0); PG8_SCHED; PG8_LDA(At, 0, 0); PG8_STAGE(PG8_SA(1, 1), a1 + hstepA, voffA);
;       PG8_WAIT_L(8); PG8_BAR; PG8_WAIT_L(0); PG8_MMA(0, 0, At, B0); PG8_BAR; PG8_SCHED;
;       PG8_LDB(B1, 0, 1); PG8_STAGE(PG8_SB(0, 0), b2, voffB);
;       PG8_BAR; PG8_WAIT_L(0); PG8_MMA(0, 1, At, B1); PG8_BAR;
;       PG8_LDA(At, 0, 1); PG8_STAGE(PG8_SA(0, 0), a2, voffA);
;       PG8_BAR; PG8_WAIT_L(0); PG8_MMA(1, 0, At, B0); PG8_BAR; PG8_SCHED;
;       PG8_STAGE(PG8_SB(0, 1), b2 + hstepB, voffB);
;       PG8_WAIT_V(6); PG8_BAR; PG8_MMA(1, 1, At, B1); PG8_BAR;
;       PG8_LDB(B0, 1, 0); PG8_SCHED; PG8_LDA(At, 1, 0); PG8_STAGE(PG8_SA(0, 1), a2 + hstepA, voffA);
;       PG8_WAIT_L(8); PG8_BAR; PG8_WAIT_L(0); PG8_MMA(0, 0, At, B0); PG8_BAR; PG8_SCHED;
;       PG8_LDB(B1, 1, 1); PG8_STAGE(PG8_SB(1, 0), b3, voffB);
;       PG8_BAR; PG8_WAIT_L(0); PG8_MMA(0, 1, At, B1); PG8_BAR;
;       PG8_LDA(At, 1, 1); PG8_STAGE(PG8_SA(1, 0), a3, voffA);
;       PG8_BAR; PG8_WAIT_L(0); PG8_MMA(1, 0, At, B0); PG8_BAR; PG8_SCHED;
;       PG8_STAGE(PG8_SB(1, 1), b3 + hstepB, voffB);
;       PG8_WAIT_V(6); PG8_BAR; PG8_MMA(1, 1, At, B1); PG8_BAR;
	s_waitcnt lgkmcnt(0)
	v_mfma_f32_16x16x32_bf16 v[64:67], v[216:219], v[148:151], v[64:67]
	v_mfma_f32_16x16x32_bf16 v[64:67], v[220:223], v[152:155], v[64:67]
	v_mfma_f32_16x16x32_bf16 v[56:59], v[216:219], v[176:179], v[56:59]
	v_mfma_f32_16x16x32_bf16 v[56:59], v[220:223], v[180:183], v[56:59]
	v_mfma_f32_16x16x32_bf16 v[48:51], v[216:219], v[184:187], v[48:51]
	v_mfma_f32_16x16x32_bf16 v[48:51], v[220:223], v[188:191], v[48:51]
	v_mfma_f32_16x16x32_bf16 v[40:43], v[216:219], v[192:195], v[40:43]
	v_mfma_f32_16x16x32_bf16 v[40:43], v[220:223], v[212:215], v[40:43]
	v_mfma_f32_16x16x32_bf16 v[60:63], v[224:227], v[148:151], v[60:63]
	v_mfma_f32_16x16x32_bf16 v[60:63], v[228:231], v[152:155], v[60:63]
	v_mfma_f32_16x16x32_bf16 v[52:55], v[224:227], v[176:179], v[52:55]
	v_mfma_f32_16x16x32_bf16 v[52:55], v[228:231], v[180:183], v[52:55]
	v_mfma_f32_16x16x32_bf16 v[44:47], v[224:227], v[184:187], v[44:47]
	v_mfma_f32_16x16x32_bf16 v[44:47], v[228:231], v[188:191], v[44:47]
	v_mfma_f32_16x16x32_bf16 v[36:39], v[224:227], v[192:195], v[36:39]
	v_mfma_f32_16x16x32_bf16 v[36:39], v[228:231], v[212:215], v[36:39]
	s_barrier
	s_setprio 0
	s_mov_b32 m0, s30
	v_lshl_add_u64 v[234:235], s[10:11], 0, v[160:161]
	ds_read_b128 v[148:151], v169 offset:16384
	ds_read_b128 v[152:155], v169 offset:17408
	ds_read_b128 v[176:179], v169 offset:18432
	ds_read_b128 v[180:183], v169 offset:19456
	ds_read_b128 v[184:187], v169 offset:20480
	ds_read_b128 v[188:191], v169 offset:21504
	ds_read_b128 v[192:195], v169 offset:22528
	ds_read_b128 v[212:215], v169 offset:23552
	global_load_lds_dwordx4 v[234:235], off
	v_lshl_add_u64 v[236:237], s[10:11], 0, v[156:157]
	s_mov_b32 m0, s31
	s_nop 0
	global_load_lds_dwordx4 v[236:237], off
	s_setprio 1
	s_barrier
	s_waitcnt lgkmcnt(0)
	v_mfma_f32_16x16x32_bf16 v[104:107], v[92:95], v[148:151], v[104:107]
	v_mfma_f32_16x16x32_bf16 v[104:107], v[100:103], v[152:155], v[104:107]
	v_mfma_f32_16x16x32_bf16 v[88:91], v[92:95], v[176:179], v[88:91]
	v_mfma_f32_16x16x32_bf16 v[88:91], v[100:103], v[180:183], v[88:91]
	v_mfma_f32_16x16x32_bf16 v[80:83], v[92:95], v[184:187], v[80:83]
	v_mfma_f32_16x16x32_bf16 v[80:83], v[100:103], v[188:191], v[80:83]
	v_mfma_f32_16x16x32_bf16 v[72:75], v[92:95], v[192:195], v[72:75]
	v_mfma_f32_16x16x32_bf16 v[72:75], v[100:103], v[212:215], v[72:75]
	v_mfma_f32_16x16x32_bf16 v[96:99], v[132:135], v[148:151], v[96:99]
	v_mfma_f32_16x16x32_bf16 v[96:99], v[144:147], v[152:155], v[96:99]
	v_mfma_f32_16x16x32_bf16 v[84:87], v[132:135], v[176:179], v[84:87]
	v_mfma_f32_16x16x32_bf16 v[84:87], v[144:147], v[180:183], v[84:87]
	v_mfma_f32_16x16x32_bf16 v[76:79], v[132:135], v[184:187], v[76:79]
	v_mfma_f32_16x16x32_bf16 v[76:79], v[144:147], v[188:191], v[76:79]
	v_mfma_f32_16x16x32_bf16 v[68:71], v[132:135], v[192:195], v[68:71]
	v_mfma_f32_16x16x32_bf16 v[68:71], v[144:147], v[212:215], v[68:71]
	s_barrier
	s_setprio 0
	s_add_u32 s44, s6, 0x20000
	s_addc_u32 s45, s7, 0
	s_add_i32 s46, s46, s29
	v_lshl_add_u64 v[92:93], s[44:45], 0, v[158:159]
	s_mov_b32 m0, s46
	s_nop 0
	global_load_lds_dwordx4 v[92:93], off
	v_lshl_add_u64 v[92:93], s[44:45], 0, v[0:1]
	s_add_i32 m0, s46, 0x2000
	s_nop 0
	global_load_lds_dwordx4 v[92:93], off
	s_waitcnt vmcnt(6)
	s_setprio 1
	s_barrier
	v_mfma_f32_16x16x32_bf16 v[32:35], v[216:219], v[148:151], v[32:35]
	v_mfma_f32_16x16x32_bf16 v[32:35], v[220:223], v[152:155], v[32:35]
	v_mfma_f32_16x16x32_bf16 v[24:27], v[216:219], v[176:179], v[24:27]
	v_mfma_f32_16x16x32_bf16 v[24:27], v[220:223], v[180:183], v[24:27]
	v_mfma_f32_16x16x32_bf16 v[16:19], v[216:219], v[184:187], v[16:19]
	v_mfma_f32_16x16x32_bf16 v[16:19], v[220:223], v[188:191], v[16:19]
	v_mfma_f32_16x16x32_bf16 v[8:11], v[216:219], v[192:195], v[8:11]
	v_mfma_f32_16x16x32_bf16 v[8:11], v[220:223], v[212:215], v[8:11]
	v_mfma_f32_16x16x32_bf16 v[28:31], v[224:227], v[148:151], v[28:31]
	v_mfma_f32_16x16x32_bf16 v[28:31], v[228:231], v[152:155], v[28:31]
	v_mfma_f32_16x16x32_bf16 v[20:23], v[224:227], v[176:179], v[20:23]
	v_mfma_f32_16x16x32_bf16 v[20:23], v[228:231], v[180:183], v[20:23]
	v_mfma_f32_16x16x32_bf16 v[12:15], v[224:227], v[184:187], v[12:15]
	v_mfma_f32_16x16x32_bf16 v[12:15], v[228:231], v[188:191], v[12:15]
	v_mfma_f32_16x16x32_bf16 v[4:7], v[224:227], v[192:195], v[4:7]
	v_mfma_f32_16x16x32_bf16 v[4:7], v[228:231], v[212:215], v[4:7]
	s_barrier
	s_setprio 0
	s_add_i32 s44, 0, 0x18000
	v_add_u32_e32 v2, s44, v167
	ds_read_b128 v[92:95], v2
	ds_read_b128 v[100:103], v2 offset:1024
	ds_read_b128 v[132:135], v2 offset:2048
	ds_read_b128 v[144:147], v2 offset:3072
	s_add_u32 s10, s10, 0x80000
	s_addc_u32 s11, s11, 0
	s_mov_b32 m0, s34
	v_lshl_add_u64 v[216:217], s[10:11], 0, v[160:161]
	ds_read_b128 v[148:151], v169 offset:32768
	ds_read_b128 v[152:155], v169 offset:33792
	ds_read_b128 v[176:179], v169 offset:34816
	ds_read_b128 v[180:183], v169 offset:35840
	ds_read_b128 v[184:187], v169 offset:36864
	ds_read_b128 v[188:191], v169 offset:37888
	ds_read_b128 v[192:195], v169 offset:38912
	ds_read_b128 v[212:215], v169 offset:39936
	global_load_lds_dwordx4 v[216:217], off
	v_lshl_add_u64 v[216:217], s[10:11], 0, v[156:157]
	s_mov_b32 m0, s35
	s_nop 0
	global_load_lds_dwordx4 v[216:217], off
	s_waitcnt lgkmcnt(8)
	s_setprio 1
	s_barrier
; #define PG8_WAIT_V(n) asm volatile("s_waitcnt vmcnt(" #n ")" ::: "memory")
; #define PG8_WAIT_L(n) asm volatile("s_waitcnt lgkmcnt(" #n ")" ::: "memory")
; #define PG8_BAR __builtin_amdgcn_s_barrier()
; #define PG8_SCHED __builtin_amdgcn_sched_barrier(0)
; template <class Epi, class AddrA, class AddrB>
; __device__ __forceinline__ void gemm_phase(const Sched S, const int lda, const int ldb, const int K, const AddrA addrA,
;                                            const AddrB addrB, const Epi E) {
;     ...
;       PG8_LDB(B0, 0, 0); PG8_SCHED; PG8_LDA(At, 0, 0); PG8_STAGE(PG8_SA(1, 1), a1 + hstepA, voffA);
;       PG8_WAIT_L(8); PG8_BAR; PG8_WAIT_L(0); PG8_MMA(0, 0, At, B0); PG8_BAR; PG8_SCHED;
;       PG8_LDB(B1, 0, 1); PG8_STAGE(PG8_SB(0, 0), b2, voffB);
;       PG8_BAR; PG8_WAIT_L(0); PG8_MMA(0, 1, At, B1); PG8_BAR;
;       PG8_LDA(At, 0, 1); PG8_STAGE(PG8_SA(0, 0), a2, voffA);
;       PG8_BAR; PG8_WAIT_L(0); PG8_MMA(1, 0, At, B0); PG8_BAR; PG8_SCHED;
;       PG8_STAGE(PG8_SB(0, 1), b2 + hstepB, voffB);
;       PG8_WAIT_V(6); PG8_BAR; PG8_MMA(1, 1, At, B1); PG8_BAR;
;       PG8_LDB(B0, 1, 0); PG8_SCHED; PG8_LDA(At, 1, 0); PG8_STAGE(PG8_SA(0, 1), a2 + hstepA, voffA);
;       PG8_WAIT_L(8); PG8_BAR; PG8_WAIT_L(0); PG8_MMA(0, 0, At, B0); PG8_BAR; PG8_SCHED;
;       PG8_LDB(B1, 1, 1); PG8_STAGE(PG8_SB(1, 0), b3, voffB);
;       PG8_BAR; PG8_WAIT_L(0); PG8_MMA(0, 1, At, B1); PG8_BAR;
;       PG8_LDA(At, 1, 1); PG8_STAGE(PG8_SA(1, 0), a3, voffA);
;       PG8_BAR; PG8_WAIT_L(0); PG8_MMA(1, 0, At, B0); PG8_BAR; PG8_SCHED;
;       PG8_STAGE(PG8_SB(1, 1), b3 + hstepB, voffB);
;       PG8_WAIT_V(6); PG8_BAR; PG8_MMA(1, 1, At, B1); PG8_BAR;
	s_waitcnt lgkmcnt(0)
	v_mfma_f32_16x16x32_bf16 v[140:143], v[92:95], v[148:151], v[140:143]
	v_mfma_f32_16x16x32_bf16 v[140:143], v[100:103], v[152:155], v[140:143]
	v_mfma_f32_16x16x32_bf16 v[128:131], v[92:95], v[176:179], v[128:131]
	v_mfma_f32_16x16x32_bf16 v[128:131], v[100:103], v[180:183], v[128:131]
	v_mfma_f32_16x16x32_bf16 v[120:123], v[92:95], v[184:187], v[120:123]
	v_mfma_f32_16x16x32_bf16 v[120:123], v[100:103], v[188:191], v[120:123]
	v_mfma_f32_16x16x32_bf16 v[112:115], v[92:95], v[192:195], v[112:115]
	v_mfma_f32_16x16x32_bf16 v[112:115], v[100:103], v[212:215], v[112:115]
	v_mfma_f32_16x16x32_bf16 v[136:139], v[132:135], v[148:151], v[136:139]
	v_mfma_f32_16x16x32_bf16 v[136:139], v[144:147], v[152:155], v[136:139]
	v_mfma_f32_16x16x32_bf16 v[124:127], v[132:135], v[176:179], v[124:127]
	v_mfma_f32_16x16x32_bf16 v[124:127], v[144:147], v[180:183], v[124:127]
	v_mfma_f32_16x16x32_bf16 v[116:119], v[132:135], v[184:187], v[116:119]
	v_mfma_f32_16x16x32_bf16 v[116:119], v[144:147], v[188:191], v[116:119]
	v_mfma_f32_16x16x32_bf16 v[108:111], v[132:135], v[192:195], v[108:111]
	v_mfma_f32_16x16x32_bf16 v[108:111], v[144:147], v[212:215], v[108:111]
	s_barrier
	s_setprio 0
	s_add_i32 s10, 0, 0x1c000
	s_add_i32 s11, s44, s29
	v_add_u32_e32 v2, s10, v167
	v_lshl_add_u64 v[196:197], v[196:197], 0, s[52:53]
	s_mov_b32 m0, s11
	ds_read_b128 v[216:219], v2
	ds_read_b128 v[220:223], v2 offset:1024
	ds_read_b128 v[224:227], v2 offset:2048
	ds_read_b128 v[228:231], v2 offset:3072
	global_load_lds_dwordx4 v[196:197], off
	v_lshl_add_u64 v[196:197], v[232:233], 0, s[52:53]
	s_add_i32 m0, s11, 0x2000
	s_nop 0
	global_load_lds_dwordx4 v[196:197], off
	s_setprio 1
	s_barrier
	s_waitcnt lgkmcnt(0)
	v_mfma_f32_16x16x32_bf16 v[64:67], v[216:219], v[148:151], v[64:67]
	v_mfma_f32_16x16x32_bf16 v[64:67], v[220:223], v[152:155], v[64:67]
	v_mfma_f32_16x16x32_bf16 v[56:59], v[216:219], v[176:179], v[56:59]
	v_mfma_f32_16x16x32_bf16 v[56:59], v[220:223], v[180:183], v[56:59]
	v_mfma_f32_16x16x32_bf16 v[48:51], v[216:219], v[184:187], v[48:51]
	v_mfma_f32_16x16x32_bf16 v[48:51], v[220:223], v[188:191], v[48:51]
	v_mfma_f32_16x16x32_bf16 v[40:43], v[216:219], v[192:195], v[40:43]
	v_mfma_f32_16x16x32_bf16 v[40:43], v[220:223], v[212:215], v[40:43]
	v_mfma_f32_16x16x32_bf16 v[60:63], v[224:227], v[148:151], v[60:63]
	v_mfma_f32_16x16x32_bf16 v[60:63], v[228:231], v[152:155], v[60:63]
	v_mfma_f32_16x16x32_bf16 v[52:55], v[224:227], v[176:179], v[52:55]
	v_mfma_f32_16x16x32_bf16 v[52:55], v[228:231], v[180:183], v[52:55]
	v_mfma_f32_16x16x32_bf16 v[44:47], v[224:227], v[184:187], v[44:47]
	v_mfma_f32_16x16x32_bf16 v[44:47], v[228:231], v[188:191], v[44:47]
	v_mfma_f32_16x16x32_bf16 v[36:39], v[224:227], v[192:195], v[36:39]
	v_mfma_f32_16x16x32_bf16 v[36:39], v[228:231], v[212:215], v[36:39]
	s_barrier
	s_setprio 0
	s_mov_b32 m0, s37
	v_lshl_add_u64 v[196:197], v[234:235], 0, s[52:53]
	ds_read_b128 v[148:151], v169 offset:49152
	ds_read_b128 v[152:155], v169 offset:50176
	ds_read_b128 v[176:179], v169 offset:51200
	ds_read_b128 v[180:183], v169 offset:52224
	ds_read_b128 v[184:187], v169 offset:53248
	ds_read_b128 v[188:191], v169 offset:54272
	ds_read_b128 v[192:195], v169 offset:55296
	ds_read_b128 v[212:215], v169 offset:56320
	global_load_lds_dwordx4 v[196:197], off
	v_lshl_add_u64 v[196:197], v[236:237], 0, s[52:53]
	s_mov_b32 m0, s38
	s_nop 0
	global_load_lds_dwordx4 v[196:197], off
	s_setprio 1
	s_barrier
	s_waitcnt lgkmcnt(0)
	v_mfma_f32_16x16x32_bf16 v[104:107], v[92:95], v[148:151], v[104:107]
	v_mfma_f32_16x16x32_bf16 v[104:107], v[100:103], v[152:155], v[104:107]
	v_mfma_f32_16x16x32_bf16 v[88:91], v[92:95], v[176:179], v[88:91]
	v_mfma_f32_16x16x32_bf16 v[88:91], v[100:103], v[180:183], v[88:91]
	v_mfma_f32_16x16x32_bf16 v[80:83], v[92:95], v[184:187], v[80:83]
	v_mfma_f32_16x16x32_bf16 v[80:83], v[100:103], v[188:191], v[80:83]
	v_mfma_f32_16x16x32_bf16 v[72:75], v[92:95], v[192:195], v[72:75]
	v_mfma_f32_16x16x32_bf16 v[72:75], v[100:103], v[212:215], v[72:75]
	v_mfma_f32_16x16x32_bf16 v[96:99], v[132:135], v[148:151], v[96:99]
	v_mfma_f32_16x16x32_bf16 v[96:99], v[144:147], v[152:155], v[96:99]
	v_mfma_f32_16x16x32_bf16 v[84:87], v[132:135], v[176:179], v[84:87]
	v_mfma_f32_16x16x32_bf16 v[84:87], v[144:147], v[180:183], v[84:87]
	v_mfma_f32_16x16x32_bf16 v[76:79], v[132:135], v[184:187], v[76:79]
	v_mfma_f32_16x16x32_bf16 v[76:79], v[144:147], v[188:191], v[76:79]
	v_mfma_f32_16x16x32_bf16 v[68:71], v[132:135], v[192:195], v[68:71]
	v_mfma_f32_16x16x32_bf16 v[68:71], v[144:147], v[212:215], v[68:71]
	s_barrier
	s_setprio 0
	s_add_u32 s6, s6, 0x20080
	s_addc_u32 s7, s7, 0
	s_add_i32 s10, s10, s29
	v_lshl_add_u64 v[92:93], s[6:7], 0, v[158:159]
	s_mov_b32 m0, s10
	s_nop 0
	global_load_lds_dwordx4 v[92:93], off
	v_lshl_add_u64 v[92:93], s[6:7], 0, v[0:1]
	s_add_i32 m0, s10, 0x2000
	s_nop 0
	global_load_lds_dwordx4 v[92:93], off
	s_waitcnt vmcnt(6)
	s_setprio 1
	s_barrier
	v_mfma_f32_16x16x32_bf16 v[32:35], v[216:219], v[148:151], v[32:35]
	v_mfma_f32_16x16x32_bf16 v[32:35], v[220:223], v[152:155], v[32:35]
	v_mfma_f32_16x16x32_bf16 v[24:27], v[216:219], v[176:179], v[24:27]
	v_mfma_f32_16x16x32_bf16 v[24:27], v[220:223], v[180:183], v[24:27]
	v_mfma_f32_16x16x32_bf16 v[16:19], v[216:219], v[184:187], v[16:19]
	v_mfma_f32_16x16x32_bf16 v[16:19], v[220:223], v[188:191], v[16:19]
	v_mfma_f32_16x16x32_bf16 v[8:11], v[216:219], v[192:195], v[8:11]
	v_mfma_f32_16x16x32_bf16 v[8:11], v[220:223], v[212:215], v[8:11]
	v_mfma_f32_16x16x32_bf16 v[28:31], v[224:227], v[148:151], v[28:31]
	v_mfma_f32_16x16x32_bf16 v[28:31], v[228:231], v[152:155], v[28:31]
	v_mfma_f32_16x16x32_bf16 v[20:23], v[224:227], v[176:179], v[20:23]
	v_mfma_f32_16x16x32_bf16 v[20:23], v[228:231], v[180:183], v[20:23]
	v_mfma_f32_16x16x32_bf16 v[12:15], v[224:227], v[184:187], v[12:15]
	v_mfma_f32_16x16x32_bf16 v[12:15], v[228:231], v[188:191], v[12:15]
	v_mfma_f32_16x16x32_bf16 v[4:7], v[224:227], v[192:195], v[4:7]
	v_mfma_f32_16x16x32_bf16 v[4:7], v[228:231], v[212:215], v[4:7]
	s_barrier
; __device__ __forceinline__ size_t pidx(size_t row, int col) { return ((size_t)(col >> 8) * MTOK + row) * PLD + (col & 255); }
; __device__ __forceinline__ float bflo(unsigned v) { return __uint_as_float(v << 16); }
; __device__ __forceinline__ float bfhi(unsigned v) { return __uint_as_float(v & 0xffff0000u); }
; __device__ __forceinline__ float siluf_(float x) { return x * __builtin_amdgcn_rcpf(1.0f + __expf(-x)); }
;   __device__ __forceinline__ void operator()(EPI_ARGS) const {
;     const size_t row0 = (size_t)u.pm * 256 + wr * 64 + fr;
;     const int col0 = u.pn * 256 + wc * 32 + 8 * fq;
; #pragma unroll
;     for (int bj = 0; bj < 2; ++bj) {
;       const int c = col0 + bj * HALF;
;       const f32x4 s0 = *(const f32x4*)(psc + c), s1 = *(const f32x4*)(psc + c + 4);
; #pragma unroll
;       for (int ai = 0; ai < 2; ++ai) {
;         u32x4 z[4];
; #pragma unroll
;         for (int m = 0; m < 4; ++m) z[m] = *(const u32x4*)(proj + pidx(row0 + ai * HALF + m * 16, PZ + c));
;         __builtin_amdgcn_sched_barrier(0);
; #pragma unroll
;         for (int m = 0; m < 4; ++m) {
;           const size_t row = row0 + ai * HALF + m * 16;
;           const f32x4 v0 = acc[ai][bj][m][0], v1 = acc[ai][bj][m][1];
;           u32x4 o;
;           o.x = pack2(v0[0] * s0[0] * siluf_(bflo(z[m].x)), v0[1] * s0[1] * siluf_(bfhi(z[m].x)));
;           o.y = pack2(v0[2] * s0[2] * siluf_(bflo(z[m].y)), v0[3] * s0[3] * siluf_(bfhi(z[m].y)));
;           o.z = pack2(v1[0] * s1[0] * siluf_(bflo(z[m].z)), v1[1] * s1[1] * siluf_(bfhi(z[m].z)));
;           o.w = pack2(v1[2] * s1[2] * siluf_(bflo(z[m].w)), v1[3] * s1[3] * siluf_(bfhi(z[m].w)));
;           *(u32x4*)(y0 + row * DM + c) = o;
;         }
;       }
;     }
	s_setprio 0
	s_add_i32 s43, s43, 2
	s_add_u32 s41, s41, 0x100
	s_addc_u32 s42, s42, 0
	s_add_u32 s4, s4, 0x100
	s_addc_u32 s5, s5, 0
	s_cmp_gt_u32 s43, 5
	s_cbranch_scc0 .LBB0_485
	s_ashr_i32 s3, s2, 31
	s_lshl_b64 s[2:3], s[2:3], 8
	v_lshl_add_u64 v[186:187], s[2:3], 0, v[162:163]
	s_lshl_b32 s2, s33, 8
	v_or_b32_e32 v196, s2, v168
	s_addk_i32 s2, 0x800
	s_ashr_i32 s2, s2, 8
	s_ashr_i32 s3, s2, 31
	s_lshl_b64 s[2:3], s[2:3], 23
	s_add_u32 s2, s0, s2
	s_addc_u32 s3, s1, s3
	v_lshlrev_b32_e32 v2, 1, v168
	v_or_b32_e32 v194, 16, v186
	v_mov_b32_e32 v195, v187
	v_ashrrev_i32_e32 v197, 31, v196
	v_lshl_add_u64 v[188:189], s[2:3], 0, v[2:3]
	v_lshlrev_b64 v[178:179], 9, v[186:187]
	v_lshlrev_b64 v[180:181], 9, v[194:195]
	v_or_b32_e32 v192, 32, v186
	v_mov_b32_e32 v193, v187
	v_or_b32_e32 v190, 48, v186
	v_mov_b32_e32 v191, v187
	v_lshl_add_u64 v[176:177], v[196:197], 2, s[12:13]
	v_lshl_add_u64 v[132:133], v[188:189], 0, v[178:179]
	v_lshl_add_u64 v[134:135], v[188:189], 0, v[180:181]
	v_lshlrev_b64 v[182:183], 9, v[192:193]
	v_lshlrev_b64 v[184:185], 9, v[190:191]
	global_load_dwordx4 v[92:95], v[176:177], off offset:16
	global_load_dwordx4 v[100:103], v[176:177], off
	flat_load_dwordx4 v[152:155], v[132:133]
	flat_load_dwordx4 v[148:151], v[134:135]
	v_lshl_add_u64 v[132:133], v[188:189], 0, v[182:183]
	v_lshl_add_u64 v[134:135], v[188:189], 0, v[184:185]
	flat_load_dwordx4 v[144:147], v[132:133]
	s_nop 0
	flat_load_dwordx4 v[132:135], v[134:135]
	s_waitcnt vmcnt(0) lgkmcnt(0)
	v_lshlrev_b32_e32 v213, 16, v152
	v_mul_f32_e32 v2, 0xbfb8aa3b, v213
	v_exp_f32_e32 v2, v2
	v_mov_b32_e32 v214, v140
	v_mov_b32_e32 v212, v100
	s_mov_b64 s[4:5], 0x90
	v_add_f32_e32 v2, 1.0, v2
	v_rcp_f32_e32 v215, v2
	s_nop 0
	v_pk_mul_f32 v[212:213], v[214:215], v[212:213]
	s_nop 0
	v_mul_f32_e32 v2, v212, v213
	v_and_b32_e32 v213, 0xffff0000, v152
	v_mul_f32_e32 v140, 0xbfb8aa3b, v213
	v_exp_f32_e32 v140, v140
	v_mov_b32_e32 v214, v141
	v_mov_b32_e32 v212, v101
	v_add_f32_e32 v140, 1.0, v140
	v_rcp_f32_e32 v215, v140
	s_nop 0
	v_pk_mul_f32 v[140:141], v[214:215], v[212:213]
	s_nop 0
	v_mul_f32_e32 v140, v140, v141
	v_lshlrev_b32_e32 v141, 16, v153
	v_cvt_pk_bf16_f32 v152, v2, v140
	v_mul_f32_e32 v2, 0xbfb8aa3b, v141
	v_exp_f32_e32 v2, v2
	v_mov_b32_e32 v212, v142
	v_mov_b32_e32 v140, v102
	v_mov_b32_e32 v142, v136
	v_add_f32_e32 v2, 1.0, v2
	v_rcp_f32_e32 v213, v2
	s_nop 0
	v_pk_mul_f32 v[140:141], v[212:213], v[140:141]
	s_nop 0
	v_mul_f32_e32 v2, v140, v141
	v_and_b32_e32 v141, 0xffff0000, v153
	v_mul_f32_e32 v140, 0xbfb8aa3b, v141
	v_exp_f32_e32 v140, v140
	v_mov_b32_e32 v212, v143
	v_add_f32_e32 v140, 1.0, v140
	v_rcp_f32_e32 v213, v140
	v_mov_b32_e32 v140, v103
	v_pk_mul_f32 v[140:141], v[212:213], v[140:141]
	s_nop 0
	v_mul_f32_e32 v140, v140, v141
	v_lshlrev_b32_e32 v141, 16, v154
	v_cvt_pk_bf16_f32 v153, v2, v140
	v_mul_f32_e32 v2, 0xbfb8aa3b, v141
	v_exp_f32_e32 v2, v2
	v_mov_b32_e32 v140, v92
	v_add_f32_e32 v2, 1.0, v2
	v_rcp_f32_e32 v143, v2
	s_nop 0
	v_pk_mul_f32 v[140:141], v[142:143], v[140:141]
	s_nop 0
	v_mul_f32_e32 v2, v140, v141
	v_and_b32_e32 v141, 0xffff0000, v154
	v_mul_f32_e32 v136, 0xbfb8aa3b, v141
	v_exp_f32_e32 v136, v136
	v_mov_b32_e32 v142, v137
	v_mov_b32_e32 v140, v93
	v_add_f32_e32 v136, 1.0, v136
	v_rcp_f32_e32 v143, v136
	s_nop 0
	v_pk_mul_f32 v[136:137], v[142:143], v[140:141]
	s_nop 0
	v_mul_f32_e32 v136, v136, v137
	v_lshlrev_b32_e32 v137, 16, v155
	v_cvt_pk_bf16_f32 v154, v2, v136
	v_mul_f32_e32 v2, 0xbfb8aa3b, v137
	v_exp_f32_e32 v2, v2
	v_mov_b32_e32 v140, v138
	v_mov_b32_e32 v136, v94
	v_mov_b32_e32 v142, v128
	v_add_f32_e32 v2, 1.0, v2
	v_rcp_f32_e32 v141, v2
	v_mov_b32_e32 v138, v100
	v_pk_mul_f32 v[136:137], v[140:141], v[136:137]
	s_nop 0
	v_mul_f32_e32 v2, v136, v137
	v_and_b32_e32 v137, 0xffff0000, v155
	v_mul_f32_e32 v136, 0xbfb8aa3b, v137
	v_exp_f32_e32 v136, v136
	v_mov_b32_e32 v140, v139
	v_lshlrev_b32_e32 v139, 16, v148
	v_add_f32_e32 v136, 1.0, v136
	v_rcp_f32_e32 v141, v136
	v_mov_b32_e32 v136, v95
	v_pk_mul_f32 v[136:137], v[140:141], v[136:137]
	s_nop 0
	v_mul_f32_e32 v136, v136, v137
	v_cvt_pk_bf16_f32 v155, v2, v136
	v_mul_f32_e32 v2, 0xbfb8aa3b, v139
	v_exp_f32_e32 v2, v2
	v_lshlrev_b64 v[140:141], 1, v[196:197]
	v_lshlrev_b64 v[136:137], 12, v[186:187]
	v_lshl_add_u64 v[136:137], s[8:9], 0, v[136:137]
	v_add_f32_e32 v2, 1.0, v2
	v_rcp_f32_e32 v143, v2
	v_lshl_add_u64 v[136:137], v[136:137], 0, v[140:141]
	flat_store_dwordx4 v[136:137], v[152:155]
	v_pk_mul_f32 v[138:139], v[142:143], v[138:139]
	s_nop 0
	v_mul_f32_e32 v2, v138, v139
	v_and_b32_e32 v139, 0xffff0000, v148
	v_mul_f32_e32 v128, 0xbfb8aa3b, v139
	v_exp_f32_e32 v128, v128
	v_mov_b32_e32 v142, v129
	v_mov_b32_e32 v138, v101
	v_add_f32_e32 v128, 1.0, v128
	v_rcp_f32_e32 v143, v128
	s_nop 0
	v_pk_mul_f32 v[128:129], v[142:143], v[138:139]
	s_nop 0
	v_mul_f32_e32 v128, v128, v129
	v_lshlrev_b32_e32 v139, 16, v149
	v_cvt_pk_bf16_f32 v128, v2, v128
	v_mul_f32_e32 v2, 0xbfb8aa3b, v139
	v_exp_f32_e32 v2, v2
	v_mov_b32_e32 v142, v130
	v_mov_b32_e32 v138, v102
	v_add_f32_e32 v2, 1.0, v2
	v_rcp_f32_e32 v143, v2
	s_nop 0
	v_pk_mul_f32 v[138:139], v[142:143], v[138:139]
	s_nop 0
	v_mul_f32_e32 v2, v138, v139
	v_and_b32_e32 v139, 0xffff0000, v149
	v_mul_f32_e32 v129, 0xbfb8aa3b, v139
	v_exp_f32_e32 v129, v129
	v_mov_b32_e32 v142, v131
	v_mov_b32_e32 v138, v103
	v_lshl_add_u64 v[148:149], v[186:187], 0, s[52:53]
	v_add_f32_e32 v129, 1.0, v129
	v_rcp_f32_e32 v143, v129
	s_nop 0
	v_pk_mul_f32 v[130:131], v[142:143], v[138:139]
	s_nop 0
	v_mul_f32_e32 v129, v130, v131
	v_lshlrev_b32_e32 v131, 16, v150
	v_cvt_pk_bf16_f32 v129, v2, v129
	v_mul_f32_e32 v2, 0xbfb8aa3b, v131
; __device__ __forceinline__ size_t pidx(size_t row, int col) { return ((size_t)(col >> 8) * MTOK + row) * PLD + (col & 255); }
; __device__ __forceinline__ float bflo(unsigned v) { return __uint_as_float(v << 16); }
; __device__ __forceinline__ float bfhi(unsigned v) { return __uint_as_float(v & 0xffff0000u); }
; __device__ __forceinline__ float siluf_(float x) { return x * __builtin_amdgcn_rcpf(1.0f + __expf(-x)); }
;   __device__ __forceinline__ void operator()(EPI_ARGS) const {
;     ...
;     for (int bj = 0; bj < 2; ++bj) {
;       const int c = col0 + bj * HALF;
;       const f32x4 s0 = *(const f32x4*)(psc + c), s1 = *(const f32x4*)(psc + c + 4);
; #pragma unroll
;       for (int ai = 0; ai < 2; ++ai) {
;         u32x4 z[4];
; #pragma unroll
;         for (int m = 0; m < 4; ++m) z[m] = *(const u32x4*)(proj + pidx(row0 + ai * HALF + m * 16, PZ + c));
;         __builtin_amdgcn_sched_barrier(0);
; #pragma unroll
;         for (int m = 0; m < 4; ++m) {
;           const size_t row = row0 + ai * HALF + m * 16;
;           const f32x4 v0 = acc[ai][bj][m][0], v1 = acc[ai][bj][m][1];
;           u32x4 o;
;           o.x = pack2(v0[0] * s0[0] * siluf_(bflo(z[m].x)), v0[1] * s0[1] * siluf_(bfhi(z[m].x)));
;           o.y = pack2(v0[2] * s0[2] * siluf_(bflo(z[m].y)), v0[3] * s0[3] * siluf_(bfhi(z[m].y)));
;           o.z = pack2(v1[0] * s1[0] * siluf_(bflo(z[m].z)), v1[1] * s1[1] * siluf_(bfhi(z[m].z)));
;           o.w = pack2(v1[2] * s1[2] * siluf_(bflo(z[m].w)), v1[3] * s1[3] * siluf_(bfhi(z[m].w)));
;           *(u32x4*)(y0 + row * DM + c) = o;
;         }
;       }
;     }
	v_exp_f32_e32 v2, v2
	v_mov_b32_e32 v138, v124
	v_mov_b32_e32 v130, v92
	v_add_f32_e32 v2, 1.0, v2
	v_rcp_f32_e32 v139, v2
	s_nop 0
	v_pk_mul_f32 v[130:131], v[138:139], v[130:131]
	s_nop 0
	v_mul_f32_e32 v2, v130, v131
	v_and_b32_e32 v131, 0xffff0000, v150
	v_mul_f32_e32 v124, 0xbfb8aa3b, v131
	v_exp_f32_e32 v124, v124
	v_mov_b32_e32 v138, v125
	v_mov_b32_e32 v130, v93
	v_add_f32_e32 v124, 1.0, v124
	v_rcp_f32_e32 v139, v124
	s_nop 0
	v_pk_mul_f32 v[124:125], v[138:139], v[130:131]
	s_nop 0
	v_mul_f32_e32 v124, v124, v125
	v_lshlrev_b32_e32 v125, 16, v151
	v_cvt_pk_bf16_f32 v130, v2, v124
	v_mul_f32_e32 v2, 0xbfb8aa3b, v125
	v_exp_f32_e32 v2, v2
	v_mov_b32_e32 v138, v126
	v_mov_b32_e32 v124, v94
	v_mov_b32_e32 v126, v100
	v_add_f32_e32 v2, 1.0, v2
	v_rcp_f32_e32 v139, v2
	s_nop 0
	v_pk_mul_f32 v[124:125], v[138:139], v[124:125]
	s_nop 0
	v_mul_f32_e32 v2, v124, v125
	v_and_b32_e32 v125, 0xffff0000, v151
	v_mul_f32_e32 v124, 0xbfb8aa3b, v125
	v_exp_f32_e32 v124, v124
	v_mov_b32_e32 v138, v127
	v_lshlrev_b32_e32 v127, 16, v144
	v_add_f32_e32 v124, 1.0, v124
	v_rcp_f32_e32 v139, v124
	v_mov_b32_e32 v124, v95
	v_pk_mul_f32 v[124:125], v[138:139], v[124:125]
	s_nop 0
	v_mul_f32_e32 v124, v124, v125
	v_cvt_pk_bf16_f32 v131, v2, v124
	v_mul_f32_e32 v2, 0xbfb8aa3b, v127
	v_exp_f32_e32 v2, v2
	v_lshlrev_b64 v[124:125], 12, v[194:195]
	v_lshl_add_u64 v[124:125], s[8:9], 0, v[124:125]
	v_lshl_add_u64 v[124:125], v[124:125], 0, v[140:141]
	v_add_f32_e32 v2, 1.0, v2
	flat_store_dwordx4 v[124:125], v[128:131]
	s_nop 1
	v_rcp_f32_e32 v129, v2
	v_mov_b32_e32 v128, v120
	v_lshlrev_b64 v[130:131], 9, v[148:149]
	v_pk_mul_f32 v[126:127], v[128:129], v[126:127]
	s_nop 0
	v_mul_f32_e32 v2, v126, v127
	v_and_b32_e32 v127, 0xffff0000, v144
	v_mul_f32_e32 v120, 0xbfb8aa3b, v127
	v_exp_f32_e32 v120, v120
	v_mov_b32_e32 v128, v121
	v_mov_b32_e32 v126, v101
	v_add_f32_e32 v120, 1.0, v120
	v_rcp_f32_e32 v129, v120
	s_nop 0
	v_pk_mul_f32 v[120:121], v[128:129], v[126:127]
	s_nop 0
	v_mul_f32_e32 v120, v120, v121
	v_lshlrev_b32_e32 v127, 16, v145
	v_cvt_pk_bf16_f32 v120, v2, v120
	v_mul_f32_e32 v2, 0xbfb8aa3b, v127
	v_exp_f32_e32 v2, v2
	v_mov_b32_e32 v128, v122
	v_mov_b32_e32 v126, v102
	v_add_f32_e32 v2, 1.0, v2
	v_rcp_f32_e32 v129, v2
	s_nop 0
	v_pk_mul_f32 v[126:127], v[128:129], v[126:127]
	s_nop 0
	v_mul_f32_e32 v2, v126, v127
	v_and_b32_e32 v127, 0xffff0000, v145
	v_mul_f32_e32 v121, 0xbfb8aa3b, v127
	v_exp_f32_e32 v121, v121
	v_mov_b32_e32 v128, v123
	v_mov_b32_e32 v126, v103
	v_add_f32_e32 v121, 1.0, v121
	v_rcp_f32_e32 v129, v121
	s_nop 0
	v_pk_mul_f32 v[122:123], v[128:129], v[126:127]
	s_nop 0
	v_mul_f32_e32 v121, v122, v123
	v_lshlrev_b32_e32 v123, 16, v146
	v_cvt_pk_bf16_f32 v121, v2, v121
	v_mul_f32_e32 v2, 0xbfb8aa3b, v123
	v_exp_f32_e32 v2, v2
	v_mov_b32_e32 v126, v116
	v_mov_b32_e32 v122, v92
	v_add_f32_e32 v2, 1.0, v2
	v_rcp_f32_e32 v127, v2
	s_nop 0
	v_pk_mul_f32 v[122:123], v[126:127], v[122:123]
	s_nop 0
	v_mul_f32_e32 v2, v122, v123
	v_and_b32_e32 v123, 0xffff0000, v146
	v_mul_f32_e32 v116, 0xbfb8aa3b, v123
	v_exp_f32_e32 v116, v116
	v_mov_b32_e32 v126, v117
	v_mov_b32_e32 v122, v93
	v_add_f32_e32 v116, 1.0, v116
	v_rcp_f32_e32 v127, v116
	s_nop 0
	v_pk_mul_f32 v[116:117], v[126:127], v[122:123]
	s_nop 0
	v_mul_f32_e32 v116, v116, v117
	v_lshlrev_b32_e32 v117, 16, v147
	v_cvt_pk_bf16_f32 v122, v2, v116
	v_mul_f32_e32 v2, 0xbfb8aa3b, v117
	v_exp_f32_e32 v2, v2
	v_mov_b32_e32 v126, v118
	v_mov_b32_e32 v116, v94
	v_mov_b32_e32 v118, v112
	v_add_f32_e32 v2, 1.0, v2
	v_rcp_f32_e32 v127, v2
	s_nop 0
	v_pk_mul_f32 v[116:117], v[126:127], v[116:117]
	s_nop 0
	v_mul_f32_e32 v2, v116, v117
	v_and_b32_e32 v117, 0xffff0000, v147
	v_mul_f32_e32 v116, 0xbfb8aa3b, v117
	v_exp_f32_e32 v116, v116
	v_mov_b32_e32 v126, v119
	v_lshl_add_u64 v[146:147], v[186:187], 0, s[4:5]
	s_mov_b64 s[4:5], 0xa0
	v_add_f32_e32 v116, 1.0, v116
	v_rcp_f32_e32 v127, v116
	v_mov_b32_e32 v116, v95
	v_lshl_add_u64 v[144:145], v[186:187], 0, s[4:5]
	s_mov_b64 s[4:5], 0xb0
	v_pk_mul_f32 v[116:117], v[126:127], v[116:117]
	v_lshl_add_u64 v[142:143], v[186:187], 0, s[4:5]
	v_mul_f32_e32 v116, v116, v117
	v_cvt_pk_bf16_f32 v123, v2, v116
	v_lshlrev_b64 v[116:117], 12, v[192:193]
	v_lshl_add_u64 v[116:117], s[8:9], 0, v[116:117]
	v_lshl_add_u64 v[128:129], v[116:117], 0, v[140:141]
	v_lshlrev_b32_e32 v117, 16, v132
	v_mul_f32_e32 v2, 0xbfb8aa3b, v117
	v_exp_f32_e32 v2, v2
	v_mov_b32_e32 v116, v100
	flat_store_dwordx4 v[128:129], v[120:123]
	v_lshlrev_b64 v[138:139], 9, v[142:143]
	v_add_f32_e32 v2, 1.0, v2
	v_rcp_f32_e32 v119, v2
	s_nop 0
	v_pk_mul_f32 v[116:117], v[118:119], v[116:117]
	s_nop 0
	v_mul_f32_e32 v2, v116, v117
	v_and_b32_e32 v117, 0xffff0000, v132
	v_mul_f32_e32 v112, 0xbfb8aa3b, v117
	v_exp_f32_e32 v112, v112
	v_mov_b32_e32 v118, v113
	v_mov_b32_e32 v116, v101
	v_add_f32_e32 v112, 1.0, v112
	v_rcp_f32_e32 v119, v112
	s_nop 0
	v_pk_mul_f32 v[112:113], v[118:119], v[116:117]
	s_nop 0
	v_mul_f32_e32 v112, v112, v113
	v_lshlrev_b32_e32 v117, 16, v133
	v_cvt_pk_bf16_f32 v112, v2, v112
	v_mul_f32_e32 v2, 0xbfb8aa3b, v117
	v_exp_f32_e32 v2, v2
	v_mov_b32_e32 v118, v114
	v_mov_b32_e32 v116, v102
	v_add_f32_e32 v2, 1.0, v2
	v_rcp_f32_e32 v119, v2
	s_nop 0
	v_pk_mul_f32 v[116:117], v[118:119], v[116:117]
	s_nop 0
	v_mul_f32_e32 v2, v116, v117
	v_and_b32_e32 v117, 0xffff0000, v133
	v_mul_f32_e32 v113, 0xbfb8aa3b, v117
	v_exp_f32_e32 v113, v113
	v_mov_b32_e32 v118, v115
	v_mov_b32_e32 v116, v103
	v_lshlrev_b64 v[132:133], 9, v[146:147]
	v_add_f32_e32 v113, 1.0, v113
	v_rcp_f32_e32 v119, v113
	s_nop 0
	v_pk_mul_f32 v[114:115], v[118:119], v[116:117]
	s_nop 0
	v_mul_f32_e32 v113, v114, v115
; __device__ __forceinline__ size_t pidx(size_t row, int col) { return ((size_t)(col >> 8) * MTOK + row) * PLD + (col & 255); }
; __device__ __forceinline__ float bflo(unsigned v) { return __uint_as_float(v << 16); }
; __device__ __forceinline__ float bfhi(unsigned v) { return __uint_as_float(v & 0xffff0000u); }
; __device__ __forceinline__ float siluf_(float x) { return x * __builtin_amdgcn_rcpf(1.0f + __expf(-x)); }
;   __device__ __forceinline__ void operator()(EPI_ARGS) const {
;     ...
;     for (int bj = 0; bj < 2; ++bj) {
;       const int c = col0 + bj * HALF;
;       const f32x4 s0 = *(const f32x4*)(psc + c), s1 = *(const f32x4*)(psc + c + 4);
; #pragma unroll
;       for (int ai = 0; ai < 2; ++ai) {
;         u32x4 z[4];
; #pragma unroll
;         for (int m = 0; m < 4; ++m) z[m] = *(const u32x4*)(proj + pidx(row0 + ai * HALF + m * 16, PZ + c));
;         __builtin_amdgcn_sched_barrier(0);
; #pragma unroll
;         for (int m = 0; m < 4; ++m) {
;           const size_t row = row0 + ai * HALF + m * 16;
;           const f32x4 v0 = acc[ai][bj][m][0], v1 = acc[ai][bj][m][1];
;           u32x4 o;
;           o.x = pack2(v0[0] * s0[0] * siluf_(bflo(z[m].x)), v0[1] * s0[1] * siluf_(bfhi(z[m].x)));
;           o.y = pack2(v0[2] * s0[2] * siluf_(bflo(z[m].y)), v0[3] * s0[3] * siluf_(bfhi(z[m].y)));
;           o.z = pack2(v1[0] * s1[0] * siluf_(bflo(z[m].z)), v1[1] * s1[1] * siluf_(bfhi(z[m].z)));
;           o.w = pack2(v1[2] * s1[2] * siluf_(bflo(z[m].w)), v1[3] * s1[3] * siluf_(bfhi(z[m].w)));
;           *(u32x4*)(y0 + row * DM + c) = o;
;         }
;       }
;     }
	v_lshlrev_b32_e32 v115, 16, v134
	v_cvt_pk_bf16_f32 v113, v2, v113
	v_mul_f32_e32 v2, 0xbfb8aa3b, v115
	v_exp_f32_e32 v2, v2
	v_mov_b32_e32 v116, v108
	v_mov_b32_e32 v114, v92
	v_add_f32_e32 v2, 1.0, v2
	v_rcp_f32_e32 v117, v2
	s_nop 0
	v_pk_mul_f32 v[114:115], v[116:117], v[114:115]
	s_nop 0
	v_mul_f32_e32 v2, v114, v115
	v_and_b32_e32 v115, 0xffff0000, v134
	v_mul_f32_e32 v108, 0xbfb8aa3b, v115
	v_exp_f32_e32 v108, v108
	v_mov_b32_e32 v116, v109
	v_mov_b32_e32 v114, v93
	v_add_f32_e32 v108, 1.0, v108
	v_rcp_f32_e32 v117, v108
	s_nop 0
	v_pk_mul_f32 v[108:109], v[116:117], v[114:115]
	s_nop 0
	v_mul_f32_e32 v108, v108, v109
	v_lshlrev_b32_e32 v109, 16, v135
	v_cvt_pk_bf16_f32 v114, v2, v108
	v_mul_f32_e32 v2, 0xbfb8aa3b, v109
	v_exp_f32_e32 v2, v2
	v_mov_b32_e32 v116, v110
	v_mov_b32_e32 v108, v94
	v_add_f32_e32 v2, 1.0, v2
	v_rcp_f32_e32 v117, v2
	s_nop 0
	v_pk_mul_f32 v[108:109], v[116:117], v[108:109]
	s_nop 0
	v_mul_f32_e32 v2, v108, v109
	v_and_b32_e32 v109, 0xffff0000, v135
	v_mul_f32_e32 v108, 0xbfb8aa3b, v109
	v_exp_f32_e32 v108, v108
	v_mov_b32_e32 v116, v111
	v_lshlrev_b64 v[134:135], 9, v[144:145]
	v_add_f32_e32 v108, 1.0, v108
	v_rcp_f32_e32 v117, v108
	v_mov_b32_e32 v108, v95
	v_pk_mul_f32 v[108:109], v[116:117], v[108:109]
	s_nop 0
	v_mul_f32_e32 v108, v108, v109
	v_cvt_pk_bf16_f32 v115, v2, v108
	v_lshlrev_b64 v[108:109], 12, v[190:191]
	v_lshl_add_u64 v[108:109], s[8:9], 0, v[108:109]
	v_lshl_add_u64 v[126:127], v[108:109], 0, v[140:141]
	flat_store_dwordx4 v[126:127], v[112:115]
	v_lshl_add_u64 v[108:109], v[188:189], 0, v[130:131]
	flat_load_dwordx4 v[120:123], v[108:109]
	v_lshl_add_u64 v[108:109], v[188:189], 0, v[132:133]
	flat_load_dwordx4 v[116:119], v[108:109]
	v_lshl_add_u64 v[108:109], v[188:189], 0, v[134:135]
	flat_load_dwordx4 v[112:115], v[108:109]
	v_lshl_add_u64 v[108:109], v[188:189], 0, v[138:139]
	flat_load_dwordx4 v[108:111], v[108:109]
	s_waitcnt vmcnt(0) lgkmcnt(0)
	v_lshlrev_b32_e32 v151, 16, v120
	v_mul_f32_e32 v2, 0xbfb8aa3b, v151
	v_exp_f32_e32 v2, v2
	v_mov_b32_e32 v152, v104
	v_mov_b32_e32 v150, v100
	v_mov_b32_e32 v175, v3
	v_add_f32_e32 v2, 1.0, v2
	v_rcp_f32_e32 v153, v2
	s_nop 0
	v_pk_mul_f32 v[150:151], v[152:153], v[150:151]
	s_nop 0
	v_mul_f32_e32 v2, v150, v151
	v_and_b32_e32 v151, 0xffff0000, v120
	v_mul_f32_e32 v104, 0xbfb8aa3b, v151
	v_exp_f32_e32 v104, v104
	v_mov_b32_e32 v152, v105
	v_mov_b32_e32 v150, v101
	v_mov_b32_e32 v120, v103
	v_add_f32_e32 v104, 1.0, v104
	v_rcp_f32_e32 v153, v104
	s_nop 0
	v_pk_mul_f32 v[104:105], v[152:153], v[150:151]
	s_nop 0
	v_mul_f32_e32 v104, v104, v105
	v_lshlrev_b32_e32 v151, 16, v121
	v_cvt_pk_bf16_f32 v104, v2, v104
	v_mul_f32_e32 v2, 0xbfb8aa3b, v151
	v_exp_f32_e32 v2, v2
	v_and_b32_e32 v121, 0xffff0000, v121
	v_mul_f32_e32 v105, 0xbfb8aa3b, v121
	v_exp_f32_e32 v105, v105
	v_add_f32_e32 v2, 1.0, v2
	v_rcp_f32_e32 v153, v2
	v_mov_b32_e32 v152, v106
	v_mov_b32_e32 v150, v102
	v_add_f32_e32 v105, 1.0, v105
	v_pk_mul_f32 v[150:151], v[152:153], v[150:151]
	s_nop 0
	v_mul_f32_e32 v2, v150, v151
	v_rcp_f32_e32 v151, v105
	v_mov_b32_e32 v150, v107
	v_pk_mul_f32 v[106:107], v[150:151], v[120:121]
	s_nop 0
	v_mul_f32_e32 v105, v106, v107
	v_lshlrev_b32_e32 v107, 16, v122
	v_cvt_pk_bf16_f32 v105, v2, v105
	v_mul_f32_e32 v2, 0xbfb8aa3b, v107
	v_exp_f32_e32 v2, v2
	v_mov_b32_e32 v120, v96
	v_mov_b32_e32 v106, v92
	v_add_f32_e32 v2, 1.0, v2
	v_rcp_f32_e32 v121, v2
	s_nop 0
	v_pk_mul_f32 v[106:107], v[120:121], v[106:107]
	s_nop 0
	v_mul_f32_e32 v2, v106, v107
	v_and_b32_e32 v107, 0xffff0000, v122
	v_mul_f32_e32 v96, 0xbfb8aa3b, v107
	v_exp_f32_e32 v96, v96
	v_mov_b32_e32 v120, v97
	v_mov_b32_e32 v106, v93
	v_add_f32_e32 v96, 1.0, v96
	v_rcp_f32_e32 v121, v96
	s_nop 0
	v_pk_mul_f32 v[96:97], v[120:121], v[106:107]
	s_nop 0
	v_mul_f32_e32 v96, v96, v97
	v_lshlrev_b32_e32 v97, 16, v123
	v_cvt_pk_bf16_f32 v106, v2, v96
	v_mul_f32_e32 v2, 0xbfb8aa3b, v97
	v_exp_f32_e32 v2, v2
	v_mov_b32_e32 v120, v98
	v_mov_b32_e32 v96, v94
	v_mov_b32_e32 v98, v100
	v_add_f32_e32 v2, 1.0, v2
	v_rcp_f32_e32 v121, v2
	s_nop 0
	v_pk_mul_f32 v[96:97], v[120:121], v[96:97]
	s_nop 0
	v_mul_f32_e32 v2, v96, v97
	v_and_b32_e32 v97, 0xffff0000, v123
	v_mul_f32_e32 v96, 0xbfb8aa3b, v97
	v_exp_f32_e32 v96, v96
	v_mov_b32_e32 v120, v99
	v_lshlrev_b32_e32 v99, 16, v116
	v_add_f32_e32 v96, 1.0, v96
	v_rcp_f32_e32 v121, v96
	v_mov_b32_e32 v96, v95
	v_pk_mul_f32 v[96:97], v[120:121], v[96:97]
	s_nop 0
	v_mul_f32_e32 v96, v96, v97
	v_cvt_pk_bf16_f32 v107, v2, v96
	v_mul_f32_e32 v2, 0xbfb8aa3b, v99
	v_exp_f32_e32 v2, v2
	v_lshlrev_b64 v[96:97], 12, v[148:149]
	v_lshl_add_u64 v[96:97], s[8:9], 0, v[96:97]
	v_lshl_add_u64 v[96:97], v[96:97], 0, v[140:141]
	v_add_f32_e32 v2, 1.0, v2
	flat_store_dwordx4 v[96:97], v[104:107]
	s_nop 1
	v_rcp_f32_e32 v105, v2
	v_mov_b32_e32 v104, v88
	v_pk_mul_f32 v[98:99], v[104:105], v[98:99]
	s_nop 0
	v_mul_f32_e32 v2, v98, v99
	v_and_b32_e32 v99, 0xffff0000, v116
	v_mul_f32_e32 v88, 0xbfb8aa3b, v99
	v_exp_f32_e32 v88, v88
	v_mov_b32_e32 v104, v89
	v_mov_b32_e32 v98, v101
	v_add_f32_e32 v88, 1.0, v88
	v_rcp_f32_e32 v105, v88
	s_nop 0
	v_pk_mul_f32 v[88:89], v[104:105], v[98:99]
	s_nop 0
	v_mul_f32_e32 v88, v88, v89
	v_lshlrev_b32_e32 v99, 16, v117
	v_cvt_pk_bf16_f32 v88, v2, v88
	v_mul_f32_e32 v2, 0xbfb8aa3b, v99
	v_exp_f32_e32 v2, v2
	v_mov_b32_e32 v104, v90
	v_mov_b32_e32 v98, v102
	v_add_f32_e32 v2, 1.0, v2
	v_rcp_f32_e32 v105, v2
	s_nop 0
	v_pk_mul_f32 v[98:99], v[104:105], v[98:99]
	s_nop 0
	v_mul_f32_e32 v2, v98, v99
	v_and_b32_e32 v99, 0xffff0000, v117
	v_mul_f32_e32 v89, 0xbfb8aa3b, v99
	v_exp_f32_e32 v89, v89
	v_mov_b32_e32 v104, v91
	v_mov_b32_e32 v98, v103
; __device__ __forceinline__ size_t pidx(size_t row, int col) { return ((size_t)(col >> 8) * MTOK + row) * PLD + (col & 255); }
; __device__ __forceinline__ float bflo(unsigned v) { return __uint_as_float(v << 16); }
; __device__ __forceinline__ float bfhi(unsigned v) { return __uint_as_float(v & 0xffff0000u); }
; __device__ __forceinline__ float siluf_(float x) { return x * __builtin_amdgcn_rcpf(1.0f + __expf(-x)); }
;   __device__ __forceinline__ void operator()(EPI_ARGS) const {
;     ...
;     for (int bj = 0; bj < 2; ++bj) {
;       const int c = col0 + bj * HALF;
;       const f32x4 s0 = *(const f32x4*)(psc + c), s1 = *(const f32x4*)(psc + c + 4);
; #pragma unroll
;       for (int ai = 0; ai < 2; ++ai) {
;         u32x4 z[4];
; #pragma unroll
;         for (int m = 0; m < 4; ++m) z[m] = *(const u32x4*)(proj + pidx(row0 + ai * HALF + m * 16, PZ + c));
;         __builtin_amdgcn_sched_barrier(0);
; #pragma unroll
;         for (int m = 0; m < 4; ++m) {
;           const size_t row = row0 + ai * HALF + m * 16;
;           const f32x4 v0 = acc[ai][bj][m][0], v1 = acc[ai][bj][m][1];
;           u32x4 o;
;           o.x = pack2(v0[0] * s0[0] * siluf_(bflo(z[m].x)), v0[1] * s0[1] * siluf_(bfhi(z[m].x)));
;           o.y = pack2(v0[2] * s0[2] * siluf_(bflo(z[m].y)), v0[3] * s0[3] * siluf_(bfhi(z[m].y)));
;           o.z = pack2(v1[0] * s1[0] * siluf_(bflo(z[m].z)), v1[1] * s1[1] * siluf_(bfhi(z[m].z)));
;           o.w = pack2(v1[2] * s1[2] * siluf_(bflo(z[m].w)), v1[3] * s1[3] * siluf_(bfhi(z[m].w)));
;           *(u32x4*)(y0 + row * DM + c) = o;
;         }
;       }
;     }
	v_add_f32_e32 v89, 1.0, v89
	v_rcp_f32_e32 v105, v89
	s_nop 0
	v_pk_mul_f32 v[90:91], v[104:105], v[98:99]
	s_nop 0
	v_mul_f32_e32 v89, v90, v91
	v_lshlrev_b32_e32 v91, 16, v118
	v_cvt_pk_bf16_f32 v89, v2, v89
	v_mul_f32_e32 v2, 0xbfb8aa3b, v91
	v_exp_f32_e32 v2, v2
	v_mov_b32_e32 v98, v84
	v_mov_b32_e32 v90, v92
	v_add_f32_e32 v2, 1.0, v2
	v_rcp_f32_e32 v99, v2
	s_nop 0
	v_pk_mul_f32 v[90:91], v[98:99], v[90:91]
	s_nop 0
	v_mul_f32_e32 v2, v90, v91
	v_and_b32_e32 v91, 0xffff0000, v118
	v_mul_f32_e32 v84, 0xbfb8aa3b, v91
	v_exp_f32_e32 v84, v84
	v_mov_b32_e32 v98, v85
	v_mov_b32_e32 v90, v93
	v_add_f32_e32 v84, 1.0, v84
	v_rcp_f32_e32 v99, v84
	s_nop 0
	v_pk_mul_f32 v[84:85], v[98:99], v[90:91]
	s_nop 0
	v_mul_f32_e32 v84, v84, v85
	v_lshlrev_b32_e32 v85, 16, v119
	v_cvt_pk_bf16_f32 v90, v2, v84
	v_mul_f32_e32 v2, 0xbfb8aa3b, v85
	v_exp_f32_e32 v2, v2
	v_mov_b32_e32 v98, v86
	v_mov_b32_e32 v84, v94
	v_mov_b32_e32 v86, v80
	v_add_f32_e32 v2, 1.0, v2
	v_rcp_f32_e32 v99, v2
	s_nop 0
	v_pk_mul_f32 v[84:85], v[98:99], v[84:85]
	s_nop 0
	v_mul_f32_e32 v2, v84, v85
	v_and_b32_e32 v85, 0xffff0000, v119
	v_mul_f32_e32 v84, 0xbfb8aa3b, v85
	v_exp_f32_e32 v84, v84
	v_mov_b32_e32 v98, v87
	v_add_f32_e32 v84, 1.0, v84
	v_rcp_f32_e32 v99, v84
	v_mov_b32_e32 v84, v95
	v_pk_mul_f32 v[84:85], v[98:99], v[84:85]
	s_nop 0
	v_mul_f32_e32 v84, v84, v85
	v_cvt_pk_bf16_f32 v91, v2, v84
	v_lshlrev_b64 v[84:85], 12, v[146:147]
	v_lshl_add_u64 v[84:85], s[8:9], 0, v[84:85]
	v_lshl_add_u64 v[98:99], v[84:85], 0, v[140:141]
	v_lshlrev_b32_e32 v85, 16, v112
	v_mul_f32_e32 v2, 0xbfb8aa3b, v85
	v_exp_f32_e32 v2, v2
	v_mov_b32_e32 v84, v100
	flat_store_dwordx4 v[98:99], v[88:91]
	v_add_f32_e32 v2, 1.0, v2
	v_rcp_f32_e32 v87, v2
	s_nop 0
	v_pk_mul_f32 v[84:85], v[86:87], v[84:85]
	s_nop 0
	v_mul_f32_e32 v2, v84, v85
	v_and_b32_e32 v85, 0xffff0000, v112
	v_mul_f32_e32 v80, 0xbfb8aa3b, v85
	v_exp_f32_e32 v80, v80
	v_mov_b32_e32 v86, v81
	v_mov_b32_e32 v84, v101
	v_add_f32_e32 v80, 1.0, v80
	v_rcp_f32_e32 v87, v80
	s_nop 0
	v_pk_mul_f32 v[80:81], v[86:87], v[84:85]
	s_nop 0
	v_mul_f32_e32 v80, v80, v81
	v_lshlrev_b32_e32 v85, 16, v113
	v_cvt_pk_bf16_f32 v80, v2, v80
	v_mul_f32_e32 v2, 0xbfb8aa3b, v85
	v_exp_f32_e32 v2, v2
	v_mov_b32_e32 v86, v82
	v_mov_b32_e32 v84, v102
	v_add_f32_e32 v2, 1.0, v2
	v_rcp_f32_e32 v87, v2
	s_nop 0
	v_pk_mul_f32 v[84:85], v[86:87], v[84:85]
	s_nop 0
	v_mul_f32_e32 v2, v84, v85
	v_and_b32_e32 v85, 0xffff0000, v113
	v_mul_f32_e32 v81, 0xbfb8aa3b, v85
	v_exp_f32_e32 v81, v81
	v_mov_b32_e32 v86, v83
	v_mov_b32_e32 v84, v103
	v_add_f32_e32 v81, 1.0, v81
	v_rcp_f32_e32 v87, v81
	s_nop 0
	v_pk_mul_f32 v[82:83], v[86:87], v[84:85]
	s_nop 0
	v_mul_f32_e32 v81, v82, v83
	v_lshlrev_b32_e32 v83, 16, v114
	v_cvt_pk_bf16_f32 v81, v2, v81
	v_mul_f32_e32 v2, 0xbfb8aa3b, v83
	v_exp_f32_e32 v2, v2
	v_mov_b32_e32 v84, v76
	v_mov_b32_e32 v82, v92
	v_add_f32_e32 v2, 1.0, v2
	v_rcp_f32_e32 v85, v2
	s_nop 0
	v_pk_mul_f32 v[82:83], v[84:85], v[82:83]
	s_nop 0
	v_mul_f32_e32 v2, v82, v83
	v_and_b32_e32 v83, 0xffff0000, v114
	v_mul_f32_e32 v76, 0xbfb8aa3b, v83
	v_exp_f32_e32 v76, v76
	v_mov_b32_e32 v84, v77
	v_mov_b32_e32 v82, v93
	v_add_f32_e32 v76, 1.0, v76
	v_rcp_f32_e32 v85, v76
	s_nop 0
	v_pk_mul_f32 v[76:77], v[84:85], v[82:83]
	s_nop 0
	v_mul_f32_e32 v76, v76, v77
	v_lshlrev_b32_e32 v77, 16, v115
	v_cvt_pk_bf16_f32 v82, v2, v76
	v_mul_f32_e32 v2, 0xbfb8aa3b, v77
	v_exp_f32_e32 v2, v2
	v_mov_b32_e32 v84, v78
	v_mov_b32_e32 v76, v94
	v_mov_b32_e32 v78, v72
	v_add_f32_e32 v2, 1.0, v2
	v_rcp_f32_e32 v85, v2
	s_nop 0
	v_pk_mul_f32 v[76:77], v[84:85], v[76:77]
	s_nop 0
	v_mul_f32_e32 v2, v76, v77
	v_and_b32_e32 v77, 0xffff0000, v115
	v_mul_f32_e32 v76, 0xbfb8aa3b, v77
	v_exp_f32_e32 v76, v76
	v_mov_b32_e32 v84, v79
	v_add_f32_e32 v76, 1.0, v76
	v_rcp_f32_e32 v85, v76
	v_mov_b32_e32 v76, v95
	v_pk_mul_f32 v[76:77], v[84:85], v[76:77]
	s_nop 0
	v_mul_f32_e32 v76, v76, v77
	v_cvt_pk_bf16_f32 v83, v2, v76
	v_lshlrev_b64 v[76:77], 12, v[144:145]
	v_lshl_add_u64 v[76:77], s[8:9], 0, v[76:77]
	v_lshl_add_u64 v[104:105], v[76:77], 0, v[140:141]
	v_lshlrev_b32_e32 v77, 16, v108
	v_mul_f32_e32 v2, 0xbfb8aa3b, v77
	v_exp_f32_e32 v2, v2
	v_mov_b32_e32 v76, v100
	flat_store_dwordx4 v[104:105], v[80:83]
	v_add_f32_e32 v2, 1.0, v2
	v_rcp_f32_e32 v79, v2
	s_nop 0
	v_pk_mul_f32 v[76:77], v[78:79], v[76:77]
	s_nop 0
	v_mul_f32_e32 v2, v76, v77
	v_and_b32_e32 v77, 0xffff0000, v108
	v_mul_f32_e32 v72, 0xbfb8aa3b, v77
	v_exp_f32_e32 v72, v72
	v_mov_b32_e32 v78, v73
	v_mov_b32_e32 v76, v101
	v_add_f32_e32 v72, 1.0, v72
	v_rcp_f32_e32 v79, v72
	s_nop 0
	v_pk_mul_f32 v[72:73], v[78:79], v[76:77]
	s_nop 0
	v_mul_f32_e32 v72, v72, v73
	v_lshlrev_b32_e32 v77, 16, v109
	v_cvt_pk_bf16_f32 v72, v2, v72
	v_mul_f32_e32 v2, 0xbfb8aa3b, v77
	v_exp_f32_e32 v2, v2
	v_mov_b32_e32 v78, v74
	v_mov_b32_e32 v76, v102
	v_add_f32_e32 v2, 1.0, v2
	v_rcp_f32_e32 v79, v2
	s_nop 0
	v_pk_mul_f32 v[76:77], v[78:79], v[76:77]
	s_nop 0
	v_mul_f32_e32 v2, v76, v77
	v_and_b32_e32 v77, 0xffff0000, v109
	v_mul_f32_e32 v73, 0xbfb8aa3b, v77
	v_exp_f32_e32 v73, v73
	v_mov_b32_e32 v78, v75
	v_mov_b32_e32 v76, v103
	v_add_f32_e32 v73, 1.0, v73
	v_rcp_f32_e32 v79, v73
	s_nop 0
	v_pk_mul_f32 v[74:75], v[78:79], v[76:77]
	s_nop 0
	v_mul_f32_e32 v73, v74, v75
	v_lshlrev_b32_e32 v75, 16, v110
	v_cvt_pk_bf16_f32 v73, v2, v73
	v_mul_f32_e32 v2, 0xbfb8aa3b, v75
	v_exp_f32_e32 v2, v2
	v_mov_b32_e32 v76, v68
	v_mov_b32_e32 v74, v92
	v_add_f32_e32 v2, 1.0, v2
	v_rcp_f32_e32 v77, v2
	s_nop 0
	v_pk_mul_f32 v[74:75], v[76:77], v[74:75]
	s_nop 0
	v_mul_f32_e32 v2, v74, v75
	v_and_b32_e32 v75, 0xffff0000, v110
	v_mul_f32_e32 v68, 0xbfb8aa3b, v75
; __device__ __forceinline__ size_t pidx(size_t row, int col) { return ((size_t)(col >> 8) * MTOK + row) * PLD + (col & 255); }
; __device__ __forceinline__ float bflo(unsigned v) { return __uint_as_float(v << 16); }
; __device__ __forceinline__ float bfhi(unsigned v) { return __uint_as_float(v & 0xffff0000u); }
; __device__ __forceinline__ float siluf_(float x) { return x * __builtin_amdgcn_rcpf(1.0f + __expf(-x)); }
;   __device__ __forceinline__ void operator()(EPI_ARGS) const {
;     ...
;     for (int bj = 0; bj < 2; ++bj) {
;       const int c = col0 + bj * HALF;
;       const f32x4 s0 = *(const f32x4*)(psc + c), s1 = *(const f32x4*)(psc + c + 4);
; #pragma unroll
;       for (int ai = 0; ai < 2; ++ai) {
;         u32x4 z[4];
; #pragma unroll
;         for (int m = 0; m < 4; ++m) z[m] = *(const u32x4*)(proj + pidx(row0 + ai * HALF + m * 16, PZ + c));
;         __builtin_amdgcn_sched_barrier(0);
; #pragma unroll
;         for (int m = 0; m < 4; ++m) {
;           const size_t row = row0 + ai * HALF + m * 16;
;           const f32x4 v0 = acc[ai][bj][m][0], v1 = acc[ai][bj][m][1];
;           u32x4 o;
;           o.x = pack2(v0[0] * s0[0] * siluf_(bflo(z[m].x)), v0[1] * s0[1] * siluf_(bfhi(z[m].x)));
;           o.y = pack2(v0[2] * s0[2] * siluf_(bflo(z[m].y)), v0[3] * s0[3] * siluf_(bfhi(z[m].y)));
;           o.z = pack2(v1[0] * s1[0] * siluf_(bflo(z[m].z)), v1[1] * s1[1] * siluf_(bfhi(z[m].z)));
;           o.w = pack2(v1[2] * s1[2] * siluf_(bflo(z[m].w)), v1[3] * s1[3] * siluf_(bfhi(z[m].w)));
;           *(u32x4*)(y0 + row * DM + c) = o;
;         }
;       }
;     }
	v_exp_f32_e32 v68, v68
	v_mov_b32_e32 v76, v69
	v_mov_b32_e32 v74, v93
	v_add_f32_e32 v68, 1.0, v68
	v_rcp_f32_e32 v77, v68
	s_nop 0
	v_pk_mul_f32 v[68:69], v[76:77], v[74:75]
	s_nop 0
	v_mul_f32_e32 v68, v68, v69
	v_lshlrev_b32_e32 v69, 16, v111
	v_cvt_pk_bf16_f32 v74, v2, v68
	v_mul_f32_e32 v2, 0xbfb8aa3b, v69
	v_exp_f32_e32 v2, v2
	v_mov_b32_e32 v76, v70
	v_mov_b32_e32 v68, v94
	v_add_f32_e32 v2, 1.0, v2
	v_rcp_f32_e32 v77, v2
	s_nop 0
	v_pk_mul_f32 v[68:69], v[76:77], v[68:69]
	s_nop 0
	v_mul_f32_e32 v2, v68, v69
	v_and_b32_e32 v69, 0xffff0000, v111
	v_mul_f32_e32 v68, 0xbfb8aa3b, v69
	v_exp_f32_e32 v68, v68
	v_mov_b32_e32 v76, v71
	v_add_f32_e32 v68, 1.0, v68
	v_rcp_f32_e32 v77, v68
	v_mov_b32_e32 v68, v95
	v_lshl_add_u64 v[94:95], s[2:3], 0, v[174:175]
	v_pk_mul_f32 v[68:69], v[76:77], v[68:69]
	s_nop 0
	v_mul_f32_e32 v68, v68, v69
	v_cvt_pk_bf16_f32 v75, v2, v68
	v_lshlrev_b64 v[68:69], 12, v[142:143]
	v_lshl_add_u64 v[68:69], s[8:9], 0, v[68:69]
	v_lshl_add_u64 v[92:93], v[68:69], 0, v[140:141]
	flat_store_dwordx4 v[92:93], v[72:75]
	v_lshl_add_u64 v[76:77], v[94:95], 0, v[178:179]
	global_load_dwordx4 v[68:71], v[176:177], off offset:528
	global_load_dwordx4 v[72:75], v[176:177], off offset:512
	flat_load_dwordx4 v[88:91], v[76:77]
	v_lshl_add_u64 v[76:77], v[94:95], 0, v[180:181]
	flat_load_dwordx4 v[84:87], v[76:77]
	v_lshl_add_u64 v[76:77], v[94:95], 0, v[182:183]
	flat_load_dwordx4 v[80:83], v[76:77]
	v_lshl_add_u64 v[76:77], v[94:95], 0, v[184:185]
	flat_load_dwordx4 v[76:79], v[76:77]
	s_waitcnt vmcnt(0) lgkmcnt(0)
	v_lshlrev_b32_e32 v101, 16, v88
	v_mul_f32_e32 v2, 0xbfb8aa3b, v101
	v_exp_f32_e32 v2, v2
	v_mov_b32_e32 v102, v64
	v_mov_b32_e32 v100, v72
	v_add_f32_e32 v2, 1.0, v2
	v_rcp_f32_e32 v103, v2
	s_nop 0
	v_pk_mul_f32 v[100:101], v[102:103], v[100:101]
	s_nop 0
	v_mul_f32_e32 v2, v100, v101
	v_and_b32_e32 v101, 0xffff0000, v88
	v_mul_f32_e32 v64, 0xbfb8aa3b, v101
	v_exp_f32_e32 v64, v64
	v_mov_b32_e32 v102, v65
	v_mov_b32_e32 v100, v73
	v_mov_b32_e32 v88, v75
	v_add_f32_e32 v64, 1.0, v64
	v_rcp_f32_e32 v103, v64
	s_nop 0
	v_pk_mul_f32 v[64:65], v[102:103], v[100:101]
	s_nop 0
	v_mul_f32_e32 v64, v64, v65
	v_lshlrev_b32_e32 v101, 16, v89
	v_cvt_pk_bf16_f32 v64, v2, v64
	v_mul_f32_e32 v2, 0xbfb8aa3b, v101
	v_exp_f32_e32 v2, v2
	v_and_b32_e32 v89, 0xffff0000, v89
	v_mul_f32_e32 v65, 0xbfb8aa3b, v89
	v_exp_f32_e32 v65, v65
	v_add_f32_e32 v2, 1.0, v2
	v_rcp_f32_e32 v103, v2
	v_mov_b32_e32 v102, v66
	v_mov_b32_e32 v100, v74
	v_add_f32_e32 v65, 1.0, v65
	v_pk_mul_f32 v[100:101], v[102:103], v[100:101]
	s_nop 0
	v_mul_f32_e32 v2, v100, v101
	v_rcp_f32_e32 v101, v65
	v_mov_b32_e32 v100, v67
	v_pk_mul_f32 v[66:67], v[100:101], v[88:89]
	s_nop 0
	v_mul_f32_e32 v65, v66, v67
	v_lshlrev_b32_e32 v67, 16, v90
	v_cvt_pk_bf16_f32 v65, v2, v65
	v_mul_f32_e32 v2, 0xbfb8aa3b, v67
	v_exp_f32_e32 v2, v2
	v_mov_b32_e32 v88, v60
	v_mov_b32_e32 v66, v68
	v_add_f32_e32 v2, 1.0, v2
	v_rcp_f32_e32 v89, v2
	s_nop 0
	v_pk_mul_f32 v[66:67], v[88:89], v[66:67]
	s_nop 0
	v_mul_f32_e32 v2, v66, v67
	v_and_b32_e32 v67, 0xffff0000, v90
	v_mul_f32_e32 v60, 0xbfb8aa3b, v67
	v_exp_f32_e32 v60, v60
	v_mov_b32_e32 v88, v61
	v_mov_b32_e32 v66, v69
	v_add_f32_e32 v60, 1.0, v60
	v_rcp_f32_e32 v89, v60
	s_nop 0
	v_pk_mul_f32 v[60:61], v[88:89], v[66:67]
	s_nop 0
	v_mul_f32_e32 v60, v60, v61
	v_lshlrev_b32_e32 v61, 16, v91
	v_cvt_pk_bf16_f32 v66, v2, v60
	v_mul_f32_e32 v2, 0xbfb8aa3b, v61
	v_exp_f32_e32 v2, v2
	v_mov_b32_e32 v88, v62
	v_mov_b32_e32 v60, v70
	v_mov_b32_e32 v62, v56
	v_add_f32_e32 v2, 1.0, v2
	v_rcp_f32_e32 v89, v2
	s_nop 0
	v_pk_mul_f32 v[60:61], v[88:89], v[60:61]
	s_nop 0
	v_mul_f32_e32 v2, v60, v61
	v_and_b32_e32 v61, 0xffff0000, v91
	v_mul_f32_e32 v60, 0xbfb8aa3b, v61
	v_exp_f32_e32 v60, v60
	v_mov_b32_e32 v88, v63
	v_add_f32_e32 v60, 1.0, v60
	v_rcp_f32_e32 v89, v60
	v_mov_b32_e32 v60, v71
	v_pk_mul_f32 v[60:61], v[88:89], v[60:61]
	s_nop 0
	v_mul_f32_e32 v60, v60, v61
	v_lshlrev_b32_e32 v61, 16, v84
	v_cvt_pk_bf16_f32 v67, v2, v60
	v_mul_f32_e32 v2, 0xbfb8aa3b, v61
	v_exp_f32_e32 v2, v2
	v_mov_b32_e32 v60, v72
	flat_store_dwordx4 v[136:137], v[64:67] offset:256
	v_add_f32_e32 v2, 1.0, v2
	v_rcp_f32_e32 v63, v2
	s_nop 0
	v_pk_mul_f32 v[60:61], v[62:63], v[60:61]
	s_nop 0
	v_mul_f32_e32 v2, v60, v61
	v_and_b32_e32 v61, 0xffff0000, v84
	v_mul_f32_e32 v56, 0xbfb8aa3b, v61
	v_exp_f32_e32 v56, v56
	v_mov_b32_e32 v62, v57
	v_mov_b32_e32 v60, v73
	v_add_f32_e32 v56, 1.0, v56
	v_rcp_f32_e32 v63, v56
	s_nop 0
	v_pk_mul_f32 v[56:57], v[62:63], v[60:61]
	s_nop 0
	v_mul_f32_e32 v56, v56, v57
	v_lshlrev_b32_e32 v61, 16, v85
	v_cvt_pk_bf16_f32 v56, v2, v56
	v_mul_f32_e32 v2, 0xbfb8aa3b, v61
	v_exp_f32_e32 v2, v2
	v_mov_b32_e32 v62, v58
	v_mov_b32_e32 v60, v74
	v_add_f32_e32 v2, 1.0, v2
	v_rcp_f32_e32 v63, v2
	s_nop 0
	v_pk_mul_f32 v[60:61], v[62:63], v[60:61]
	s_nop 0
	v_mul_f32_e32 v2, v60, v61
	v_and_b32_e32 v61, 0xffff0000, v85
	v_mul_f32_e32 v57, 0xbfb8aa3b, v61
	v_exp_f32_e32 v57, v57
	v_mov_b32_e32 v62, v59
	v_mov_b32_e32 v60, v75
	v_add_f32_e32 v57, 1.0, v57
	v_rcp_f32_e32 v63, v57
	s_nop 0
	v_pk_mul_f32 v[58:59], v[62:63], v[60:61]
	s_nop 0
	v_mul_f32_e32 v57, v58, v59
	v_lshlrev_b32_e32 v59, 16, v86
	v_cvt_pk_bf16_f32 v57, v2, v57
	v_mul_f32_e32 v2, 0xbfb8aa3b, v59
	v_exp_f32_e32 v2, v2
	v_mov_b32_e32 v60, v52
	v_mov_b32_e32 v58, v68
	v_add_f32_e32 v2, 1.0, v2
	v_rcp_f32_e32 v61, v2
	s_nop 0
	v_pk_mul_f32 v[58:59], v[60:61], v[58:59]
	s_nop 0
	v_mul_f32_e32 v2, v58, v59
	v_and_b32_e32 v59, 0xffff0000, v86
	v_mul_f32_e32 v52, 0xbfb8aa3b, v59
	v_exp_f32_e32 v52, v52
	v_mov_b32_e32 v60, v53
	v_mov_b32_e32 v58, v69
	v_add_f32_e32 v52, 1.0, v52
; __device__ __forceinline__ size_t pidx(size_t row, int col) { return ((size_t)(col >> 8) * MTOK + row) * PLD + (col & 255); }
; __device__ __forceinline__ float bflo(unsigned v) { return __uint_as_float(v << 16); }
; __device__ __forceinline__ float bfhi(unsigned v) { return __uint_as_float(v & 0xffff0000u); }
; __device__ __forceinline__ float siluf_(float x) { return x * __builtin_amdgcn_rcpf(1.0f + __expf(-x)); }
;   __device__ __forceinline__ void operator()(EPI_ARGS) const {
;     ...
;     for (int bj = 0; bj < 2; ++bj) {
;       const int c = col0 + bj * HALF;
;       const f32x4 s0 = *(const f32x4*)(psc + c), s1 = *(const f32x4*)(psc + c + 4);
; #pragma unroll
;       for (int ai = 0; ai < 2; ++ai) {
;         u32x4 z[4];
; #pragma unroll
;         for (int m = 0; m < 4; ++m) z[m] = *(const u32x4*)(proj + pidx(row0 + ai * HALF + m * 16, PZ + c));
;         __builtin_amdgcn_sched_barrier(0);
; #pragma unroll
;         for (int m = 0; m < 4; ++m) {
;           const size_t row = row0 + ai * HALF + m * 16;
;           const f32x4 v0 = acc[ai][bj][m][0], v1 = acc[ai][bj][m][1];
;           u32x4 o;
;           o.x = pack2(v0[0] * s0[0] * siluf_(bflo(z[m].x)), v0[1] * s0[1] * siluf_(bfhi(z[m].x)));
;           o.y = pack2(v0[2] * s0[2] * siluf_(bflo(z[m].y)), v0[3] * s0[3] * siluf_(bfhi(z[m].y)));
;           o.z = pack2(v1[0] * s1[0] * siluf_(bflo(z[m].z)), v1[1] * s1[1] * siluf_(bfhi(z[m].z)));
;           o.w = pack2(v1[2] * s1[2] * siluf_(bflo(z[m].w)), v1[3] * s1[3] * siluf_(bfhi(z[m].w)));
;           *(u32x4*)(y0 + row * DM + c) = o;
;         }
;       }
;     }
	v_rcp_f32_e32 v61, v52
	s_nop 0
	v_pk_mul_f32 v[52:53], v[60:61], v[58:59]
	s_nop 0
	v_mul_f32_e32 v52, v52, v53
	v_lshlrev_b32_e32 v53, 16, v87
	v_cvt_pk_bf16_f32 v58, v2, v52
	v_mul_f32_e32 v2, 0xbfb8aa3b, v53
	v_exp_f32_e32 v2, v2
	v_mov_b32_e32 v60, v54
	v_mov_b32_e32 v52, v70
	v_mov_b32_e32 v54, v48
	v_add_f32_e32 v2, 1.0, v2
	v_rcp_f32_e32 v61, v2
	s_nop 0
	v_pk_mul_f32 v[52:53], v[60:61], v[52:53]
	s_nop 0
	v_mul_f32_e32 v2, v52, v53
	v_and_b32_e32 v53, 0xffff0000, v87
	v_mul_f32_e32 v52, 0xbfb8aa3b, v53
	v_exp_f32_e32 v52, v52
	v_mov_b32_e32 v60, v55
	v_add_f32_e32 v52, 1.0, v52
	v_rcp_f32_e32 v61, v52
	v_mov_b32_e32 v52, v71
	v_pk_mul_f32 v[52:53], v[60:61], v[52:53]
	s_nop 0
	v_mul_f32_e32 v52, v52, v53
	v_lshlrev_b32_e32 v53, 16, v80
	v_cvt_pk_bf16_f32 v59, v2, v52
	v_mul_f32_e32 v2, 0xbfb8aa3b, v53
	v_exp_f32_e32 v2, v2
	v_mov_b32_e32 v52, v72
	flat_store_dwordx4 v[124:125], v[56:59] offset:256
	v_add_f32_e32 v2, 1.0, v2
	v_rcp_f32_e32 v55, v2
	s_nop 0
	v_pk_mul_f32 v[52:53], v[54:55], v[52:53]
	s_nop 0
	v_mul_f32_e32 v2, v52, v53
	v_and_b32_e32 v53, 0xffff0000, v80
	v_mul_f32_e32 v48, 0xbfb8aa3b, v53
	v_exp_f32_e32 v48, v48
	v_mov_b32_e32 v54, v49
	v_mov_b32_e32 v52, v73
	v_add_f32_e32 v48, 1.0, v48
	v_rcp_f32_e32 v55, v48
	s_nop 0
	v_pk_mul_f32 v[48:49], v[54:55], v[52:53]
	s_nop 0
	v_mul_f32_e32 v48, v48, v49
	v_lshlrev_b32_e32 v53, 16, v81
	v_cvt_pk_bf16_f32 v48, v2, v48
	v_mul_f32_e32 v2, 0xbfb8aa3b, v53
	v_exp_f32_e32 v2, v2
	v_mov_b32_e32 v54, v50
	v_mov_b32_e32 v52, v74
	v_add_f32_e32 v2, 1.0, v2
	v_rcp_f32_e32 v55, v2
	s_nop 0
	v_pk_mul_f32 v[52:53], v[54:55], v[52:53]
	s_nop 0
	v_mul_f32_e32 v2, v52, v53
	v_and_b32_e32 v53, 0xffff0000, v81
	v_mul_f32_e32 v49, 0xbfb8aa3b, v53
	v_exp_f32_e32 v49, v49
	v_mov_b32_e32 v54, v51
	v_mov_b32_e32 v52, v75
	v_add_f32_e32 v49, 1.0, v49
	v_rcp_f32_e32 v55, v49
	s_nop 0
	v_pk_mul_f32 v[50:51], v[54:55], v[52:53]
	s_nop 0
	v_mul_f32_e32 v49, v50, v51
	v_lshlrev_b32_e32 v51, 16, v82
	v_cvt_pk_bf16_f32 v49, v2, v49
	v_mul_f32_e32 v2, 0xbfb8aa3b, v51
	v_exp_f32_e32 v2, v2
	v_mov_b32_e32 v52, v44
	v_mov_b32_e32 v50, v68
	v_add_f32_e32 v2, 1.0, v2
	v_rcp_f32_e32 v53, v2
	s_nop 0
	v_pk_mul_f32 v[50:51], v[52:53], v[50:51]
	s_nop 0
	v_mul_f32_e32 v2, v50, v51
	v_and_b32_e32 v51, 0xffff0000, v82
	v_mul_f32_e32 v44, 0xbfb8aa3b, v51
	v_exp_f32_e32 v44, v44
	v_mov_b32_e32 v52, v45
	v_mov_b32_e32 v50, v69
	v_add_f32_e32 v44, 1.0, v44
	v_rcp_f32_e32 v53, v44
	s_nop 0
	v_pk_mul_f32 v[44:45], v[52:53], v[50:51]
	s_nop 0
	v_mul_f32_e32 v44, v44, v45
	v_lshlrev_b32_e32 v45, 16, v83
	v_cvt_pk_bf16_f32 v50, v2, v44
	v_mul_f32_e32 v2, 0xbfb8aa3b, v45
	v_exp_f32_e32 v2, v2
	v_mov_b32_e32 v52, v46
	v_mov_b32_e32 v44, v70
	v_mov_b32_e32 v46, v40
	v_add_f32_e32 v2, 1.0, v2
	v_rcp_f32_e32 v53, v2
	s_nop 0
	v_pk_mul_f32 v[44:45], v[52:53], v[44:45]
	s_nop 0
	v_mul_f32_e32 v2, v44, v45
	v_and_b32_e32 v45, 0xffff0000, v83
	v_mul_f32_e32 v44, 0xbfb8aa3b, v45
	v_exp_f32_e32 v44, v44
	v_mov_b32_e32 v52, v47
	v_add_f32_e32 v44, 1.0, v44
	v_rcp_f32_e32 v53, v44
	v_mov_b32_e32 v44, v71
	v_pk_mul_f32 v[44:45], v[52:53], v[44:45]
	s_nop 0
	v_mul_f32_e32 v44, v44, v45
	v_lshlrev_b32_e32 v45, 16, v76
	v_cvt_pk_bf16_f32 v51, v2, v44
	v_mul_f32_e32 v2, 0xbfb8aa3b, v45
	v_exp_f32_e32 v2, v2
	v_mov_b32_e32 v44, v72
	flat_store_dwordx4 v[128:129], v[48:51] offset:256
	v_add_f32_e32 v2, 1.0, v2
	v_rcp_f32_e32 v47, v2
	s_nop 0
	v_pk_mul_f32 v[44:45], v[46:47], v[44:45]
	s_nop 0
	v_mul_f32_e32 v2, v44, v45
	v_and_b32_e32 v45, 0xffff0000, v76
	v_mul_f32_e32 v40, 0xbfb8aa3b, v45
	v_exp_f32_e32 v40, v40
	v_mov_b32_e32 v46, v41
	v_mov_b32_e32 v44, v73
	v_add_f32_e32 v40, 1.0, v40
	v_rcp_f32_e32 v47, v40
	s_nop 0
	v_pk_mul_f32 v[40:41], v[46:47], v[44:45]
	s_nop 0
	v_mul_f32_e32 v40, v40, v41
	v_lshlrev_b32_e32 v45, 16, v77
	v_cvt_pk_bf16_f32 v40, v2, v40
	v_mul_f32_e32 v2, 0xbfb8aa3b, v45
	v_exp_f32_e32 v2, v2
	v_mov_b32_e32 v46, v42
	v_mov_b32_e32 v44, v74
	v_add_f32_e32 v2, 1.0, v2
	v_rcp_f32_e32 v47, v2
	s_nop 0
	v_pk_mul_f32 v[44:45], v[46:47], v[44:45]
	s_nop 0
	v_mul_f32_e32 v2, v44, v45
	v_and_b32_e32 v45, 0xffff0000, v77
	v_mul_f32_e32 v41, 0xbfb8aa3b, v45
	v_exp_f32_e32 v41, v41
	v_mov_b32_e32 v46, v43
	v_mov_b32_e32 v44, v75
	v_add_f32_e32 v41, 1.0, v41
	v_rcp_f32_e32 v47, v41
	s_nop 0
	v_pk_mul_f32 v[42:43], v[46:47], v[44:45]
	s_nop 0
	v_mul_f32_e32 v41, v42, v43
	v_lshlrev_b32_e32 v43, 16, v78
	v_cvt_pk_bf16_f32 v41, v2, v41
	v_mul_f32_e32 v2, 0xbfb8aa3b, v43
	v_exp_f32_e32 v2, v2
	v_mov_b32_e32 v44, v36
	v_mov_b32_e32 v42, v68
	v_add_f32_e32 v2, 1.0, v2
	v_rcp_f32_e32 v45, v2
	s_nop 0
	v_pk_mul_f32 v[42:43], v[44:45], v[42:43]
	s_nop 0
	v_mul_f32_e32 v2, v42, v43
	v_and_b32_e32 v43, 0xffff0000, v78
	v_mul_f32_e32 v36, 0xbfb8aa3b, v43
	v_exp_f32_e32 v36, v36
	v_mov_b32_e32 v44, v37
	v_mov_b32_e32 v42, v69
	v_add_f32_e32 v36, 1.0, v36
	v_rcp_f32_e32 v45, v36
	s_nop 0
	v_pk_mul_f32 v[36:37], v[44:45], v[42:43]
	s_nop 0
	v_mul_f32_e32 v36, v36, v37
	v_lshlrev_b32_e32 v37, 16, v79
	v_cvt_pk_bf16_f32 v42, v2, v36
	v_mul_f32_e32 v2, 0xbfb8aa3b, v37
	v_exp_f32_e32 v2, v2
	v_mov_b32_e32 v44, v38
	v_mov_b32_e32 v36, v70
	v_add_f32_e32 v2, 1.0, v2
	v_rcp_f32_e32 v45, v2
	s_nop 0
	v_pk_mul_f32 v[36:37], v[44:45], v[36:37]
	s_nop 0
	v_mul_f32_e32 v2, v36, v37
	v_and_b32_e32 v37, 0xffff0000, v79
	v_mul_f32_e32 v36, 0xbfb8aa3b, v37
	v_exp_f32_e32 v36, v36
	v_mov_b32_e32 v44, v39
	v_add_f32_e32 v36, 1.0, v36
	v_rcp_f32_e32 v45, v36
	v_mov_b32_e32 v36, v71
	v_pk_mul_f32 v[36:37], v[44:45], v[36:37]
	s_nop 0
	v_mul_f32_e32 v36, v36, v37
	v_cvt_pk_bf16_f32 v43, v2, v36
	flat_store_dwordx4 v[126:127], v[40:43] offset:256
	v_lshl_add_u64 v[36:37], v[94:95], 0, v[130:131]
	flat_load_dwordx4 v[48:51], v[36:37]
	v_lshl_add_u64 v[36:37], v[94:95], 0, v[132:133]
	flat_load_dwordx4 v[44:47], v[36:37]
	v_lshl_add_u64 v[36:37], v[94:95], 0, v[134:135]
	flat_load_dwordx4 v[40:43], v[36:37]
	v_lshl_add_u64 v[36:37], v[94:95], 0, v[138:139]
	flat_load_dwordx4 v[36:39], v[36:37]
	s_waitcnt vmcnt(0) lgkmcnt(0)
; __device__ __forceinline__ size_t pidx(size_t row, int col) { return ((size_t)(col >> 8) * MTOK + row) * PLD + (col & 255); }
; __device__ __forceinline__ float bflo(unsigned v) { return __uint_as_float(v << 16); }
; __device__ __forceinline__ float bfhi(unsigned v) { return __uint_as_float(v & 0xffff0000u); }
; __device__ __forceinline__ float siluf_(float x) { return x * __builtin_amdgcn_rcpf(1.0f + __expf(-x)); }
;   __device__ __forceinline__ void operator()(EPI_ARGS) const {
;     ...
;     for (int bj = 0; bj < 2; ++bj) {
;       const int c = col0 + bj * HALF;
;       const f32x4 s0 = *(const f32x4*)(psc + c), s1 = *(const f32x4*)(psc + c + 4);
; #pragma unroll
;       for (int ai = 0; ai < 2; ++ai) {
;         u32x4 z[4];
; #pragma unroll
;         for (int m = 0; m < 4; ++m) z[m] = *(const u32x4*)(proj + pidx(row0 + ai * HALF + m * 16, PZ + c));
;         __builtin_amdgcn_sched_barrier(0);
; #pragma unroll
;         for (int m = 0; m < 4; ++m) {
;           const size_t row = row0 + ai * HALF + m * 16;
;           const f32x4 v0 = acc[ai][bj][m][0], v1 = acc[ai][bj][m][1];
;           u32x4 o;
;           o.x = pack2(v0[0] * s0[0] * siluf_(bflo(z[m].x)), v0[1] * s0[1] * siluf_(bfhi(z[m].x)));
;           o.y = pack2(v0[2] * s0[2] * siluf_(bflo(z[m].y)), v0[3] * s0[3] * siluf_(bfhi(z[m].y)));
;           o.z = pack2(v1[0] * s1[0] * siluf_(bflo(z[m].z)), v1[1] * s1[1] * siluf_(bfhi(z[m].z)));
;           o.w = pack2(v1[2] * s1[2] * siluf_(bflo(z[m].w)), v1[3] * s1[3] * siluf_(bfhi(z[m].w)));
;           *(u32x4*)(y0 + row * DM + c) = o;
;         }
;       }
;     }
	v_lshlrev_b32_e32 v53, 16, v48
	v_mul_f32_e32 v2, 0xbfb8aa3b, v53
	v_exp_f32_e32 v2, v2
	v_mov_b32_e32 v54, v32
	v_mov_b32_e32 v52, v72
	s_and_b64 vcc, exec, s[18:19]
	v_add_f32_e32 v2, 1.0, v2
	v_rcp_f32_e32 v55, v2
	s_mov_b32 s33, s16
	s_mov_b32 s2, s14
	s_mov_b64 s[4:5], s[22:23]
	v_pk_mul_f32 v[52:53], v[54:55], v[52:53]
	v_mov_b32_e32 v54, v33
	v_mul_f32_e32 v2, v52, v53
	v_and_b32_e32 v53, 0xffff0000, v48
	v_mul_f32_e32 v32, 0xbfb8aa3b, v53
	v_exp_f32_e32 v32, v32
	v_mov_b32_e32 v52, v73
	v_mov_b32_e32 v48, v75
	s_mov_b64 s[6:7], s[20:21]
	v_add_f32_e32 v32, 1.0, v32
	v_rcp_f32_e32 v55, v32
	s_nop 0
	v_pk_mul_f32 v[32:33], v[54:55], v[52:53]
	s_nop 0
	v_mul_f32_e32 v32, v32, v33
	v_lshlrev_b32_e32 v53, 16, v49
	v_cvt_pk_bf16_f32 v32, v2, v32
	v_mul_f32_e32 v2, 0xbfb8aa3b, v53
	v_exp_f32_e32 v2, v2
	v_and_b32_e32 v49, 0xffff0000, v49
	v_mul_f32_e32 v33, 0xbfb8aa3b, v49
	v_exp_f32_e32 v33, v33
	v_add_f32_e32 v2, 1.0, v2
	v_rcp_f32_e32 v55, v2
	v_mov_b32_e32 v54, v34
	v_mov_b32_e32 v52, v74
	v_add_f32_e32 v33, 1.0, v33
	v_pk_mul_f32 v[52:53], v[54:55], v[52:53]
	s_nop 0
	v_mul_f32_e32 v2, v52, v53
	v_rcp_f32_e32 v53, v33
	v_mov_b32_e32 v52, v35
	v_pk_mul_f32 v[34:35], v[52:53], v[48:49]
	s_nop 0
	v_mul_f32_e32 v33, v34, v35
	v_lshlrev_b32_e32 v35, 16, v50
	v_cvt_pk_bf16_f32 v33, v2, v33
	v_mul_f32_e32 v2, 0xbfb8aa3b, v35
	v_exp_f32_e32 v2, v2
	v_mov_b32_e32 v48, v28
	v_mov_b32_e32 v34, v68
	v_add_f32_e32 v2, 1.0, v2
	v_rcp_f32_e32 v49, v2
	s_nop 0
	v_pk_mul_f32 v[34:35], v[48:49], v[34:35]
	s_nop 0
	v_mul_f32_e32 v2, v34, v35
	v_and_b32_e32 v35, 0xffff0000, v50
	v_mul_f32_e32 v28, 0xbfb8aa3b, v35
	v_exp_f32_e32 v28, v28
	v_mov_b32_e32 v48, v29
	v_mov_b32_e32 v34, v69
	v_add_f32_e32 v28, 1.0, v28
	v_rcp_f32_e32 v49, v28
	s_nop 0
	v_pk_mul_f32 v[28:29], v[48:49], v[34:35]
	s_nop 0
	v_mul_f32_e32 v28, v28, v29
	v_lshlrev_b32_e32 v29, 16, v51
	v_cvt_pk_bf16_f32 v34, v2, v28
	v_mul_f32_e32 v2, 0xbfb8aa3b, v29
	v_exp_f32_e32 v2, v2
	v_mov_b32_e32 v48, v30
	v_mov_b32_e32 v28, v70
	v_mov_b32_e32 v30, v24
	v_add_f32_e32 v2, 1.0, v2
	v_rcp_f32_e32 v49, v2
	s_nop 0
	v_pk_mul_f32 v[28:29], v[48:49], v[28:29]
	s_nop 0
	v_mul_f32_e32 v2, v28, v29
	v_and_b32_e32 v29, 0xffff0000, v51
	v_mul_f32_e32 v28, 0xbfb8aa3b, v29
	v_exp_f32_e32 v28, v28
	v_mov_b32_e32 v48, v31
	v_add_f32_e32 v28, 1.0, v28
	v_rcp_f32_e32 v49, v28
	v_mov_b32_e32 v28, v71
	v_pk_mul_f32 v[28:29], v[48:49], v[28:29]
	s_nop 0
	v_mul_f32_e32 v28, v28, v29
	v_lshlrev_b32_e32 v29, 16, v44
	v_cvt_pk_bf16_f32 v35, v2, v28
	v_mul_f32_e32 v2, 0xbfb8aa3b, v29
	v_exp_f32_e32 v2, v2
	v_mov_b32_e32 v28, v72
	flat_store_dwordx4 v[96:97], v[32:35] offset:256
	v_add_f32_e32 v2, 1.0, v2
	v_rcp_f32_e32 v31, v2
	s_nop 0
	v_pk_mul_f32 v[28:29], v[30:31], v[28:29]
	s_nop 0
	v_mul_f32_e32 v2, v28, v29
	v_and_b32_e32 v29, 0xffff0000, v44
	v_mul_f32_e32 v24, 0xbfb8aa3b, v29
	v_exp_f32_e32 v24, v24
	v_mov_b32_e32 v30, v25
	v_mov_b32_e32 v28, v73
	v_add_f32_e32 v24, 1.0, v24
	v_rcp_f32_e32 v31, v24
	s_nop 0
	v_pk_mul_f32 v[24:25], v[30:31], v[28:29]
	s_nop 0
	v_mul_f32_e32 v24, v24, v25
	v_lshlrev_b32_e32 v29, 16, v45
	v_cvt_pk_bf16_f32 v24, v2, v24
	v_mul_f32_e32 v2, 0xbfb8aa3b, v29
	v_exp_f32_e32 v2, v2
	v_mov_b32_e32 v30, v26
	v_mov_b32_e32 v28, v74
	v_add_f32_e32 v2, 1.0, v2
	v_rcp_f32_e32 v31, v2
	s_nop 0
	v_pk_mul_f32 v[28:29], v[30:31], v[28:29]
	s_nop 0
	v_mul_f32_e32 v2, v28, v29
	v_and_b32_e32 v29, 0xffff0000, v45
	v_mul_f32_e32 v25, 0xbfb8aa3b, v29
	v_exp_f32_e32 v25, v25
	v_mov_b32_e32 v30, v27
	v_mov_b32_e32 v28, v75
	v_add_f32_e32 v25, 1.0, v25
	v_rcp_f32_e32 v31, v25
	s_nop 0
	v_pk_mul_f32 v[26:27], v[30:31], v[28:29]
	s_nop 0
	v_mul_f32_e32 v25, v26, v27
	v_lshlrev_b32_e32 v27, 16, v46
	v_cvt_pk_bf16_f32 v25, v2, v25
	v_mul_f32_e32 v2, 0xbfb8aa3b, v27
	v_exp_f32_e32 v2, v2
	v_mov_b32_e32 v28, v20
	v_mov_b32_e32 v26, v68
	v_add_f32_e32 v2, 1.0, v2
	v_rcp_f32_e32 v29, v2
	s_nop 0
	v_pk_mul_f32 v[26:27], v[28:29], v[26:27]
	s_nop 0
	v_mul_f32_e32 v2, v26, v27
	v_and_b32_e32 v27, 0xffff0000, v46
	v_mul_f32_e32 v20, 0xbfb8aa3b, v27
	v_exp_f32_e32 v20, v20
	v_mov_b32_e32 v28, v21
	v_mov_b32_e32 v26, v69
	v_add_f32_e32 v20, 1.0, v20
	v_rcp_f32_e32 v29, v20
	s_nop 0
	v_pk_mul_f32 v[20:21], v[28:29], v[26:27]
	s_nop 0
	v_mul_f32_e32 v20, v20, v21
	v_lshlrev_b32_e32 v21, 16, v47
	v_cvt_pk_bf16_f32 v26, v2, v20
	v_mul_f32_e32 v2, 0xbfb8aa3b, v21
	v_exp_f32_e32 v2, v2
	v_mov_b32_e32 v28, v22
	v_mov_b32_e32 v20, v70
	v_mov_b32_e32 v22, v16
	v_add_f32_e32 v2, 1.0, v2
	v_rcp_f32_e32 v29, v2
	s_nop 0
	v_pk_mul_f32 v[20:21], v[28:29], v[20:21]
	s_nop 0
	v_mul_f32_e32 v2, v20, v21
	v_and_b32_e32 v21, 0xffff0000, v47
	v_mul_f32_e32 v20, 0xbfb8aa3b, v21
	v_exp_f32_e32 v20, v20
	v_mov_b32_e32 v28, v23
	v_add_f32_e32 v20, 1.0, v20
	v_rcp_f32_e32 v29, v20
	v_mov_b32_e32 v20, v71
	v_pk_mul_f32 v[20:21], v[28:29], v[20:21]
	s_nop 0
	v_mul_f32_e32 v20, v20, v21
	v_lshlrev_b32_e32 v21, 16, v40
	v_cvt_pk_bf16_f32 v27, v2, v20
	v_mul_f32_e32 v2, 0xbfb8aa3b, v21
	v_exp_f32_e32 v2, v2
	v_mov_b32_e32 v20, v72
	flat_store_dwordx4 v[98:99], v[24:27] offset:256
; __device__ __forceinline__ size_t pidx(size_t row, int col) { return ((size_t)(col >> 8) * MTOK + row) * PLD + (col & 255); }
; __device__ __forceinline__ float bflo(unsigned v) { return __uint_as_float(v << 16); }
; __device__ __forceinline__ float bfhi(unsigned v) { return __uint_as_float(v & 0xffff0000u); }
; __device__ __forceinline__ float siluf_(float x) { return x * __builtin_amdgcn_rcpf(1.0f + __expf(-x)); }
;   __device__ __forceinline__ void operator()(EPI_ARGS) const {
;     ...
;     for (int bj = 0; bj < 2; ++bj) {
;       const int c = col0 + bj * HALF;
;       const f32x4 s0 = *(const f32x4*)(psc + c), s1 = *(const f32x4*)(psc + c + 4);
; #pragma unroll
;       for (int ai = 0; ai < 2; ++ai) {
;         u32x4 z[4];
; #pragma unroll
;         for (int m = 0; m < 4; ++m) z[m] = *(const u32x4*)(proj + pidx(row0 + ai * HALF + m * 16, PZ + c));
;         __builtin_amdgcn_sched_barrier(0);
; #pragma unroll
;         for (int m = 0; m < 4; ++m) {
;           const size_t row = row0 + ai * HALF + m * 16;
;           const f32x4 v0 = acc[ai][bj][m][0], v1 = acc[ai][bj][m][1];
;           u32x4 o;
;           o.x = pack2(v0[0] * s0[0] * siluf_(bflo(z[m].x)), v0[1] * s0[1] * siluf_(bfhi(z[m].x)));
;           o.y = pack2(v0[2] * s0[2] * siluf_(bflo(z[m].y)), v0[3] * s0[3] * siluf_(bfhi(z[m].y)));
;           o.z = pack2(v1[0] * s1[0] * siluf_(bflo(z[m].z)), v1[1] * s1[1] * siluf_(bfhi(z[m].z)));
;           o.w = pack2(v1[2] * s1[2] * siluf_(bflo(z[m].w)), v1[3] * s1[3] * siluf_(bfhi(z[m].w)));
;           *(u32x4*)(y0 + row * DM + c) = o;
;         }
;       }
;     }
	v_add_f32_e32 v2, 1.0, v2
	v_rcp_f32_e32 v23, v2
	s_nop 0
	v_pk_mul_f32 v[20:21], v[22:23], v[20:21]
	s_nop 0
	v_mul_f32_e32 v2, v20, v21
	v_and_b32_e32 v21, 0xffff0000, v40
	v_mul_f32_e32 v16, 0xbfb8aa3b, v21
	v_exp_f32_e32 v16, v16
	v_mov_b32_e32 v22, v17
	v_mov_b32_e32 v20, v73
	v_add_f32_e32 v16, 1.0, v16
	v_rcp_f32_e32 v23, v16
	s_nop 0
	v_pk_mul_f32 v[16:17], v[22:23], v[20:21]
	s_nop 0
	v_mul_f32_e32 v16, v16, v17
	v_lshlrev_b32_e32 v21, 16, v41
	v_cvt_pk_bf16_f32 v16, v2, v16
	v_mul_f32_e32 v2, 0xbfb8aa3b, v21
	v_exp_f32_e32 v2, v2
	v_mov_b32_e32 v22, v18
	v_mov_b32_e32 v20, v74
	v_add_f32_e32 v2, 1.0, v2
	v_rcp_f32_e32 v23, v2
	s_nop 0
	v_pk_mul_f32 v[20:21], v[22:23], v[20:21]
	s_nop 0
	v_mul_f32_e32 v2, v20, v21
	v_and_b32_e32 v21, 0xffff0000, v41
	v_mul_f32_e32 v17, 0xbfb8aa3b, v21
	v_exp_f32_e32 v17, v17
	v_mov_b32_e32 v22, v19
	v_mov_b32_e32 v20, v75
	v_add_f32_e32 v17, 1.0, v17
	v_rcp_f32_e32 v23, v17
	s_nop 0
	v_pk_mul_f32 v[18:19], v[22:23], v[20:21]
	s_nop 0
	v_mul_f32_e32 v17, v18, v19
	v_lshlrev_b32_e32 v19, 16, v42
	v_cvt_pk_bf16_f32 v17, v2, v17
	v_mul_f32_e32 v2, 0xbfb8aa3b, v19
	v_exp_f32_e32 v2, v2
	v_mov_b32_e32 v20, v12
	v_mov_b32_e32 v18, v68
	v_add_f32_e32 v2, 1.0, v2
	v_rcp_f32_e32 v21, v2
	s_nop 0
	v_pk_mul_f32 v[18:19], v[20:21], v[18:19]
	s_nop 0
	v_mul_f32_e32 v2, v18, v19
	v_and_b32_e32 v19, 0xffff0000, v42
	v_mul_f32_e32 v12, 0xbfb8aa3b, v19
	v_exp_f32_e32 v12, v12
	v_mov_b32_e32 v20, v13
	v_mov_b32_e32 v18, v69
	v_add_f32_e32 v12, 1.0, v12
	v_rcp_f32_e32 v21, v12
	s_nop 0
	v_pk_mul_f32 v[12:13], v[20:21], v[18:19]
	s_nop 0
	v_mul_f32_e32 v12, v12, v13
	v_lshlrev_b32_e32 v13, 16, v43
	v_cvt_pk_bf16_f32 v18, v2, v12
	v_mul_f32_e32 v2, 0xbfb8aa3b, v13
	v_exp_f32_e32 v2, v2
	v_mov_b32_e32 v20, v14
	v_mov_b32_e32 v12, v70
	v_mov_b32_e32 v14, v8
	v_add_f32_e32 v2, 1.0, v2
	v_rcp_f32_e32 v21, v2
	s_nop 0
	v_pk_mul_f32 v[12:13], v[20:21], v[12:13]
	s_nop 0
	v_mul_f32_e32 v2, v12, v13
	v_and_b32_e32 v13, 0xffff0000, v43
	v_mul_f32_e32 v12, 0xbfb8aa3b, v13
	v_exp_f32_e32 v12, v12
	v_mov_b32_e32 v20, v15
	v_add_f32_e32 v12, 1.0, v12
	v_rcp_f32_e32 v21, v12
	v_mov_b32_e32 v12, v71
	v_pk_mul_f32 v[12:13], v[20:21], v[12:13]
	s_nop 0
	v_mul_f32_e32 v12, v12, v13
	v_lshlrev_b32_e32 v13, 16, v36
	v_cvt_pk_bf16_f32 v19, v2, v12
	v_mul_f32_e32 v2, 0xbfb8aa3b, v13
	v_exp_f32_e32 v2, v2
	v_mov_b32_e32 v12, v72
	flat_store_dwordx4 v[104:105], v[16:19] offset:256
	v_add_f32_e32 v2, 1.0, v2
	v_rcp_f32_e32 v15, v2
	s_nop 0
	v_pk_mul_f32 v[12:13], v[14:15], v[12:13]
	s_nop 0
	v_mul_f32_e32 v2, v12, v13
	v_and_b32_e32 v13, 0xffff0000, v36
	v_mul_f32_e32 v8, 0xbfb8aa3b, v13
	v_exp_f32_e32 v8, v8
	v_mov_b32_e32 v14, v9
	v_mov_b32_e32 v12, v73
	v_add_f32_e32 v8, 1.0, v8
	v_rcp_f32_e32 v15, v8
	s_nop 0
	v_pk_mul_f32 v[8:9], v[14:15], v[12:13]
	s_nop 0
	v_mul_f32_e32 v8, v8, v9
	v_lshlrev_b32_e32 v13, 16, v37
	v_cvt_pk_bf16_f32 v8, v2, v8
	v_mul_f32_e32 v2, 0xbfb8aa3b, v13
	v_exp_f32_e32 v2, v2
	v_mov_b32_e32 v14, v10
	v_mov_b32_e32 v12, v74
	v_add_f32_e32 v2, 1.0, v2
	v_rcp_f32_e32 v15, v2
	s_nop 0
	v_pk_mul_f32 v[12:13], v[14:15], v[12:13]
	s_nop 0
	v_mul_f32_e32 v2, v12, v13
	v_and_b32_e32 v13, 0xffff0000, v37
	v_mul_f32_e32 v9, 0xbfb8aa3b, v13
	v_exp_f32_e32 v9, v9
	v_mov_b32_e32 v14, v11
	v_mov_b32_e32 v12, v75
	v_add_f32_e32 v9, 1.0, v9
	v_rcp_f32_e32 v15, v9
	s_nop 0
	v_pk_mul_f32 v[10:11], v[14:15], v[12:13]
	s_nop 0
	v_mul_f32_e32 v9, v10, v11
	v_lshlrev_b32_e32 v11, 16, v38
	v_cvt_pk_bf16_f32 v9, v2, v9
	v_mul_f32_e32 v2, 0xbfb8aa3b, v11
	v_exp_f32_e32 v2, v2
	v_mov_b32_e32 v12, v4
	v_mov_b32_e32 v10, v68
	v_add_f32_e32 v2, 1.0, v2
	v_rcp_f32_e32 v13, v2
	s_nop 0
	v_pk_mul_f32 v[10:11], v[12:13], v[10:11]
	s_nop 0
	v_mul_f32_e32 v2, v10, v11
	v_and_b32_e32 v11, 0xffff0000, v38
	v_mul_f32_e32 v4, 0xbfb8aa3b, v11
	v_exp_f32_e32 v4, v4
	v_mov_b32_e32 v12, v5
	v_mov_b32_e32 v10, v69
	v_add_f32_e32 v4, 1.0, v4
	v_rcp_f32_e32 v13, v4
	s_nop 0
	v_pk_mul_f32 v[4:5], v[12:13], v[10:11]
	s_nop 0
	v_mul_f32_e32 v4, v4, v5
	v_lshlrev_b32_e32 v5, 16, v39
	v_cvt_pk_bf16_f32 v10, v2, v4
	v_mul_f32_e32 v2, 0xbfb8aa3b, v5
	v_exp_f32_e32 v2, v2
	v_mov_b32_e32 v12, v6
	v_mov_b32_e32 v4, v70
	v_add_f32_e32 v2, 1.0, v2
	v_rcp_f32_e32 v13, v2
	s_nop 0
	v_pk_mul_f32 v[4:5], v[12:13], v[4:5]
	s_nop 0
	v_mul_f32_e32 v2, v4, v5
	v_and_b32_e32 v5, 0xffff0000, v39
	v_mul_f32_e32 v4, 0xbfb8aa3b, v5
	v_exp_f32_e32 v4, v4
	v_mov_b32_e32 v12, v7
	v_add_f32_e32 v4, 1.0, v4
	v_rcp_f32_e32 v13, v4
	v_mov_b32_e32 v4, v71
	v_pk_mul_f32 v[4:5], v[12:13], v[4:5]
	s_nop 0
	v_mul_f32_e32 v4, v4, v5
	v_cvt_pk_bf16_f32 v11, v2, v4
	flat_store_dwordx4 v[92:93], v[8:11] offset:256
	s_cbranch_vccz .LBB0_482
	s_waitcnt vmcnt(0)
	v_readlane_b32 s44, v244, 59
	v_readlane_b32 s40, v243, 18
	s_cmpk_gt_u32 s24, 0xff
	s_mov_b32 s43, 0x800000
	v_readlane_b32 s45, v244, 60
	v_readlane_b32 s46, v244, 61
	v_readlane_b32 s47, v244, 62
	v_readlane_b32 s48, v244, 63
	v_readlane_b32 s49, v243, 0
	v_readlane_b32 s50, v243, 1
	v_readlane_b32 s51, v243, 2
	v_readlane_b32 s41, v243, 19
	s_cbranch_scc1 .LBB0_489
	s_barrier

; #define PG8_WAIT_V(n) asm volatile("s_waitcnt vmcnt(" #n ")" ::: "memory")
; #define PG8_WAIT_L(n) asm volatile("s_waitcnt lgkmcnt(" #n ")" ::: "memory")
; #define PG8_BAR __builtin_amdgcn_s_barrier()
; #define PG8_SCHED __builtin_amdgcn_sched_barrier(0)
; template <class Epi, class AddrA, class AddrB>
; __device__ __forceinline__ void gemm_phase(const Sched S, const int lda, const int ldb, const int K, const AddrA addrA,
;                                            const AddrB addrB, const Epi E) {
;     ...
;       PG8_LDB(B0, 0, 0); PG8_SCHED; PG8_LDA(At, 0, 0); PG8_STAGE(PG8_SA(1, 1), a1 + hstepA, voffA);
;       PG8_WAIT_L(8); PG8_BAR; PG8_WAIT_L(0); PG8_MMA(0, 0, At, B0); PG8_BAR; PG8_SCHED;
;       PG8_LDB(B1, 0, 1); PG8_STAGE(PG8_SB(0, 0), b2, voffB);
;       PG8_BAR; PG8_WAIT_L(0); PG8_MMA(0, 1, At, B1); PG8_BAR;
;       PG8_LDA(At, 0, 1); PG8_STAGE(PG8_SA(0, 0), a2, voffA);
;       PG8_BAR; PG8_WAIT_L(0); PG8_MMA(1, 0, At, B0); PG8_BAR; PG8_SCHED;
;       PG8_STAGE(PG8_SB(0, 1), b2 + hstepB, voffB);
;       PG8_WAIT_V(6); PG8_BAR; PG8_MMA(1, 1, At, B1); PG8_BAR;
;       PG8_LDB(B0, 1, 0); PG8_SCHED; PG8_LDA(At, 1, 0); PG8_STAGE(PG8_SA(0, 1), a2 + hstepA, voffA);
;       PG8_WAIT_L(8); PG8_BAR; PG8_WAIT_L(0); PG8_MMA(0, 0, At, B0); PG8_BAR; PG8_SCHED;
;       PG8_LDB(B1, 1, 1); PG8_STAGE(PG8_SB(1, 0), b3, voffB);
;       PG8_BAR; PG8_WAIT_L(0); PG8_MMA(0, 1, At, B1); PG8_BAR;
;       PG8_LDA(At, 1, 1); PG8_STAGE(PG8_SA(1, 0), a3, voffA);
;       PG8_BAR; PG8_WAIT_L(0); PG8_MMA(1, 0, At, B0); PG8_BAR; PG8_SCHED;
;       PG8_STAGE(PG8_SB(1, 1), b3 + hstepB, voffB);
;       PG8_WAIT_V(6); PG8_BAR; PG8_MMA(1, 1, At, B1); PG8_BAR;
.LBB0_543:
	s_add_u32 s4, s2, 0xfff80080
	s_addc_u32 s5, s3, -1
	s_add_i32 s43, 0, 0x10000
	v_add_u32_e32 v0, s43, v167
	ds_read_b128 v[132:135], v0
	ds_read_b128 v[136:139], v0 offset:1024
	ds_read_b128 v[140:143], v0 offset:2048
	ds_read_b128 v[144:147], v0 offset:3072
	s_cmp_eq_u32 s42, 28
	s_cselect_b32 s7, s1, s5
	s_cselect_b32 s6, s9, s4
	s_cselect_b32 s5, s13, s41
	s_cselect_b32 s4, s15, s33
	v_lshl_add_u64 v[0:1], s[2:3], 0, v[180:181]
	s_add_i32 m0, s28, 0xc000
	ds_read_b128 v[148:151], v188
	ds_read_b128 v[152:155], v188 offset:1024
	ds_read_b128 v[156:159], v188 offset:2048
	ds_read_b128 v[160:163], v188 offset:3072
	ds_read_b128 v[182:185], v188 offset:4096
	ds_read_b128 v[190:193], v188 offset:5120
	ds_read_b128 v[194:197], v188 offset:6144
	ds_read_b128 v[212:215], v188 offset:7168
	global_load_lds_dwordx4 v[0:1], off
	v_lshl_add_u64 v[0:1], s[2:3], 0, v[178:179]
	s_add_i32 m0, s28, 0xe000
	s_nop 0
	global_load_lds_dwordx4 v[0:1], off
	s_waitcnt lgkmcnt(8)
	s_setprio 1
	s_barrier
	s_waitcnt lgkmcnt(0)
	v_mfma_f32_16x16x32_bf16 v[128:131], v[132:135], v[148:151], v[128:131]
	v_mfma_f32_16x16x32_bf16 v[128:131], v[136:139], v[152:155], v[128:131]
	v_mfma_f32_16x16x32_bf16 v[120:123], v[132:135], v[156:159], v[120:123]
	v_mfma_f32_16x16x32_bf16 v[120:123], v[136:139], v[160:163], v[120:123]
	v_mfma_f32_16x16x32_bf16 v[112:115], v[132:135], v[182:185], v[112:115]
	v_mfma_f32_16x16x32_bf16 v[112:115], v[136:139], v[190:193], v[112:115]
	v_mfma_f32_16x16x32_bf16 v[104:107], v[132:135], v[194:197], v[104:107]
	v_mfma_f32_16x16x32_bf16 v[104:107], v[136:139], v[212:215], v[104:107]
	v_mfma_f32_16x16x32_bf16 v[124:127], v[140:143], v[148:151], v[124:127]
	v_mfma_f32_16x16x32_bf16 v[124:127], v[144:147], v[152:155], v[124:127]
	v_mfma_f32_16x16x32_bf16 v[116:119], v[140:143], v[156:159], v[116:119]
	v_mfma_f32_16x16x32_bf16 v[116:119], v[144:147], v[160:163], v[116:119]
	v_mfma_f32_16x16x32_bf16 v[108:111], v[140:143], v[182:185], v[108:111]
	v_mfma_f32_16x16x32_bf16 v[108:111], v[144:147], v[190:193], v[108:111]
	v_mfma_f32_16x16x32_bf16 v[100:103], v[140:143], v[194:197], v[100:103]
	v_mfma_f32_16x16x32_bf16 v[100:103], v[144:147], v[212:215], v[100:103]
	s_barrier
	s_setprio 0
	s_add_i32 s46, 0, 0x14000
	v_add_u32_e32 v0, s46, v167
	s_add_i32 s43, s43, s27
	ds_read_b128 v[216:219], v0
	ds_read_b128 v[220:223], v0 offset:1024
	ds_read_b128 v[224:227], v0 offset:2048
	ds_read_b128 v[228:231], v0 offset:3072
	v_lshl_add_u64 v[0:1], s[4:5], 0, v[172:173]
	s_mov_b32 m0, s43
	v_lshl_add_u64 v[232:233], s[4:5], 0, v[168:169]
	global_load_lds_dwordx4 v[0:1], off
	s_add_i32 m0, s43, 0x2000
	s_nop 0
	global_load_lds_dwordx4 v[232:233], off
	s_setprio 1
	s_barrier
	s_waitcnt lgkmcnt(0)
	v_mfma_f32_16x16x32_bf16 v[96:99], v[216:219], v[148:151], v[96:99]
	v_mfma_f32_16x16x32_bf16 v[96:99], v[220:223], v[152:155], v[96:99]
	v_mfma_f32_16x16x32_bf16 v[88:91], v[216:219], v[156:159], v[88:91]
	v_mfma_f32_16x16x32_bf16 v[88:91], v[220:223], v[160:163], v[88:91]
	v_mfma_f32_16x16x32_bf16 v[80:83], v[216:219], v[182:185], v[80:83]
	v_mfma_f32_16x16x32_bf16 v[80:83], v[220:223], v[190:193], v[80:83]
	v_mfma_f32_16x16x32_bf16 v[72:75], v[216:219], v[194:197], v[72:75]
	v_mfma_f32_16x16x32_bf16 v[72:75], v[220:223], v[212:215], v[72:75]
	v_mfma_f32_16x16x32_bf16 v[92:95], v[224:227], v[148:151], v[92:95]
	v_mfma_f32_16x16x32_bf16 v[92:95], v[228:231], v[152:155], v[92:95]
	v_mfma_f32_16x16x32_bf16 v[84:87], v[224:227], v[156:159], v[84:87]
	v_mfma_f32_16x16x32_bf16 v[84:87], v[228:231], v[160:163], v[84:87]
	v_mfma_f32_16x16x32_bf16 v[76:79], v[224:227], v[182:185], v[76:79]
	v_mfma_f32_16x16x32_bf16 v[76:79], v[228:231], v[190:193], v[76:79]
	v_mfma_f32_16x16x32_bf16 v[68:71], v[224:227], v[194:197], v[68:71]
	v_mfma_f32_16x16x32_bf16 v[68:71], v[228:231], v[212:215], v[68:71]
	s_barrier
	s_setprio 0
	s_mov_b32 m0, s28
	v_lshl_add_u64 v[234:235], s[6:7], 0, v[174:175]
	ds_read_b128 v[148:151], v188 offset:16384
	ds_read_b128 v[152:155], v188 offset:17408
	ds_read_b128 v[156:159], v188 offset:18432
	ds_read_b128 v[160:163], v188 offset:19456
	ds_read_b128 v[182:185], v188 offset:20480
	ds_read_b128 v[190:193], v188 offset:21504
	ds_read_b128 v[194:197], v188 offset:22528
	ds_read_b128 v[212:215], v188 offset:23552
	global_load_lds_dwordx4 v[234:235], off
	v_lshl_add_u64 v[236:237], s[6:7], 0, v[170:171]
	s_mov_b32 m0, s29
	s_nop 0
	global_load_lds_dwordx4 v[236:237], off
	s_setprio 1
	s_barrier
	s_waitcnt lgkmcnt(0)
	v_mfma_f32_16x16x32_bf16 v[64:67], v[132:135], v[148:151], v[64:67]
	v_mfma_f32_16x16x32_bf16 v[64:67], v[136:139], v[152:155], v[64:67]
	v_mfma_f32_16x16x32_bf16 v[56:59], v[132:135], v[156:159], v[56:59]
	v_mfma_f32_16x16x32_bf16 v[56:59], v[136:139], v[160:163], v[56:59]
	v_mfma_f32_16x16x32_bf16 v[48:51], v[132:135], v[182:185], v[48:51]
	v_mfma_f32_16x16x32_bf16 v[48:51], v[136:139], v[190:193], v[48:51]
	v_mfma_f32_16x16x32_bf16 v[40:43], v[132:135], v[194:197], v[40:43]
	v_mfma_f32_16x16x32_bf16 v[40:43], v[136:139], v[212:215], v[40:43]
	v_mfma_f32_16x16x32_bf16 v[60:63], v[140:143], v[148:151], v[60:63]
	v_mfma_f32_16x16x32_bf16 v[60:63], v[144:147], v[152:155], v[60:63]
	v_mfma_f32_16x16x32_bf16 v[52:55], v[140:143], v[156:159], v[52:55]
	v_mfma_f32_16x16x32_bf16 v[52:55], v[144:147], v[160:163], v[52:55]
	v_mfma_f32_16x16x32_bf16 v[44:47], v[140:143], v[182:185], v[44:47]
	v_mfma_f32_16x16x32_bf16 v[44:47], v[144:147], v[190:193], v[44:47]
	v_mfma_f32_16x16x32_bf16 v[36:39], v[140:143], v[194:197], v[36:39]
	v_mfma_f32_16x16x32_bf16 v[36:39], v[144:147], v[212:215], v[36:39]
	s_barrier
; #define PG8_WAIT_V(n) asm volatile("s_waitcnt vmcnt(" #n ")" ::: "memory")
; #define PG8_WAIT_L(n) asm volatile("s_waitcnt lgkmcnt(" #n ")" ::: "memory")
; #define PG8_BAR __builtin_amdgcn_s_barrier()
; #define PG8_SCHED __builtin_amdgcn_sched_barrier(0)
; template <class Epi, class AddrA, class AddrB>
; __device__ __forceinline__ void gemm_phase(const Sched S, const int lda, const int ldb, const int K, const AddrA addrA,
;                                            const AddrB addrB, const Epi E) {
;     ...
;       PG8_LDB(B0, 0, 0); PG8_SCHED; PG8_LDA(At, 0, 0); PG8_STAGE(PG8_SA(1, 1), a1 + hstepA, voffA);
;       PG8_WAIT_L(8); PG8_BAR; PG8_WAIT_L(0); PG8_MMA(0, 0, At, B0); PG8_BAR; PG8_SCHED;
;       PG8_LDB(B1, 0, 1); PG8_STAGE(PG8_SB(0, 0), b2, voffB);
;       PG8_BAR; PG8_WAIT_L(0); PG8_MMA(0, 1, At, B1); PG8_BAR;
;       PG8_LDA(At, 0, 1); PG8_STAGE(PG8_SA(0, 0), a2, voffA);
;       PG8_BAR; PG8_WAIT_L(0); PG8_MMA(1, 0, At, B0); PG8_BAR; PG8_SCHED;
;       PG8_STAGE(PG8_SB(0, 1), b2 + hstepB, voffB);
;       PG8_WAIT_V(6); PG8_BAR; PG8_MMA(1, 1, At, B1); PG8_BAR;
;       PG8_LDB(B0, 1, 0); PG8_SCHED; PG8_LDA(At, 1, 0); PG8_STAGE(PG8_SA(0, 1), a2 + hstepA, voffA);
;       PG8_WAIT_L(8); PG8_BAR; PG8_WAIT_L(0); PG8_MMA(0, 0, At, B0); PG8_BAR; PG8_SCHED;
;       PG8_LDB(B1, 1, 1); PG8_STAGE(PG8_SB(1, 0), b3, voffB);
;       PG8_BAR; PG8_WAIT_L(0); PG8_MMA(0, 1, At, B1); PG8_BAR;
;       PG8_LDA(At, 1, 1); PG8_STAGE(PG8_SA(1, 0), a3, voffA);
;       PG8_BAR; PG8_WAIT_L(0); PG8_MMA(1, 0, At, B0); PG8_BAR; PG8_SCHED;
;       PG8_STAGE(PG8_SB(1, 1), b3 + hstepB, voffB);
;       PG8_WAIT_V(6); PG8_BAR; PG8_MMA(1, 1, At, B1); PG8_BAR;
	s_setprio 0
	s_add_u32 s44, s4, 0x80000
	s_addc_u32 s45, s5, 0
	s_add_i32 s43, s46, s27
	v_lshl_add_u64 v[132:133], s[44:45], 0, v[172:173]
	s_mov_b32 m0, s43
	s_nop 0
	global_load_lds_dwordx4 v[132:133], off
	v_lshl_add_u64 v[132:133], s[44:45], 0, v[168:169]
	s_add_i32 m0, s43, 0x2000
	s_nop 0
	global_load_lds_dwordx4 v[132:133], off
	s_waitcnt vmcnt(6)
	s_setprio 1
	s_barrier
	v_mfma_f32_16x16x32_bf16 v[32:35], v[216:219], v[148:151], v[32:35]
	v_mfma_f32_16x16x32_bf16 v[32:35], v[220:223], v[152:155], v[32:35]
	v_mfma_f32_16x16x32_bf16 v[24:27], v[216:219], v[156:159], v[24:27]
	v_mfma_f32_16x16x32_bf16 v[24:27], v[220:223], v[160:163], v[24:27]
	v_mfma_f32_16x16x32_bf16 v[16:19], v[216:219], v[182:185], v[16:19]
	v_mfma_f32_16x16x32_bf16 v[16:19], v[220:223], v[190:193], v[16:19]
	v_mfma_f32_16x16x32_bf16 v[8:11], v[216:219], v[194:197], v[8:11]
	v_mfma_f32_16x16x32_bf16 v[8:11], v[220:223], v[212:215], v[8:11]
	v_mfma_f32_16x16x32_bf16 v[28:31], v[224:227], v[148:151], v[28:31]
	v_mfma_f32_16x16x32_bf16 v[28:31], v[228:231], v[152:155], v[28:31]
	v_mfma_f32_16x16x32_bf16 v[20:23], v[224:227], v[156:159], v[20:23]
	v_mfma_f32_16x16x32_bf16 v[20:23], v[228:231], v[160:163], v[20:23]
	v_mfma_f32_16x16x32_bf16 v[12:15], v[224:227], v[182:185], v[12:15]
	v_mfma_f32_16x16x32_bf16 v[12:15], v[228:231], v[190:193], v[12:15]
	v_mfma_f32_16x16x32_bf16 v[4:7], v[224:227], v[194:197], v[4:7]
	v_mfma_f32_16x16x32_bf16 v[4:7], v[228:231], v[212:215], v[4:7]
	s_barrier
	s_setprio 0
	s_add_i32 s43, 0, 0x18000
	v_add_u32_e32 v2, s43, v167
	ds_read_b128 v[132:135], v2
	ds_read_b128 v[136:139], v2 offset:1024
	ds_read_b128 v[140:143], v2 offset:2048
	ds_read_b128 v[144:147], v2 offset:3072
	s_add_u32 s6, s6, 0x80000
	s_addc_u32 s7, s7, 0
	s_mov_b32 m0, s30
	v_lshl_add_u64 v[216:217], s[6:7], 0, v[174:175]
	ds_read_b128 v[148:151], v188 offset:32768
	ds_read_b128 v[152:155], v188 offset:33792
	ds_read_b128 v[156:159], v188 offset:34816
	ds_read_b128 v[160:163], v188 offset:35840
	ds_read_b128 v[182:185], v188 offset:36864
	ds_read_b128 v[190:193], v188 offset:37888
	ds_read_b128 v[194:197], v188 offset:38912
	ds_read_b128 v[212:215], v188 offset:39936
	global_load_lds_dwordx4 v[216:217], off
	v_lshl_add_u64 v[216:217], s[6:7], 0, v[170:171]
	s_mov_b32 m0, s31
	s_nop 0
	global_load_lds_dwordx4 v[216:217], off
	s_waitcnt lgkmcnt(8)
	s_setprio 1
	s_barrier
	s_waitcnt lgkmcnt(0)
	v_mfma_f32_16x16x32_bf16 v[128:131], v[132:135], v[148:151], v[128:131]
	v_mfma_f32_16x16x32_bf16 v[128:131], v[136:139], v[152:155], v[128:131]
	v_mfma_f32_16x16x32_bf16 v[120:123], v[132:135], v[156:159], v[120:123]
	v_mfma_f32_16x16x32_bf16 v[120:123], v[136:139], v[160:163], v[120:123]
	v_mfma_f32_16x16x32_bf16 v[112:115], v[132:135], v[182:185], v[112:115]
	v_mfma_f32_16x16x32_bf16 v[112:115], v[136:139], v[190:193], v[112:115]
	v_mfma_f32_16x16x32_bf16 v[104:107], v[132:135], v[194:197], v[104:107]
	v_mfma_f32_16x16x32_bf16 v[104:107], v[136:139], v[212:215], v[104:107]
	v_mfma_f32_16x16x32_bf16 v[124:127], v[140:143], v[148:151], v[124:127]
	v_mfma_f32_16x16x32_bf16 v[124:127], v[144:147], v[152:155], v[124:127]
	v_mfma_f32_16x16x32_bf16 v[116:119], v[140:143], v[156:159], v[116:119]
	v_mfma_f32_16x16x32_bf16 v[116:119], v[144:147], v[160:163], v[116:119]
	v_mfma_f32_16x16x32_bf16 v[108:111], v[140:143], v[182:185], v[108:111]
	v_mfma_f32_16x16x32_bf16 v[108:111], v[144:147], v[190:193], v[108:111]
	v_mfma_f32_16x16x32_bf16 v[100:103], v[140:143], v[194:197], v[100:103]
	v_mfma_f32_16x16x32_bf16 v[100:103], v[144:147], v[212:215], v[100:103]
	s_barrier
	s_setprio 0
	s_add_i32 s6, 0, 0x1c000
	s_add_i32 s7, s43, s27
	v_add_u32_e32 v2, s6, v167
	v_lshl_add_u64 v[0:1], v[0:1], 0, s[52:53]
	s_mov_b32 m0, s7
	ds_read_b128 v[216:219], v2
	ds_read_b128 v[220:223], v2 offset:1024
	ds_read_b128 v[224:227], v2 offset:2048
	ds_read_b128 v[228:231], v2 offset:3072
	global_load_lds_dwordx4 v[0:1], off
	v_lshl_add_u64 v[0:1], v[232:233], 0, s[52:53]
	s_add_i32 m0, s7, 0x2000
	s_nop 0
	global_load_lds_dwordx4 v[0:1], off
	s_setprio 1
	s_barrier
	s_waitcnt lgkmcnt(0)
	v_mfma_f32_16x16x32_bf16 v[96:99], v[216:219], v[148:151], v[96:99]
	v_mfma_f32_16x16x32_bf16 v[96:99], v[220:223], v[152:155], v[96:99]
	v_mfma_f32_16x16x32_bf16 v[88:91], v[216:219], v[156:159], v[88:91]
	v_mfma_f32_16x16x32_bf16 v[88:91], v[220:223], v[160:163], v[88:91]
	v_mfma_f32_16x16x32_bf16 v[80:83], v[216:219], v[182:185], v[80:83]
	v_mfma_f32_16x16x32_bf16 v[80:83], v[220:223], v[190:193], v[80:83]
	v_mfma_f32_16x16x32_bf16 v[72:75], v[216:219], v[194:197], v[72:75]
	v_mfma_f32_16x16x32_bf16 v[72:75], v[220:223], v[212:215], v[72:75]
	v_mfma_f32_16x16x32_bf16 v[92:95], v[224:227], v[148:151], v[92:95]
	v_mfma_f32_16x16x32_bf16 v[92:95], v[228:231], v[152:155], v[92:95]
	v_mfma_f32_16x16x32_bf16 v[84:87], v[224:227], v[156:159], v[84:87]
	v_mfma_f32_16x16x32_bf16 v[84:87], v[228:231], v[160:163], v[84:87]
	v_mfma_f32_16x16x32_bf16 v[76:79], v[224:227], v[182:185], v[76:79]
	v_mfma_f32_16x16x32_bf16 v[76:79], v[228:231], v[190:193], v[76:79]
	v_mfma_f32_16x16x32_bf16 v[68:71], v[224:227], v[194:197], v[68:71]
	v_mfma_f32_16x16x32_bf16 v[68:71], v[228:231], v[212:215], v[68:71]
	s_barrier
	s_setprio 0
	s_mov_b32 m0, s38
	v_lshl_add_u64 v[0:1], v[234:235], 0, s[52:53]
	ds_read_b128 v[148:151], v188 offset:49152
	ds_read_b128 v[152:155], v188 offset:50176
	ds_read_b128 v[156:159], v188 offset:51200
	ds_read_b128 v[160:163], v188 offset:52224
	ds_read_b128 v[182:185], v188 offset:53248
	ds_read_b128 v[190:193], v188 offset:54272
	ds_read_b128 v[194:197], v188 offset:55296
	ds_read_b128 v[212:215], v188 offset:56320
	global_load_lds_dwordx4 v[0:1], off
	v_lshl_add_u64 v[0:1], v[236:237], 0, s[52:53]
	s_mov_b32 m0, s39
	s_nop 0
	global_load_lds_dwordx4 v[0:1], off
	s_setprio 1
	s_barrier
; #define PG8_WAIT_V(n) asm volatile("s_waitcnt vmcnt(" #n ")" ::: "memory")
; #define PG8_WAIT_L(n) asm volatile("s_waitcnt lgkmcnt(" #n ")" ::: "memory")
; #define PG8_BAR __builtin_amdgcn_s_barrier()
; #define PG8_SCHED __builtin_amdgcn_sched_barrier(0)
; template <class Epi, class AddrA, class AddrB>
; __device__ __forceinline__ void gemm_phase(const Sched S, const int lda, const int ldb, const int K, const AddrA addrA,
;                                            const AddrB addrB, const Epi E) {
;     ...
;       PG8_BAR; PG8_WAIT_L(0); PG8_MMA(1, 0, At, B0); PG8_BAR; PG8_SCHED;
;       PG8_STAGE(PG8_SB(1, 1), b3 + hstepB, voffB);
;       PG8_WAIT_V(6); PG8_BAR; PG8_MMA(1, 1, At, B1); PG8_BAR;
;   __device__ __forceinline__ void operator()(EPI_ARGS) const {
;     const int col0 = u.pn * 256 + wc * 32 + 8 * fq;
;     const int br = u.br, brn = br < 2 ? br + 1 : 2;
;     const unsigned loff0 = (unsigned)((wr * 64 + fr) * PLD + wc * 32 + 8 * fq);
;     const bf16_t* pc = proj + ((size_t)((GT + br * DM) / 256 + u.pn) * MTOK + (size_t)u.pm * 256) * PLD;
;     const bf16_t* pn_ = proj + ((size_t)((GT + brn * DM) / 256 + u.pn) * MTOK + (size_t)u.pm * 256) * PLD;
;     bf16_t* mrow = merged + ((size_t)u.pm * 256 + wr * 64 + fr) * DM + col0;
; #pragma unroll
;     for (int bj = 0; bj < 2; ++bj) {
;       const int c = col0 + bj * HALF;
;       float gc[8], gn[8];
;       {
;         const f32x4 a0 = *(const f32x4*)(bg + br * DM + c), a1 = *(const f32x4*)(bg + br * DM + c + 4);
;         const f32x4 b0 = *(const f32x4*)(bg + brn * DM + c), b1 = *(const f32x4*)(bg + brn * DM + c + 4);
; #pragma unroll
;         for (int k = 0; k < 4; ++k) { gc[k] = a0[k]; gc[4 + k] = a1[k]; gn[k] = b0[k]; gn[4 + k] = b1[k]; }
;       }
; #pragma unroll
;       for (int ai = 0; ai < 2; ++ai) {
;         unsigned loff = loff0;
;         asm volatile("" : "+v"(loff));
;         u32x4 zc[4], zn[4];
; #pragma unroll
;         for (int m = 0; m < 4; ++m) {
;           const unsigned o = loff + (unsigned)((ai * HALF + m * 16) * PLD + bj * HALF);
;           zc[m] = *(const u32x4*)(pc + o);
;           zn[m] = *(const u32x4*)(pn_ + o);
;         }
;         __builtin_amdgcn_sched_barrier(0);
	s_waitcnt lgkmcnt(0)
	v_mfma_f32_16x16x32_bf16 v[64:67], v[132:135], v[148:151], v[64:67]
	v_mfma_f32_16x16x32_bf16 v[64:67], v[136:139], v[152:155], v[64:67]
	v_mfma_f32_16x16x32_bf16 v[56:59], v[132:135], v[156:159], v[56:59]
	v_mfma_f32_16x16x32_bf16 v[56:59], v[136:139], v[160:163], v[56:59]
	v_mfma_f32_16x16x32_bf16 v[48:51], v[132:135], v[182:185], v[48:51]
	v_mfma_f32_16x16x32_bf16 v[48:51], v[136:139], v[190:193], v[48:51]
	v_mfma_f32_16x16x32_bf16 v[40:43], v[132:135], v[194:197], v[40:43]
	v_mfma_f32_16x16x32_bf16 v[40:43], v[136:139], v[212:215], v[40:43]
	v_mfma_f32_16x16x32_bf16 v[60:63], v[140:143], v[148:151], v[60:63]
	v_mfma_f32_16x16x32_bf16 v[60:63], v[144:147], v[152:155], v[60:63]
	v_mfma_f32_16x16x32_bf16 v[52:55], v[140:143], v[156:159], v[52:55]
	v_mfma_f32_16x16x32_bf16 v[52:55], v[144:147], v[160:163], v[52:55]
	v_mfma_f32_16x16x32_bf16 v[44:47], v[140:143], v[182:185], v[44:47]
	v_mfma_f32_16x16x32_bf16 v[44:47], v[144:147], v[190:193], v[44:47]
	v_mfma_f32_16x16x32_bf16 v[36:39], v[140:143], v[194:197], v[36:39]
	v_mfma_f32_16x16x32_bf16 v[36:39], v[144:147], v[212:215], v[36:39]
	s_barrier
	s_setprio 0
	s_add_u32 s4, s4, 0x80080
	s_addc_u32 s5, s5, 0
	s_add_i32 s6, s6, s27
	v_lshl_add_u64 v[0:1], s[4:5], 0, v[172:173]
	s_mov_b32 m0, s6
	s_nop 0
	global_load_lds_dwordx4 v[0:1], off
	v_lshl_add_u64 v[0:1], s[4:5], 0, v[168:169]
	s_add_i32 m0, s6, 0x2000
	s_nop 0
	global_load_lds_dwordx4 v[0:1], off
	s_waitcnt vmcnt(6)
	s_setprio 1
	s_barrier
	v_mfma_f32_16x16x32_bf16 v[32:35], v[216:219], v[148:151], v[32:35]
	v_mfma_f32_16x16x32_bf16 v[32:35], v[220:223], v[152:155], v[32:35]
	v_mfma_f32_16x16x32_bf16 v[24:27], v[216:219], v[156:159], v[24:27]
	v_mfma_f32_16x16x32_bf16 v[24:27], v[220:223], v[160:163], v[24:27]
	v_mfma_f32_16x16x32_bf16 v[16:19], v[216:219], v[182:185], v[16:19]
	v_mfma_f32_16x16x32_bf16 v[16:19], v[220:223], v[190:193], v[16:19]
	v_mfma_f32_16x16x32_bf16 v[8:11], v[216:219], v[194:197], v[8:11]
	v_mfma_f32_16x16x32_bf16 v[8:11], v[220:223], v[212:215], v[8:11]
	v_mfma_f32_16x16x32_bf16 v[28:31], v[224:227], v[148:151], v[28:31]
	v_mfma_f32_16x16x32_bf16 v[28:31], v[228:231], v[152:155], v[28:31]
	v_mfma_f32_16x16x32_bf16 v[20:23], v[224:227], v[156:159], v[20:23]
	v_mfma_f32_16x16x32_bf16 v[20:23], v[228:231], v[160:163], v[20:23]
	v_mfma_f32_16x16x32_bf16 v[12:15], v[224:227], v[182:185], v[12:15]
	v_mfma_f32_16x16x32_bf16 v[12:15], v[228:231], v[190:193], v[12:15]
	v_mfma_f32_16x16x32_bf16 v[4:7], v[224:227], v[194:197], v[4:7]
	v_mfma_f32_16x16x32_bf16 v[4:7], v[228:231], v[212:215], v[4:7]
	s_barrier
	s_setprio 0
	s_add_i32 s42, s42, 2
	s_add_u32 s33, s33, 0x100
	s_addc_u32 s41, s41, 0
	s_add_u32 s2, s2, 0x100
	s_addc_u32 s3, s3, 0
	s_cmp_gt_u32 s42, 29
	s_cbranch_scc0 .LBB0_543
	s_cmp_gt_i32 s10, 1
	s_cselect_b64 s[6:7], -1, 0
	s_lshl_b32 s42, s10, 11
	s_add_i32 s2, s42, 0x4c00
	s_ashr_i32 s2, s2, 8
	s_add_i32 s2, s2, s11
	s_ashr_i32 s3, s2, 31
	s_min_i32 s1, s10, 1
	s_ashr_i32 s9, s8, 31
	s_lshl_b64 s[2:3], s[2:3], 23
	s_add_u32 s2, s34, s2
	s_addc_u32 s3, s35, s3
	s_lshl_b64 s[4:5], s[8:9], 17
	s_add_u32 s2, s2, s4
	s_addc_u32 s3, s3, s5
	s_lshl_b32 s1, s1, 11
	s_add_i32 s44, s1, 0x800
	s_addk_i32 s1, 0x5400
	s_ashr_i32 s1, s1, 8
	s_add_i32 s46, s1, s11
	s_ashr_i32 s47, s46, 31
	s_lshl_b64 s[46:47], s[46:47], 23
	s_add_u32 s1, s34, s46
	v_lshl_or_b32 v132, s11, 8, v187
	s_addc_u32 s11, s35, s47
	s_add_u32 s4, s1, s4
	s_addc_u32 s5, s11, s5
	s_ashr_i32 s43, s42, 31
	s_lshl_b64 s[8:9], s[8:9], 20
	s_ashr_i32 s45, s44, 31
	s_lshl_b64 s[42:43], s[42:43], 2
	s_add_u32 s42, s36, s42
	s_addc_u32 s43, s37, s43
	s_lshl_b64 s[44:45], s[44:45], 2
	s_add_u32 s44, s36, s44
	v_lshl_add_u64 v[0:1], v[176:177], 0, s[8:9]
	v_ashrrev_i32_e32 v133, 31, v132
	s_addc_u32 s45, s37, s45
	v_lshl_add_u64 v[0:1], v[132:133], 1, v[0:1]
	v_lshlrev_b64 v[132:133], 2, v[132:133]
	v_lshl_add_u64 v[182:183], s[42:43], 0, v[132:133]
	v_lshl_add_u64 v[184:185], s[44:45], 0, v[132:133]
	v_mov_b32_e32 v2, v186
	global_load_dwordx4 v[144:147], v[182:183], off
	global_load_dwordx4 v[136:139], v[182:183], off offset:16
	global_load_dwordx4 v[140:143], v[184:185], off
	global_load_dwordx4 v[132:135], v[184:185], off offset:16
	s_cmp_lt_i32 s10, 2
	v_lshlrev_b64 v[148:149], 1, v[2:3]
	v_lshl_add_u64 v[150:151], s[2:3], 0, v[148:149]
	v_lshl_add_u64 v[148:149], s[4:5], 0, v[148:149]
	flat_load_dwordx4 v[190:193], v[150:151]
	flat_load_dwordx4 v[160:163], v[148:149]
	v_add_u32_e32 v148, 0x1000, v2
	v_mov_b32_e32 v149, v3
	v_lshlrev_b64 v[148:149], 1, v[148:149]
	v_lshl_add_u64 v[150:151], s[2:3], 0, v[148:149]
	v_lshl_add_u64 v[148:149], s[4:5], 0, v[148:149]
	flat_load_dwordx4 v[194:197], v[150:151]
	flat_load_dwordx4 v[156:159], v[148:149]
	v_add_u32_e32 v148, 0x2000, v2
	v_mov_b32_e32 v149, v3
	v_lshlrev_b64 v[148:149], 1, v[148:149]
	v_lshl_add_u64 v[150:151], s[2:3], 0, v[148:149]
	v_lshl_add_u64 v[148:149], s[4:5], 0, v[148:149]
	v_add_u32_e32 v2, 0x3000, v2
	flat_load_dwordx4 v[234:237], v[150:151]
	flat_load_dwordx4 v[152:155], v[148:149]
	v_lshlrev_b64 v[148:149], 1, v[2:3]
	v_lshl_add_u64 v[150:151], s[2:3], 0, v[148:149]
	v_lshl_add_u64 v[148:149], s[4:5], 0, v[148:149]
	flat_load_dwordx4 v[238:241], v[150:151]
	s_nop 0
	flat_load_dwordx4 v[148:151], v[148:149]
	s_waitcnt vmcnt(0) lgkmcnt(0)
; __device__ __forceinline__ float sigmoidf_(float x) { return __builtin_amdgcn_rcpf(1.0f + __expf(-x)); }
;   __device__ __forceinline__ void operator()(EPI_ARGS) const {
;     ...
;         u32x4 zc[4], zn[4];
; #pragma unroll
;         for (int m = 0; m < 4; ++m) {
;           const unsigned o = loff + (unsigned)((ai * HALF + m * 16) * PLD + bj * HALF);
;           zc[m] = *(const u32x4*)(pc + o);
;           zn[m] = *(const u32x4*)(pn_ + o);
;         }
;         __builtin_amdgcn_sched_barrier(0);
;         if (br < 2) {
; #pragma unroll
;           for (int m = 0; m < 4; ++m) {
;             float xc[8], xn[8];
;             unpack8(zc[m], xc);
;             unpack8(zn[m], xn);
; #pragma unroll
;             for (int k = 0; k < 8; ++k) {
;               const float ec = __expf(-fmaxf(xc[k] + gc[k], -40.f)), en = __expf(-fmaxf(xn[k] + gn[k], -40.f));
;               const float f = (1.0f + en) * __builtin_amdgcn_rcpf(1.0f + ec);
;               acc[ai][bj][m][k >> 2][k & 3] *= f;
;             }
;           }
;         } else {
; #pragma unroll
;           for (int m = 0; m < 4; ++m) {
;             float xc[8], y[8];
;             unpack8(zc[m], xc);
; #pragma unroll
;             for (int k = 0; k < 8; ++k) y[k] = acc[ai][bj][m][k >> 2][k & 3] * sigmoidf_(fmaxf(xc[k] + gc[k], -40.f));
;             u32x4 o;
;             o.x = pack2(y[0], y[1]); o.y = pack2(y[2], y[3]); o.z = pack2(y[4], y[5]); o.w = pack2(y[6], y[7]);
;             *(u32x4*)(mrow + (size_t)(ai * HALF + m * 16) * DM + bj * HALF) = o;
;           }
	v_lshlrev_b32_e32 v2, 16, v190
	v_and_b32_e32 v189, 0xffff0000, v190
	v_lshlrev_b32_e32 v190, 16, v191
	v_and_b32_e32 v191, 0xffff0000, v191
	v_lshlrev_b32_e32 v212, 16, v192
	v_and_b32_e32 v192, 0xffff0000, v192
	v_lshlrev_b32_e32 v213, 16, v193
	v_and_b32_e32 v193, 0xffff0000, v193
	v_add_f32_e32 v2, v144, v2
	v_add_f32_e32 v189, v145, v189
	v_add_f32_e32 v190, v146, v190
	v_add_f32_e32 v191, v147, v191
	v_add_f32_e32 v212, v136, v212
	v_add_f32_e32 v192, v137, v192
	v_add_f32_e32 v213, v138, v213
	v_add_f32_e32 v193, v139, v193
	s_mov_b64 s[8:9], -1
	v_max_f32_e32 v233, 0xc2200000, v2
	v_max_f32_e32 v232, 0xc2200000, v189
	v_max_f32_e32 v231, 0xc2200000, v190
	v_max_f32_e32 v230, 0xc2200000, v191
	v_max_f32_e32 v229, 0xc2200000, v212
	v_max_f32_e32 v228, 0xc2200000, v192
	v_max_f32_e32 v227, 0xc2200000, v213
	v_max_f32_e32 v226, 0xc2200000, v193
	v_lshlrev_b32_e32 v225, 16, v194
	v_and_b32_e32 v224, 0xffff0000, v194
	v_lshlrev_b32_e32 v223, 16, v195
	v_and_b32_e32 v222, 0xffff0000, v195
	v_lshlrev_b32_e32 v221, 16, v196
	v_and_b32_e32 v220, 0xffff0000, v196
	v_lshlrev_b32_e32 v219, 16, v197
	v_and_b32_e32 v218, 0xffff0000, v197
	v_lshlrev_b32_e32 v217, 16, v234
	v_and_b32_e32 v216, 0xffff0000, v234
	v_lshlrev_b32_e32 v215, 16, v235
	v_and_b32_e32 v214, 0xffff0000, v235
	v_lshlrev_b32_e32 v213, 16, v236
	v_and_b32_e32 v212, 0xffff0000, v236
	v_lshlrev_b32_e32 v197, 16, v237
	v_and_b32_e32 v196, 0xffff0000, v237
	v_lshlrev_b32_e32 v195, 16, v238
	v_and_b32_e32 v194, 0xffff0000, v238
	v_lshlrev_b32_e32 v193, 16, v239
	v_and_b32_e32 v192, 0xffff0000, v239
	v_lshlrev_b32_e32 v191, 16, v240
	v_and_b32_e32 v190, 0xffff0000, v240
	v_lshlrev_b32_e32 v189, 16, v241
	v_and_b32_e32 v2, 0xffff0000, v241
	s_cbranch_scc1 .LBB0_546
	v_mul_f32_e32 v234, 0xbfb8aa3b, v233
	v_mul_f32_e32 v235, 0xbfb8aa3b, v232
	v_mul_f32_e32 v236, 0xbfb8aa3b, v231
	v_exp_f32_e32 v234, v234
	v_exp_f32_e32 v235, v235
	v_exp_f32_e32 v236, v236
	v_mul_f32_e32 v237, 0xbfb8aa3b, v230
	v_exp_f32_e32 v237, v237
	v_mul_f32_e32 v238, 0xbfb8aa3b, v229
	v_mul_f32_e32 v239, 0xbfb8aa3b, v228
	v_add_f32_e32 v234, 1.0, v234
	v_add_f32_e32 v235, 1.0, v235
	v_add_f32_e32 v236, 1.0, v236
	v_exp_f32_e32 v238, v238
	v_exp_f32_e32 v239, v239
	v_mul_f32_e32 v240, 0xbfb8aa3b, v227
	v_mul_f32_e32 v241, 0xbfb8aa3b, v226
	v_rcp_f32_e32 v234, v234
	v_rcp_f32_e32 v235, v235
	v_rcp_f32_e32 v236, v236
	v_add_f32_e32 v237, 1.0, v237
	v_exp_f32_e32 v240, v240
	v_exp_f32_e32 v241, v241
	v_rcp_f32_e32 v237, v237
	v_add_f32_e32 v238, 1.0, v238
	v_add_f32_e32 v239, 1.0, v239
	v_mul_f32_e32 v234, v128, v234
	v_mul_f32_e32 v235, v129, v235
	v_mul_f32_e32 v236, v130, v236
	v_rcp_f32_e32 v238, v238
	v_rcp_f32_e32 v239, v239
	v_add_f32_e32 v240, 1.0, v240
	v_add_f32_e32 v241, 1.0, v241
	v_mul_f32_e32 v237, v131, v237
	v_rcp_f32_e32 v240, v240
	v_rcp_f32_e32 v241, v241
	v_cvt_pk_bf16_f32 v234, v234, v235
	v_cvt_pk_bf16_f32 v235, v236, v237
	v_add_f32_e32 v236, v144, v225
	v_max_f32_e32 v236, 0xc2200000, v236
	v_mul_f32_e32 v236, 0xbfb8aa3b, v236
	v_mul_f32_e32 v238, v124, v238
	v_mul_f32_e32 v239, v125, v239
	v_exp_f32_e32 v242, v236
	v_cvt_pk_bf16_f32 v236, v238, v239
	v_mul_f32_e32 v240, v126, v240
	v_mul_f32_e32 v241, v127, v241
	v_cvt_pk_bf16_f32 v237, v240, v241
	flat_store_dwordx4 v[0:1], v[234:237]
	v_add_f32_e32 v238, v136, v221
	v_max_f32_e32 v238, 0xc2200000, v238
	v_add_f32_e32 v235, v145, v224
	v_add_f32_e32 v236, v146, v223
	v_max_f32_e32 v235, 0xc2200000, v235
	v_max_f32_e32 v236, 0xc2200000, v236
	v_add_f32_e32 v237, v147, v222
	v_add_f32_e32 v239, v137, v220
	v_mul_f32_e32 v235, 0xbfb8aa3b, v235
	v_mul_f32_e32 v236, 0xbfb8aa3b, v236
	v_max_f32_e32 v237, 0xc2200000, v237
	v_mul_f32_e32 v238, 0xbfb8aa3b, v238
	v_max_f32_e32 v239, 0xc2200000, v239
	v_exp_f32_e32 v235, v235
	v_exp_f32_e32 v236, v236
	v_mul_f32_e32 v237, 0xbfb8aa3b, v237
	v_exp_f32_e32 v238, v238
	v_mul_f32_e32 v239, 0xbfb8aa3b, v239
	v_add_f32_e32 v240, v138, v219
	v_exp_f32_e32 v237, v237
	v_exp_f32_e32 v239, v239
	v_max_f32_e32 v240, 0xc2200000, v240
	v_add_f32_e32 v241, v139, v218
	v_mul_f32_e32 v240, 0xbfb8aa3b, v240
	v_max_f32_e32 v241, 0xc2200000, v241
	v_exp_f32_e32 v240, v240
	v_mul_f32_e32 v241, 0xbfb8aa3b, v241
	v_add_f32_e32 v234, 1.0, v242
	v_add_f32_e32 v235, 1.0, v235
	v_add_f32_e32 v236, 1.0, v236
	v_add_f32_e32 v238, 1.0, v238
	v_exp_f32_e32 v241, v241
	v_rcp_f32_e32 v234, v234
	v_rcp_f32_e32 v235, v235
	v_rcp_f32_e32 v236, v236
	v_add_f32_e32 v237, 1.0, v237
	v_rcp_f32_e32 v238, v238
	v_add_f32_e32 v239, 1.0, v239
	v_rcp_f32_e32 v237, v237
	v_rcp_f32_e32 v239, v239
	v_add_f32_e32 v240, 1.0, v240
	v_rcp_f32_e32 v240, v240
	v_add_f32_e32 v241, 1.0, v241
	v_mul_f32_e32 v234, v120, v234
; __device__ __forceinline__ float sigmoidf_(float x) { return __builtin_amdgcn_rcpf(1.0f + __expf(-x)); }
;   __device__ __forceinline__ void operator()(EPI_ARGS) const {
;     ...
;           for (int m = 0; m < 4; ++m) {
;             float xc[8], y[8];
;             unpack8(zc[m], xc);
; #pragma unroll
;             for (int k = 0; k < 8; ++k) y[k] = acc[ai][bj][m][k >> 2][k & 3] * sigmoidf_(fmaxf(xc[k] + gc[k], -40.f));
;             u32x4 o;
;             o.x = pack2(y[0], y[1]); o.y = pack2(y[2], y[3]); o.z = pack2(y[4], y[5]); o.w = pack2(y[6], y[7]);
;             *(u32x4*)(mrow + (size_t)(ai * HALF + m * 16) * DM + bj * HALF) = o;
;           }
	v_mul_f32_e32 v235, v121, v235
	v_mul_f32_e32 v236, v122, v236
	v_rcp_f32_e32 v241, v241
	v_mul_f32_e32 v238, v116, v238
	v_mul_f32_e32 v237, v123, v237
	v_mul_f32_e32 v239, v117, v239
	v_cvt_pk_bf16_f32 v234, v234, v235
	v_cvt_pk_bf16_f32 v235, v236, v237
	v_cvt_pk_bf16_f32 v236, v238, v239
	v_add_f32_e32 v238, v144, v217
	v_max_f32_e32 v238, 0xc2200000, v238
	v_mul_f32_e32 v240, v118, v240
	v_mul_f32_e32 v238, 0xbfb8aa3b, v238
	v_mul_f32_e32 v241, v119, v241
	v_cvt_pk_bf16_f32 v237, v240, v241
	v_exp_f32_e32 v240, v238
	v_add_co_u32_e32 v238, vcc, s67, v0
	v_add_f32_e32 v241, v139, v196
	s_nop 0
	v_addc_co_u32_e32 v239, vcc, 0, v1, vcc
	flat_store_dwordx4 v[238:239], v[234:237]
	v_add_f32_e32 v238, v136, v213
	v_max_f32_e32 v238, 0xc2200000, v238
	v_add_f32_e32 v235, v145, v216
	v_add_f32_e32 v236, v146, v215
	v_max_f32_e32 v235, 0xc2200000, v235
	v_max_f32_e32 v236, 0xc2200000, v236
	v_add_f32_e32 v237, v147, v214
	v_add_f32_e32 v239, v137, v212
	v_mul_f32_e32 v235, 0xbfb8aa3b, v235
	v_mul_f32_e32 v236, 0xbfb8aa3b, v236
	v_max_f32_e32 v237, 0xc2200000, v237
	v_mul_f32_e32 v238, 0xbfb8aa3b, v238
	v_max_f32_e32 v239, 0xc2200000, v239
	v_add_f32_e32 v234, 1.0, v240
	v_exp_f32_e32 v235, v235
	v_exp_f32_e32 v236, v236
	v_mul_f32_e32 v237, 0xbfb8aa3b, v237
	v_exp_f32_e32 v238, v238
	v_mul_f32_e32 v239, 0xbfb8aa3b, v239
	v_add_f32_e32 v240, v138, v197
	v_exp_f32_e32 v237, v237
	v_exp_f32_e32 v239, v239
	v_max_f32_e32 v240, 0xc2200000, v240
	v_mul_f32_e32 v240, 0xbfb8aa3b, v240
	v_max_f32_e32 v241, 0xc2200000, v241
	v_exp_f32_e32 v240, v240
	v_mul_f32_e32 v241, 0xbfb8aa3b, v241
	v_add_f32_e32 v235, 1.0, v235
	v_add_f32_e32 v236, 1.0, v236
	v_add_f32_e32 v238, 1.0, v238
	v_exp_f32_e32 v241, v241
	v_rcp_f32_e32 v234, v234
	v_rcp_f32_e32 v235, v235
	v_rcp_f32_e32 v236, v236
	v_add_f32_e32 v237, 1.0, v237
	v_rcp_f32_e32 v238, v238
	v_add_f32_e32 v239, 1.0, v239
	v_rcp_f32_e32 v237, v237
	v_rcp_f32_e32 v239, v239
	v_add_f32_e32 v240, 1.0, v240
	v_rcp_f32_e32 v240, v240
	v_add_f32_e32 v241, 1.0, v241
	v_mul_f32_e32 v234, v112, v234
	v_mul_f32_e32 v235, v113, v235
	v_mul_f32_e32 v236, v114, v236
	v_rcp_f32_e32 v241, v241
	v_mul_f32_e32 v238, v108, v238
	v_mul_f32_e32 v237, v115, v237
	v_mul_f32_e32 v239, v109, v239
	v_cvt_pk_bf16_f32 v234, v234, v235
	v_cvt_pk_bf16_f32 v235, v236, v237
	v_cvt_pk_bf16_f32 v236, v238, v239
	v_add_f32_e32 v238, v144, v195
	v_max_f32_e32 v238, 0xc2200000, v238
	v_mul_f32_e32 v240, v110, v240
	v_mul_f32_e32 v238, 0xbfb8aa3b, v238
	s_mov_b32 s1, 0x20000
	v_mul_f32_e32 v241, v111, v241
	v_cvt_pk_bf16_f32 v237, v240, v241
	v_exp_f32_e32 v240, v238
	v_add_co_u32_e32 v238, vcc, s1, v0
	v_add_f32_e32 v241, v139, v2
	s_nop 0
	v_addc_co_u32_e32 v239, vcc, 0, v1, vcc
	flat_store_dwordx4 v[238:239], v[234:237]
	v_add_f32_e32 v238, v136, v191
	v_max_f32_e32 v238, 0xc2200000, v238
	v_add_f32_e32 v235, v145, v194
	v_add_f32_e32 v236, v146, v193
	v_max_f32_e32 v235, 0xc2200000, v235
	v_max_f32_e32 v236, 0xc2200000, v236
	v_add_f32_e32 v237, v147, v192
	v_add_f32_e32 v239, v137, v190
	v_mul_f32_e32 v235, 0xbfb8aa3b, v235
	v_mul_f32_e32 v236, 0xbfb8aa3b, v236
	v_max_f32_e32 v237, 0xc2200000, v237
	v_mul_f32_e32 v238, 0xbfb8aa3b, v238
	v_max_f32_e32 v239, 0xc2200000, v239
	v_add_f32_e32 v234, 1.0, v240
	v_exp_f32_e32 v235, v235
	v_exp_f32_e32 v236, v236
	v_mul_f32_e32 v237, 0xbfb8aa3b, v237
	v_exp_f32_e32 v238, v238
	v_mul_f32_e32 v239, 0xbfb8aa3b, v239
	v_add_f32_e32 v240, v138, v189
	v_exp_f32_e32 v237, v237
	v_exp_f32_e32 v239, v239
	v_max_f32_e32 v240, 0xc2200000, v240
	v_max_f32_e32 v241, 0xc2200000, v241
	v_mul_f32_e32 v240, 0xbfb8aa3b, v240
	v_mul_f32_e32 v241, 0xbfb8aa3b, v241
	v_exp_f32_e32 v240, v240
	v_exp_f32_e32 v241, v241
	v_add_f32_e32 v235, 1.0, v235
	v_add_f32_e32 v236, 1.0, v236
	v_add_f32_e32 v238, 1.0, v238
	v_rcp_f32_e32 v234, v234
	v_rcp_f32_e32 v235, v235
	v_rcp_f32_e32 v236, v236
	v_add_f32_e32 v237, 1.0, v237
	v_rcp_f32_e32 v238, v238
	v_add_f32_e32 v239, 1.0, v239
	v_rcp_f32_e32 v237, v237
	v_rcp_f32_e32 v239, v239
	v_add_f32_e32 v240, 1.0, v240
	v_add_f32_e32 v241, 1.0, v241
	v_rcp_f32_e32 v240, v240
	v_rcp_f32_e32 v241, v241
	v_mul_f32_e32 v234, v104, v234
	v_mul_f32_e32 v235, v105, v235
	v_mul_f32_e32 v236, v106, v236
	v_mul_f32_e32 v238, v100, v238
	v_mul_f32_e32 v237, v107, v237
	v_mul_f32_e32 v239, v101, v239
	v_cvt_pk_bf16_f32 v234, v234, v235
	v_cvt_pk_bf16_f32 v235, v236, v237
	v_cvt_pk_bf16_f32 v236, v238, v239
	v_add_co_u32_e32 v238, vcc, 0x30000, v0
	s_mov_b64 s[8:9], 0
	s_nop 0
	v_addc_co_u32_e32 v239, vcc, 0, v1, vcc
	v_mul_f32_e32 v240, v102, v240
	v_mul_f32_e32 v241, v103, v241
	v_cvt_pk_bf16_f32 v237, v240, v241
	flat_store_dwordx4 v[238:239], v[234:237]

; #define PG8_WAIT_V(n) asm volatile("s_waitcnt vmcnt(" #n ")" ::: "memory")
; #define PG8_WAIT_L(n) asm volatile("s_waitcnt lgkmcnt(" #n ")" ::: "memory")
; #define PG8_BAR __builtin_amdgcn_s_barrier()
; #define PG8_SCHED __builtin_amdgcn_sched_barrier(0)
; template <class Epi, class AddrA, class AddrB>
; __device__ __forceinline__ void gemm_phase(const Sched S, const int lda, const int ldb, const int K, const AddrA addrA,
;                                            const AddrB addrB, const Epi E) {
;     ...
;   for (;;) {
;     const bool has_next = S.next(ui + 1, nxt);
;     const char* nA = has_next ? addrA(nxt) : cA;
;     const char* nB = has_next ? addrB(nxt) : cB;
;     for (int t = 0; t < nt; t += 2) {
;       const bool last = (t == nt - 2);
;       const char* a1 = cA + (size_t)(t + 1) * kstep;
;       const char* a2 = last ? nA : cA + (size_t)(t + 2) * kstep;
;       const char* b2 = last ? nB : cB + (size_t)(t + 2) * kstep;
;       const char* a3 = a2 + kstep;
;       const char* b3 = b2 + kstep;
;       PG8_LDB(B0, 0, 0); PG8_SCHED; PG8_LDA(At, 0, 0); PG8_STAGE(PG8_SA(1, 1), a1 + hstepA, voffA);
;       PG8_WAIT_L(8); PG8_BAR; PG8_WAIT_L(0); PG8_MMA(0, 0, At, B0); PG8_BAR; PG8_SCHED;
;       PG8_LDB(B1, 0, 1); PG8_STAGE(PG8_SB(0, 0), b2, voffB);
;       PG8_BAR; PG8_WAIT_L(0); PG8_MMA(0, 1, At, B1); PG8_BAR;
;       PG8_LDA(At, 0, 1); PG8_STAGE(PG8_SA(0, 0), a2, voffA);
;       PG8_BAR; PG8_WAIT_L(0); PG8_MMA(1, 0, At, B0); PG8_BAR; PG8_SCHED;
;       PG8_STAGE(PG8_SB(0, 1), b2 + hstepB, voffB);
;       PG8_WAIT_V(6); PG8_BAR; PG8_MMA(1, 1, At, B1); PG8_BAR;
.LBB0_618:
	s_ashr_i32 s3, s2, 31
	s_lshl_b64 s[8:9], s[2:3], 20
	s_add_u32 s8, s23, s8
	s_addc_u32 s9, s24, s9
	s_and_b64 s[10:11], s[18:19], exec
	s_cselect_b32 s3, s9, s17
	s_cselect_b32 s13, s8, s16
	s_ashr_i32 s5, s4, 31
	s_lshl_b64 s[10:11], s[4:5], 20
	s_add_u32 s10, s21, s10
	s_addc_u32 s11, s22, s11
	s_and_b64 s[18:19], s[18:19], exec
	s_cselect_b32 s5, s11, s15
	s_cselect_b32 s35, s10, s14
	s_add_u32 s36, s14, 0x100
	s_addc_u32 s37, s15, 0
	s_add_u32 s14, s16, 0x80080
	s_addc_u32 s15, s17, 0
	s_mov_b32 s38, -2
	s_add_u32 s16, s14, 0xfff80080
	s_addc_u32 s17, s15, -1
	s_add_i32 s39, 0, 0x10000
	v_add_u32_e32 v142, s39, v144
	ds_read_b128 v[148:151], v142
	ds_read_b128 v[152:155], v142 offset:1024
	ds_read_b128 v[156:159], v142 offset:2048
	ds_read_b128 v[160:163], v142 offset:3072
	s_cmp_eq_u32 s38, 28
	s_cselect_b32 s19, s3, s17
	s_cselect_b32 s18, s13, s16
	s_cselect_b32 s17, s5, s37
	s_cselect_b32 s16, s35, s36
	v_lshl_add_u64 v[142:143], s[14:15], 0, v[140:141]
	s_add_i32 m0, s26, 0xc000
	ds_read_b128 v[168:171], v146
	ds_read_b128 v[172:175], v146 offset:1024
	ds_read_b128 v[176:179], v146 offset:2048
	ds_read_b128 v[180:183], v146 offset:3072
	ds_read_b128 v[184:187], v146 offset:4096
	ds_read_b128 v[188:191], v146 offset:5120
	ds_read_b128 v[192:195], v146 offset:6144
	ds_read_b128 v[212:215], v146 offset:7168
	global_load_lds_dwordx4 v[142:143], off
	v_lshl_add_u64 v[142:143], s[14:15], 0, v[138:139]
	s_add_i32 m0, s26, 0xe000
	s_nop 0
	global_load_lds_dwordx4 v[142:143], off
	s_waitcnt lgkmcnt(8)
	s_setprio 1
	s_barrier
	s_waitcnt lgkmcnt(0)
	v_mfma_f32_16x16x32_bf16 v[128:131], v[148:151], v[168:171], 0
	v_mfma_f32_16x16x32_bf16 v[128:131], v[152:155], v[172:175], v[128:131]
	v_mfma_f32_16x16x32_bf16 v[120:123], v[148:151], v[176:179], 0
	v_mfma_f32_16x16x32_bf16 v[120:123], v[152:155], v[180:183], v[120:123]
	v_mfma_f32_16x16x32_bf16 v[112:115], v[148:151], v[184:187], 0
	v_mfma_f32_16x16x32_bf16 v[112:115], v[152:155], v[188:191], v[112:115]
	v_mfma_f32_16x16x32_bf16 v[104:107], v[148:151], v[192:195], 0
	v_mfma_f32_16x16x32_bf16 v[104:107], v[152:155], v[212:215], v[104:107]
	v_mfma_f32_16x16x32_bf16 v[124:127], v[156:159], v[168:171], 0
	v_mfma_f32_16x16x32_bf16 v[124:127], v[160:163], v[172:175], v[124:127]
	v_mfma_f32_16x16x32_bf16 v[116:119], v[156:159], v[176:179], 0
	v_mfma_f32_16x16x32_bf16 v[116:119], v[160:163], v[180:183], v[116:119]
	v_mfma_f32_16x16x32_bf16 v[108:111], v[156:159], v[184:187], 0
	v_mfma_f32_16x16x32_bf16 v[108:111], v[160:163], v[188:191], v[108:111]
	v_mfma_f32_16x16x32_bf16 v[100:103], v[156:159], v[192:195], 0
	v_mfma_f32_16x16x32_bf16 v[100:103], v[160:163], v[212:215], v[100:103]
	s_barrier
	s_setprio 0
	s_add_i32 s42, 0, 0x14000
	v_add_u32_e32 v142, s42, v144
	s_add_i32 s39, s39, s25
	ds_read_b128 v[216:219], v142
	ds_read_b128 v[220:223], v142 offset:1024
	ds_read_b128 v[224:227], v142 offset:2048
	ds_read_b128 v[228:231], v142 offset:3072
	v_lshl_add_u64 v[142:143], s[16:17], 0, v[2:3]
	s_mov_b32 m0, s39
	v_lshl_add_u64 v[196:197], s[16:17], 0, v[0:1]
	global_load_lds_dwordx4 v[142:143], off
	s_add_i32 m0, s39, 0x2000
	s_nop 0
	global_load_lds_dwordx4 v[196:197], off
	s_setprio 1
	s_barrier
	s_waitcnt lgkmcnt(0)
	v_mfma_f32_16x16x32_bf16 v[96:99], v[216:219], v[168:171], 0
	v_mfma_f32_16x16x32_bf16 v[96:99], v[220:223], v[172:175], v[96:99]
	v_mfma_f32_16x16x32_bf16 v[88:91], v[216:219], v[176:179], 0
	v_mfma_f32_16x16x32_bf16 v[88:91], v[220:223], v[180:183], v[88:91]
	v_mfma_f32_16x16x32_bf16 v[80:83], v[216:219], v[184:187], 0
	v_mfma_f32_16x16x32_bf16 v[80:83], v[220:223], v[188:191], v[80:83]
	v_mfma_f32_16x16x32_bf16 v[72:75], v[216:219], v[192:195], 0
	v_mfma_f32_16x16x32_bf16 v[72:75], v[220:223], v[212:215], v[72:75]
	v_mfma_f32_16x16x32_bf16 v[92:95], v[224:227], v[168:171], 0
	v_mfma_f32_16x16x32_bf16 v[92:95], v[228:231], v[172:175], v[92:95]
	v_mfma_f32_16x16x32_bf16 v[84:87], v[224:227], v[176:179], 0
	v_mfma_f32_16x16x32_bf16 v[84:87], v[228:231], v[180:183], v[84:87]
	v_mfma_f32_16x16x32_bf16 v[76:79], v[224:227], v[184:187], 0
	v_mfma_f32_16x16x32_bf16 v[76:79], v[228:231], v[188:191], v[76:79]
	v_mfma_f32_16x16x32_bf16 v[68:71], v[224:227], v[192:195], 0
	v_mfma_f32_16x16x32_bf16 v[68:71], v[228:231], v[212:215], v[68:71]
	s_barrier
	s_setprio 0
	s_mov_b32 m0, s26
	v_lshl_add_u64 v[232:233], s[18:19], 0, v[134:135]
	ds_read_b128 v[168:171], v146 offset:16384
	ds_read_b128 v[172:175], v146 offset:17408
	ds_read_b128 v[176:179], v146 offset:18432
	ds_read_b128 v[180:183], v146 offset:19456
	ds_read_b128 v[184:187], v146 offset:20480
	ds_read_b128 v[188:191], v146 offset:21504
	ds_read_b128 v[192:195], v146 offset:22528
	ds_read_b128 v[212:215], v146 offset:23552
	global_load_lds_dwordx4 v[232:233], off
	v_lshl_add_u64 v[234:235], s[18:19], 0, v[132:133]
	s_mov_b32 m0, s27
	s_nop 0
	global_load_lds_dwordx4 v[234:235], off
	s_setprio 1
	s_barrier
	s_waitcnt lgkmcnt(0)
	v_mfma_f32_16x16x32_bf16 v[64:67], v[148:151], v[168:171], 0
	v_mfma_f32_16x16x32_bf16 v[64:67], v[152:155], v[172:175], v[64:67]
	v_mfma_f32_16x16x32_bf16 v[56:59], v[148:151], v[176:179], 0
	v_mfma_f32_16x16x32_bf16 v[56:59], v[152:155], v[180:183], v[56:59]
	v_mfma_f32_16x16x32_bf16 v[48:51], v[148:151], v[184:187], 0
	v_mfma_f32_16x16x32_bf16 v[48:51], v[152:155], v[188:191], v[48:51]
	v_mfma_f32_16x16x32_bf16 v[40:43], v[148:151], v[192:195], 0
	v_mfma_f32_16x16x32_bf16 v[40:43], v[152:155], v[212:215], v[40:43]
	v_mfma_f32_16x16x32_bf16 v[60:63], v[156:159], v[168:171], 0
	v_mfma_f32_16x16x32_bf16 v[60:63], v[160:163], v[172:175], v[60:63]
	v_mfma_f32_16x16x32_bf16 v[52:55], v[156:159], v[176:179], 0
	v_mfma_f32_16x16x32_bf16 v[52:55], v[160:163], v[180:183], v[52:55]
	v_mfma_f32_16x16x32_bf16 v[44:47], v[156:159], v[184:187], 0
	v_mfma_f32_16x16x32_bf16 v[44:47], v[160:163], v[188:191], v[44:47]
	v_mfma_f32_16x16x32_bf16 v[36:39], v[156:159], v[192:195], 0
	v_mfma_f32_16x16x32_bf16 v[36:39], v[160:163], v[212:215], v[36:39]
	s_barrier
; #define PG8_WAIT_V(n) asm volatile("s_waitcnt vmcnt(" #n ")" ::: "memory")
; #define PG8_WAIT_L(n) asm volatile("s_waitcnt lgkmcnt(" #n ")" ::: "memory")
; #define PG8_BAR __builtin_amdgcn_s_barrier()
; #define PG8_SCHED __builtin_amdgcn_sched_barrier(0)
; template <class Epi, class AddrA, class AddrB>
; __device__ __forceinline__ void gemm_phase(const Sched S, const int lda, const int ldb, const int K, const AddrA addrA,
;                                            const AddrB addrB, const Epi E) {
;     ...
;       PG8_BAR; PG8_WAIT_L(0); PG8_MMA(1, 0, At, B0); PG8_BAR; PG8_SCHED;
;       PG8_STAGE(PG8_SB(0, 1), b2 + hstepB, voffB);
;       PG8_WAIT_V(6); PG8_BAR; PG8_MMA(1, 1, At, B1); PG8_BAR;
;       PG8_LDB(B0, 1, 0); PG8_SCHED; PG8_LDA(At, 1, 0); PG8_STAGE(PG8_SA(0, 1), a2 + hstepA, voffA);
;       PG8_WAIT_L(8); PG8_BAR; PG8_WAIT_L(0); PG8_MMA(0, 0, At, B0); PG8_BAR; PG8_SCHED;
;       PG8_LDB(B1, 1, 1); PG8_STAGE(PG8_SB(1, 0), b3, voffB);
;       PG8_BAR; PG8_WAIT_L(0); PG8_MMA(0, 1, At, B1); PG8_BAR;
;       PG8_LDA(At, 1, 1); PG8_STAGE(PG8_SA(1, 0), a3, voffA);
;       PG8_BAR; PG8_WAIT_L(0); PG8_MMA(1, 0, At, B0); PG8_BAR; PG8_SCHED;
	s_setprio 0
	s_add_u32 s40, s16, 0x80000
	s_addc_u32 s41, s17, 0
	s_add_i32 s39, s42, s25
	v_lshl_add_u64 v[148:149], s[40:41], 0, v[2:3]
	s_mov_b32 m0, s39
	s_nop 0
	global_load_lds_dwordx4 v[148:149], off
	v_lshl_add_u64 v[148:149], s[40:41], 0, v[0:1]
	s_add_i32 m0, s39, 0x2000
	s_nop 0
	global_load_lds_dwordx4 v[148:149], off
	s_waitcnt vmcnt(6)
	s_setprio 1
	s_barrier
	v_mfma_f32_16x16x32_bf16 v[32:35], v[216:219], v[168:171], 0
	v_mfma_f32_16x16x32_bf16 v[32:35], v[220:223], v[172:175], v[32:35]
	v_mfma_f32_16x16x32_bf16 v[24:27], v[216:219], v[176:179], 0
	v_mfma_f32_16x16x32_bf16 v[24:27], v[220:223], v[180:183], v[24:27]
	v_mfma_f32_16x16x32_bf16 v[16:19], v[216:219], v[184:187], 0
	v_mfma_f32_16x16x32_bf16 v[16:19], v[220:223], v[188:191], v[16:19]
	v_mfma_f32_16x16x32_bf16 v[8:11], v[216:219], v[192:195], 0
	v_mfma_f32_16x16x32_bf16 v[8:11], v[220:223], v[212:215], v[8:11]
	v_mfma_f32_16x16x32_bf16 v[28:31], v[224:227], v[168:171], 0
	v_mfma_f32_16x16x32_bf16 v[28:31], v[228:231], v[172:175], v[28:31]
	v_mfma_f32_16x16x32_bf16 v[20:23], v[224:227], v[176:179], 0
	v_mfma_f32_16x16x32_bf16 v[20:23], v[228:231], v[180:183], v[20:23]
	v_mfma_f32_16x16x32_bf16 v[12:15], v[224:227], v[184:187], 0
	v_mfma_f32_16x16x32_bf16 v[12:15], v[228:231], v[188:191], v[12:15]
	v_mfma_f32_16x16x32_bf16 v[4:7], v[224:227], v[192:195], 0
	v_mfma_f32_16x16x32_bf16 v[4:7], v[228:231], v[212:215], v[4:7]
	s_barrier
	s_setprio 0
	s_add_i32 s39, 0, 0x18000
	v_add_u32_e32 v147, s39, v144
	ds_read_b128 v[148:151], v147
	ds_read_b128 v[152:155], v147 offset:1024
	ds_read_b128 v[156:159], v147 offset:2048
	ds_read_b128 v[160:163], v147 offset:3072
	s_add_u32 s18, s18, 0x80000
	s_addc_u32 s19, s19, 0
	s_mov_b32 m0, s28
	v_lshl_add_u64 v[216:217], s[18:19], 0, v[134:135]
	ds_read_b128 v[168:171], v146 offset:32768
	ds_read_b128 v[172:175], v146 offset:33792
	ds_read_b128 v[176:179], v146 offset:34816
	ds_read_b128 v[180:183], v146 offset:35840
	ds_read_b128 v[184:187], v146 offset:36864
	ds_read_b128 v[188:191], v146 offset:37888
	ds_read_b128 v[192:195], v146 offset:38912
	ds_read_b128 v[212:215], v146 offset:39936
	global_load_lds_dwordx4 v[216:217], off
	v_lshl_add_u64 v[216:217], s[18:19], 0, v[132:133]
	s_mov_b32 m0, s29
	s_nop 0
	global_load_lds_dwordx4 v[216:217], off
	s_waitcnt lgkmcnt(8)
	s_setprio 1
	s_barrier
	s_waitcnt lgkmcnt(0)
	v_mfma_f32_16x16x32_bf16 v[128:131], v[148:151], v[168:171], v[128:131]
	v_mfma_f32_16x16x32_bf16 v[128:131], v[152:155], v[172:175], v[128:131]
	v_mfma_f32_16x16x32_bf16 v[120:123], v[148:151], v[176:179], v[120:123]
	v_mfma_f32_16x16x32_bf16 v[120:123], v[152:155], v[180:183], v[120:123]
	v_mfma_f32_16x16x32_bf16 v[112:115], v[148:151], v[184:187], v[112:115]
	v_mfma_f32_16x16x32_bf16 v[112:115], v[152:155], v[188:191], v[112:115]
	v_mfma_f32_16x16x32_bf16 v[104:107], v[148:151], v[192:195], v[104:107]
	v_mfma_f32_16x16x32_bf16 v[104:107], v[152:155], v[212:215], v[104:107]
	v_mfma_f32_16x16x32_bf16 v[124:127], v[156:159], v[168:171], v[124:127]
	v_mfma_f32_16x16x32_bf16 v[124:127], v[160:163], v[172:175], v[124:127]
	v_mfma_f32_16x16x32_bf16 v[116:119], v[156:159], v[176:179], v[116:119]
	v_mfma_f32_16x16x32_bf16 v[116:119], v[160:163], v[180:183], v[116:119]
	v_mfma_f32_16x16x32_bf16 v[108:111], v[156:159], v[184:187], v[108:111]
	v_mfma_f32_16x16x32_bf16 v[108:111], v[160:163], v[188:191], v[108:111]
	v_mfma_f32_16x16x32_bf16 v[100:103], v[156:159], v[192:195], v[100:103]
	v_mfma_f32_16x16x32_bf16 v[100:103], v[160:163], v[212:215], v[100:103]
	s_barrier
	s_setprio 0
	s_add_i32 s18, 0, 0x1c000
	s_add_i32 s19, s39, s25
	v_add_u32_e32 v147, s18, v144
	v_lshl_add_u64 v[142:143], v[142:143], 0, s[52:53]
	s_mov_b32 m0, s19
	ds_read_b128 v[216:219], v147
	ds_read_b128 v[220:223], v147 offset:1024
	ds_read_b128 v[224:227], v147 offset:2048
	ds_read_b128 v[228:231], v147 offset:3072
	global_load_lds_dwordx4 v[142:143], off
	v_lshl_add_u64 v[142:143], v[196:197], 0, s[52:53]
	s_add_i32 m0, s19, 0x2000
	s_nop 0
	global_load_lds_dwordx4 v[142:143], off
	s_setprio 1
	s_barrier
	s_waitcnt lgkmcnt(0)
	v_mfma_f32_16x16x32_bf16 v[96:99], v[216:219], v[168:171], v[96:99]
	v_mfma_f32_16x16x32_bf16 v[96:99], v[220:223], v[172:175], v[96:99]
	v_mfma_f32_16x16x32_bf16 v[88:91], v[216:219], v[176:179], v[88:91]
	v_mfma_f32_16x16x32_bf16 v[88:91], v[220:223], v[180:183], v[88:91]
	v_mfma_f32_16x16x32_bf16 v[80:83], v[216:219], v[184:187], v[80:83]
	v_mfma_f32_16x16x32_bf16 v[80:83], v[220:223], v[188:191], v[80:83]
	v_mfma_f32_16x16x32_bf16 v[72:75], v[216:219], v[192:195], v[72:75]
	v_mfma_f32_16x16x32_bf16 v[72:75], v[220:223], v[212:215], v[72:75]
	v_mfma_f32_16x16x32_bf16 v[92:95], v[224:227], v[168:171], v[92:95]
	v_mfma_f32_16x16x32_bf16 v[92:95], v[228:231], v[172:175], v[92:95]
	v_mfma_f32_16x16x32_bf16 v[84:87], v[224:227], v[176:179], v[84:87]
	v_mfma_f32_16x16x32_bf16 v[84:87], v[228:231], v[180:183], v[84:87]
	v_mfma_f32_16x16x32_bf16 v[76:79], v[224:227], v[184:187], v[76:79]
	v_mfma_f32_16x16x32_bf16 v[76:79], v[228:231], v[188:191], v[76:79]
	v_mfma_f32_16x16x32_bf16 v[68:71], v[224:227], v[192:195], v[68:71]
	v_mfma_f32_16x16x32_bf16 v[68:71], v[228:231], v[212:215], v[68:71]
	s_barrier
	s_setprio 0
	s_mov_b32 m0, s30
	v_lshl_add_u64 v[142:143], v[232:233], 0, s[52:53]
	ds_read_b128 v[168:171], v146 offset:49152
	ds_read_b128 v[172:175], v146 offset:50176
	ds_read_b128 v[176:179], v146 offset:51200
	ds_read_b128 v[180:183], v146 offset:52224
	ds_read_b128 v[184:187], v146 offset:53248
	ds_read_b128 v[188:191], v146 offset:54272
	ds_read_b128 v[192:195], v146 offset:55296
	ds_read_b128 v[212:215], v146 offset:56320
	global_load_lds_dwordx4 v[142:143], off
	v_lshl_add_u64 v[142:143], v[234:235], 0, s[52:53]
	s_mov_b32 m0, s31
	s_nop 0
	global_load_lds_dwordx4 v[142:143], off
	s_setprio 1
	s_barrier
; #define PG8_WAIT_V(n) asm volatile("s_waitcnt vmcnt(" #n ")" ::: "memory")
; #define PG8_WAIT_L(n) asm volatile("s_waitcnt lgkmcnt(" #n ")" ::: "memory")
; #define PG8_BAR __builtin_amdgcn_s_barrier()
; #define PG8_SCHED __builtin_amdgcn_sched_barrier(0)
; template <class Epi, class AddrA, class AddrB>
; __device__ __forceinline__ void gemm_phase(const Sched S, const int lda, const int ldb, const int K, const AddrA addrA,
;                                            const AddrB addrB, const Epi E) {
;     ...
;       PG8_LDB(B0, 0, 0); PG8_SCHED; PG8_LDA(At, 0, 0); PG8_STAGE(PG8_SA(1, 1), a1 + hstepA, voffA);
;       PG8_WAIT_L(8); PG8_BAR; PG8_WAIT_L(0); PG8_MMA(0, 0, At, B0); PG8_BAR; PG8_SCHED;
;       PG8_LDB(B1, 0, 1); PG8_STAGE(PG8_SB(0, 0), b2, voffB);
;       PG8_BAR; PG8_WAIT_L(0); PG8_MMA(0, 1, At, B1); PG8_BAR;
;       PG8_LDA(At, 0, 1); PG8_STAGE(PG8_SA(0, 0), a2, voffA);
;       PG8_BAR; PG8_WAIT_L(0); PG8_MMA(1, 0, At, B0); PG8_BAR; PG8_SCHED;
;       PG8_STAGE(PG8_SB(0, 1), b2 + hstepB, voffB);
;       PG8_WAIT_V(6); PG8_BAR; PG8_MMA(1, 1, At, B1); PG8_BAR;
;       PG8_LDB(B0, 1, 0); PG8_SCHED; PG8_LDA(At, 1, 0); PG8_STAGE(PG8_SA(0, 1), a2 + hstepA, voffA);
;       PG8_WAIT_L(8); PG8_BAR; PG8_WAIT_L(0); PG8_MMA(0, 0, At, B0); PG8_BAR; PG8_SCHED;
;       PG8_LDB(B1, 1, 1); PG8_STAGE(PG8_SB(1, 0), b3, voffB);
;       PG8_BAR; PG8_WAIT_L(0); PG8_MMA(0, 1, At, B1); PG8_BAR;
;       PG8_LDA(At, 1, 1); PG8_STAGE(PG8_SA(1, 0), a3, voffA);
;       PG8_BAR; PG8_WAIT_L(0); PG8_MMA(1, 0, At, B0); PG8_BAR; PG8_SCHED;
;       PG8_STAGE(PG8_SB(1, 1), b3 + hstepB, voffB);
;       PG8_WAIT_V(6); PG8_BAR; PG8_MMA(1, 1, At, B1); PG8_BAR;
;     }
	s_waitcnt lgkmcnt(0)
	v_mfma_f32_16x16x32_bf16 v[64:67], v[148:151], v[168:171], v[64:67]
	v_mfma_f32_16x16x32_bf16 v[64:67], v[152:155], v[172:175], v[64:67]
	v_mfma_f32_16x16x32_bf16 v[56:59], v[148:151], v[176:179], v[56:59]
	v_mfma_f32_16x16x32_bf16 v[56:59], v[152:155], v[180:183], v[56:59]
	v_mfma_f32_16x16x32_bf16 v[48:51], v[148:151], v[184:187], v[48:51]
	v_mfma_f32_16x16x32_bf16 v[48:51], v[152:155], v[188:191], v[48:51]
	v_mfma_f32_16x16x32_bf16 v[40:43], v[148:151], v[192:195], v[40:43]
	v_mfma_f32_16x16x32_bf16 v[40:43], v[152:155], v[212:215], v[40:43]
	v_mfma_f32_16x16x32_bf16 v[60:63], v[156:159], v[168:171], v[60:63]
	v_mfma_f32_16x16x32_bf16 v[60:63], v[160:163], v[172:175], v[60:63]
	v_mfma_f32_16x16x32_bf16 v[52:55], v[156:159], v[176:179], v[52:55]
	v_mfma_f32_16x16x32_bf16 v[52:55], v[160:163], v[180:183], v[52:55]
	v_mfma_f32_16x16x32_bf16 v[44:47], v[156:159], v[184:187], v[44:47]
	v_mfma_f32_16x16x32_bf16 v[44:47], v[160:163], v[188:191], v[44:47]
	v_mfma_f32_16x16x32_bf16 v[36:39], v[156:159], v[192:195], v[36:39]
	v_mfma_f32_16x16x32_bf16 v[36:39], v[160:163], v[212:215], v[36:39]
	s_barrier
	s_setprio 0
	s_add_u32 s16, s16, 0x80080
	s_addc_u32 s17, s17, 0
	s_add_i32 s18, s18, s25
	v_lshl_add_u64 v[142:143], s[16:17], 0, v[2:3]
	s_mov_b32 m0, s18
	s_nop 0
	global_load_lds_dwordx4 v[142:143], off
	v_lshl_add_u64 v[142:143], s[16:17], 0, v[0:1]
	s_add_i32 m0, s18, 0x2000
	s_nop 0
	global_load_lds_dwordx4 v[142:143], off
	s_waitcnt vmcnt(6)
	s_setprio 1
	s_barrier
	v_mfma_f32_16x16x32_bf16 v[32:35], v[216:219], v[168:171], v[32:35]
	v_mfma_f32_16x16x32_bf16 v[32:35], v[220:223], v[172:175], v[32:35]
	v_mfma_f32_16x16x32_bf16 v[24:27], v[216:219], v[176:179], v[24:27]
	v_mfma_f32_16x16x32_bf16 v[24:27], v[220:223], v[180:183], v[24:27]
	v_mfma_f32_16x16x32_bf16 v[16:19], v[216:219], v[184:187], v[16:19]
	v_mfma_f32_16x16x32_bf16 v[16:19], v[220:223], v[188:191], v[16:19]
	v_mfma_f32_16x16x32_bf16 v[8:11], v[216:219], v[192:195], v[8:11]
	v_mfma_f32_16x16x32_bf16 v[8:11], v[220:223], v[212:215], v[8:11]
	v_mfma_f32_16x16x32_bf16 v[28:31], v[224:227], v[168:171], v[28:31]
	v_mfma_f32_16x16x32_bf16 v[28:31], v[228:231], v[172:175], v[28:31]
	v_mfma_f32_16x16x32_bf16 v[20:23], v[224:227], v[176:179], v[20:23]
	v_mfma_f32_16x16x32_bf16 v[20:23], v[228:231], v[180:183], v[20:23]
	v_mfma_f32_16x16x32_bf16 v[12:15], v[224:227], v[184:187], v[12:15]
	v_mfma_f32_16x16x32_bf16 v[12:15], v[228:231], v[188:191], v[12:15]
	v_mfma_f32_16x16x32_bf16 v[4:7], v[224:227], v[192:195], v[4:7]
	v_mfma_f32_16x16x32_bf16 v[4:7], v[228:231], v[212:215], v[4:7]
	s_barrier
	s_setprio 0
	s_add_i32 s38, s38, 2
	s_add_u32 s36, s36, 0x100
	s_addc_u32 s37, s37, 0
	s_add_u32 s14, s14, 0x100
	s_addc_u32 s15, s15, 0
	s_cmp_gt_u32 s38, 29
.LBB0_619:
	s_add_u32 s16, s14, 0xfff80080
	s_addc_u32 s17, s15, -1
	s_add_i32 s39, 0, 0x10000
	v_add_u32_e32 v142, s39, v144
	ds_read_b128 v[148:151], v142
	ds_read_b128 v[152:155], v142 offset:1024
	ds_read_b128 v[156:159], v142 offset:2048
	ds_read_b128 v[160:163], v142 offset:3072
	s_cmp_eq_u32 s38, 28
	s_cselect_b32 s19, s3, s17
	s_cselect_b32 s18, s13, s16
	s_cselect_b32 s17, s5, s37
	s_cselect_b32 s16, s35, s36
	v_lshl_add_u64 v[142:143], s[14:15], 0, v[140:141]
	s_add_i32 m0, s26, 0xc000
	ds_read_b128 v[168:171], v146
	ds_read_b128 v[172:175], v146 offset:1024
	ds_read_b128 v[176:179], v146 offset:2048
	ds_read_b128 v[180:183], v146 offset:3072
	ds_read_b128 v[184:187], v146 offset:4096
	ds_read_b128 v[188:191], v146 offset:5120
	ds_read_b128 v[192:195], v146 offset:6144
	ds_read_b128 v[212:215], v146 offset:7168
	global_load_lds_dwordx4 v[142:143], off
	v_lshl_add_u64 v[142:143], s[14:15], 0, v[138:139]
	s_add_i32 m0, s26, 0xe000
	s_nop 0
	global_load_lds_dwordx4 v[142:143], off
	s_waitcnt lgkmcnt(8)
	s_setprio 1
	s_barrier
	s_waitcnt lgkmcnt(0)
	v_mfma_f32_16x16x32_bf16 v[128:131], v[148:151], v[168:171], v[128:131]
	v_mfma_f32_16x16x32_bf16 v[128:131], v[152:155], v[172:175], v[128:131]
	v_mfma_f32_16x16x32_bf16 v[120:123], v[148:151], v[176:179], v[120:123]
	v_mfma_f32_16x16x32_bf16 v[120:123], v[152:155], v[180:183], v[120:123]
	v_mfma_f32_16x16x32_bf16 v[112:115], v[148:151], v[184:187], v[112:115]
	v_mfma_f32_16x16x32_bf16 v[112:115], v[152:155], v[188:191], v[112:115]
	v_mfma_f32_16x16x32_bf16 v[104:107], v[148:151], v[192:195], v[104:107]
	v_mfma_f32_16x16x32_bf16 v[104:107], v[152:155], v[212:215], v[104:107]
	v_mfma_f32_16x16x32_bf16 v[124:127], v[156:159], v[168:171], v[124:127]
	v_mfma_f32_16x16x32_bf16 v[124:127], v[160:163], v[172:175], v[124:127]
	v_mfma_f32_16x16x32_bf16 v[116:119], v[156:159], v[176:179], v[116:119]
	v_mfma_f32_16x16x32_bf16 v[116:119], v[160:163], v[180:183], v[116:119]
	v_mfma_f32_16x16x32_bf16 v[108:111], v[156:159], v[184:187], v[108:111]
	v_mfma_f32_16x16x32_bf16 v[108:111], v[160:163], v[188:191], v[108:111]
	v_mfma_f32_16x16x32_bf16 v[100:103], v[156:159], v[192:195], v[100:103]
	v_mfma_f32_16x16x32_bf16 v[100:103], v[160:163], v[212:215], v[100:103]
	s_barrier
	s_setprio 0
	s_add_i32 s42, 0, 0x14000
	v_add_u32_e32 v142, s42, v144
	s_add_i32 s39, s39, s25
	ds_read_b128 v[216:219], v142
	ds_read_b128 v[220:223], v142 offset:1024
	ds_read_b128 v[224:227], v142 offset:2048
	ds_read_b128 v[228:231], v142 offset:3072
	v_lshl_add_u64 v[142:143], s[16:17], 0, v[2:3]
	s_mov_b32 m0, s39
	v_lshl_add_u64 v[196:197], s[16:17], 0, v[0:1]
	global_load_lds_dwordx4 v[142:143], off
	s_add_i32 m0, s39, 0x2000
	s_nop 0
	global_load_lds_dwordx4 v[196:197], off
	s_setprio 1
	s_barrier
; #define PG8_WAIT_V(n) asm volatile("s_waitcnt vmcnt(" #n ")" ::: "memory")
; #define PG8_WAIT_L(n) asm volatile("s_waitcnt lgkmcnt(" #n ")" ::: "memory")
; #define PG8_BAR __builtin_amdgcn_s_barrier()
; #define PG8_SCHED __builtin_amdgcn_sched_barrier(0)
; template <class Epi, class AddrA, class AddrB>
; __device__ __forceinline__ void gemm_phase(const Sched S, const int lda, const int ldb, const int K, const AddrA addrA,
;                                            const AddrB addrB, const Epi E) {
;     ...
;       PG8_LDB(B0, 0, 0); PG8_SCHED; PG8_LDA(At, 0, 0); PG8_STAGE(PG8_SA(1, 1), a1 + hstepA, voffA);
;       PG8_WAIT_L(8); PG8_BAR; PG8_WAIT_L(0); PG8_MMA(0, 0, At, B0); PG8_BAR; PG8_SCHED;
;       PG8_LDB(B1, 0, 1); PG8_STAGE(PG8_SB(0, 0), b2, voffB);
;       PG8_BAR; PG8_WAIT_L(0); PG8_MMA(0, 1, At, B1); PG8_BAR;
;       PG8_LDA(At, 0, 1); PG8_STAGE(PG8_SA(0, 0), a2, voffA);
;       PG8_BAR; PG8_WAIT_L(0); PG8_MMA(1, 0, At, B0); PG8_BAR; PG8_SCHED;
;       PG8_STAGE(PG8_SB(0, 1), b2 + hstepB, voffB);
;       PG8_WAIT_V(6); PG8_BAR; PG8_MMA(1, 1, At, B1); PG8_BAR;
;       PG8_LDB(B0, 1, 0); PG8_SCHED; PG8_LDA(At, 1, 0); PG8_STAGE(PG8_SA(0, 1), a2 + hstepA, voffA);
;       PG8_WAIT_L(8); PG8_BAR; PG8_WAIT_L(0); PG8_MMA(0, 0, At, B0); PG8_BAR; PG8_SCHED;
;       PG8_LDB(B1, 1, 1); PG8_STAGE(PG8_SB(1, 0), b3, voffB);
;       PG8_BAR; PG8_WAIT_L(0); PG8_MMA(0, 1, At, B1); PG8_BAR;
;       PG8_LDA(At, 1, 1); PG8_STAGE(PG8_SA(1, 0), a3, voffA);
;       PG8_BAR; PG8_WAIT_L(0); PG8_MMA(1, 0, At, B0); PG8_BAR; PG8_SCHED;
	s_waitcnt lgkmcnt(0)
	v_mfma_f32_16x16x32_bf16 v[96:99], v[216:219], v[168:171], v[96:99]
	v_mfma_f32_16x16x32_bf16 v[96:99], v[220:223], v[172:175], v[96:99]
	v_mfma_f32_16x16x32_bf16 v[88:91], v[216:219], v[176:179], v[88:91]
	v_mfma_f32_16x16x32_bf16 v[88:91], v[220:223], v[180:183], v[88:91]
	v_mfma_f32_16x16x32_bf16 v[80:83], v[216:219], v[184:187], v[80:83]
	v_mfma_f32_16x16x32_bf16 v[80:83], v[220:223], v[188:191], v[80:83]
	v_mfma_f32_16x16x32_bf16 v[72:75], v[216:219], v[192:195], v[72:75]
	v_mfma_f32_16x16x32_bf16 v[72:75], v[220:223], v[212:215], v[72:75]
	v_mfma_f32_16x16x32_bf16 v[92:95], v[224:227], v[168:171], v[92:95]
	v_mfma_f32_16x16x32_bf16 v[92:95], v[228:231], v[172:175], v[92:95]
	v_mfma_f32_16x16x32_bf16 v[84:87], v[224:227], v[176:179], v[84:87]
	v_mfma_f32_16x16x32_bf16 v[84:87], v[228:231], v[180:183], v[84:87]
	v_mfma_f32_16x16x32_bf16 v[76:79], v[224:227], v[184:187], v[76:79]
	v_mfma_f32_16x16x32_bf16 v[76:79], v[228:231], v[188:191], v[76:79]
	v_mfma_f32_16x16x32_bf16 v[68:71], v[224:227], v[192:195], v[68:71]
	v_mfma_f32_16x16x32_bf16 v[68:71], v[228:231], v[212:215], v[68:71]
	s_barrier
	s_setprio 0
	s_mov_b32 m0, s26
	v_lshl_add_u64 v[232:233], s[18:19], 0, v[134:135]
	ds_read_b128 v[168:171], v146 offset:16384
	ds_read_b128 v[172:175], v146 offset:17408
	ds_read_b128 v[176:179], v146 offset:18432
	ds_read_b128 v[180:183], v146 offset:19456
	ds_read_b128 v[184:187], v146 offset:20480
	ds_read_b128 v[188:191], v146 offset:21504
	ds_read_b128 v[192:195], v146 offset:22528
	ds_read_b128 v[212:215], v146 offset:23552
	global_load_lds_dwordx4 v[232:233], off
	v_lshl_add_u64 v[234:235], s[18:19], 0, v[132:133]
	s_mov_b32 m0, s27
	s_nop 0
	global_load_lds_dwordx4 v[234:235], off
	s_setprio 1
	s_barrier
	s_waitcnt lgkmcnt(0)
	v_mfma_f32_16x16x32_bf16 v[64:67], v[148:151], v[168:171], v[64:67]
	v_mfma_f32_16x16x32_bf16 v[64:67], v[152:155], v[172:175], v[64:67]
	v_mfma_f32_16x16x32_bf16 v[56:59], v[148:151], v[176:179], v[56:59]
	v_mfma_f32_16x16x32_bf16 v[56:59], v[152:155], v[180:183], v[56:59]
	v_mfma_f32_16x16x32_bf16 v[48:51], v[148:151], v[184:187], v[48:51]
	v_mfma_f32_16x16x32_bf16 v[48:51], v[152:155], v[188:191], v[48:51]
	v_mfma_f32_16x16x32_bf16 v[40:43], v[148:151], v[192:195], v[40:43]
	v_mfma_f32_16x16x32_bf16 v[40:43], v[152:155], v[212:215], v[40:43]
	v_mfma_f32_16x16x32_bf16 v[60:63], v[156:159], v[168:171], v[60:63]
	v_mfma_f32_16x16x32_bf16 v[60:63], v[160:163], v[172:175], v[60:63]
	v_mfma_f32_16x16x32_bf16 v[52:55], v[156:159], v[176:179], v[52:55]
	v_mfma_f32_16x16x32_bf16 v[52:55], v[160:163], v[180:183], v[52:55]
	v_mfma_f32_16x16x32_bf16 v[44:47], v[156:159], v[184:187], v[44:47]
	v_mfma_f32_16x16x32_bf16 v[44:47], v[160:163], v[188:191], v[44:47]
	v_mfma_f32_16x16x32_bf16 v[36:39], v[156:159], v[192:195], v[36:39]
	v_mfma_f32_16x16x32_bf16 v[36:39], v[160:163], v[212:215], v[36:39]
	s_barrier
	s_setprio 0
	s_add_u32 s40, s16, 0x80000
	s_addc_u32 s41, s17, 0
	s_add_i32 s39, s42, s25
	v_lshl_add_u64 v[148:149], s[40:41], 0, v[2:3]
	s_mov_b32 m0, s39
	s_nop 0
	global_load_lds_dwordx4 v[148:149], off
	v_lshl_add_u64 v[148:149], s[40:41], 0, v[0:1]
	s_add_i32 m0, s39, 0x2000
	s_nop 0
	global_load_lds_dwordx4 v[148:149], off
	s_waitcnt vmcnt(6)
	s_setprio 1
	s_barrier
	v_mfma_f32_16x16x32_bf16 v[32:35], v[216:219], v[168:171], v[32:35]
	v_mfma_f32_16x16x32_bf16 v[32:35], v[220:223], v[172:175], v[32:35]
	v_mfma_f32_16x16x32_bf16 v[24:27], v[216:219], v[176:179], v[24:27]
	v_mfma_f32_16x16x32_bf16 v[24:27], v[220:223], v[180:183], v[24:27]
	v_mfma_f32_16x16x32_bf16 v[16:19], v[216:219], v[184:187], v[16:19]
	v_mfma_f32_16x16x32_bf16 v[16:19], v[220:223], v[188:191], v[16:19]
	v_mfma_f32_16x16x32_bf16 v[8:11], v[216:219], v[192:195], v[8:11]
	v_mfma_f32_16x16x32_bf16 v[8:11], v[220:223], v[212:215], v[8:11]
	v_mfma_f32_16x16x32_bf16 v[28:31], v[224:227], v[168:171], v[28:31]
	v_mfma_f32_16x16x32_bf16 v[28:31], v[228:231], v[172:175], v[28:31]
	v_mfma_f32_16x16x32_bf16 v[20:23], v[224:227], v[176:179], v[20:23]
	v_mfma_f32_16x16x32_bf16 v[20:23], v[228:231], v[180:183], v[20:23]
	v_mfma_f32_16x16x32_bf16 v[12:15], v[224:227], v[184:187], v[12:15]
	v_mfma_f32_16x16x32_bf16 v[12:15], v[228:231], v[188:191], v[12:15]
	v_mfma_f32_16x16x32_bf16 v[4:7], v[224:227], v[192:195], v[4:7]
	v_mfma_f32_16x16x32_bf16 v[4:7], v[228:231], v[212:215], v[4:7]
	s_barrier
	s_setprio 0
	s_add_i32 s39, 0, 0x18000
	v_add_u32_e32 v147, s39, v144
	ds_read_b128 v[148:151], v147
	ds_read_b128 v[152:155], v147 offset:1024
	ds_read_b128 v[156:159], v147 offset:2048
	ds_read_b128 v[160:163], v147 offset:3072
	s_add_u32 s18, s18, 0x80000
	s_addc_u32 s19, s19, 0
	s_mov_b32 m0, s28
	v_lshl_add_u64 v[216:217], s[18:19], 0, v[134:135]
	ds_read_b128 v[168:171], v146 offset:32768
	ds_read_b128 v[172:175], v146 offset:33792
	ds_read_b128 v[176:179], v146 offset:34816
	ds_read_b128 v[180:183], v146 offset:35840
	ds_read_b128 v[184:187], v146 offset:36864
	ds_read_b128 v[188:191], v146 offset:37888
	ds_read_b128 v[192:195], v146 offset:38912
	ds_read_b128 v[212:215], v146 offset:39936
	global_load_lds_dwordx4 v[216:217], off
	v_lshl_add_u64 v[216:217], s[18:19], 0, v[132:133]
	s_mov_b32 m0, s29
	s_nop 0
	global_load_lds_dwordx4 v[216:217], off
	s_waitcnt lgkmcnt(8)
	s_setprio 1
	s_barrier
; #define PG8_WAIT_V(n) asm volatile("s_waitcnt vmcnt(" #n ")" ::: "memory")
; #define PG8_WAIT_L(n) asm volatile("s_waitcnt lgkmcnt(" #n ")" ::: "memory")
; #define PG8_BAR __builtin_amdgcn_s_barrier()
; #define PG8_SCHED __builtin_amdgcn_sched_barrier(0)
; template <class Epi, class AddrA, class AddrB>
; __device__ __forceinline__ void gemm_phase(const Sched S, const int lda, const int ldb, const int K, const AddrA addrA,
;                                            const AddrB addrB, const Epi E) {
;     ...
;       PG8_WAIT_V(6); PG8_BAR; PG8_MMA(1, 1, At, B1); PG8_BAR;
;       PG8_LDB(B0, 1, 0); PG8_SCHED; PG8_LDA(At, 1, 0); PG8_STAGE(PG8_SA(0, 1), a2 + hstepA, voffA);
;       PG8_WAIT_L(8); PG8_BAR; PG8_WAIT_L(0); PG8_MMA(0, 0, At, B0); PG8_BAR; PG8_SCHED;
;       PG8_LDB(B1, 1, 1); PG8_STAGE(PG8_SB(1, 0), b3, voffB);
;       PG8_BAR; PG8_WAIT_L(0); PG8_MMA(0, 1, At, B1); PG8_BAR;
;       PG8_LDA(At, 1, 1); PG8_STAGE(PG8_SA(1, 0), a3, voffA);
;       PG8_BAR; PG8_WAIT_L(0); PG8_MMA(1, 0, At, B0); PG8_BAR; PG8_SCHED;
;       PG8_STAGE(PG8_SB(1, 1), b3 + hstepB, voffB);
;       PG8_WAIT_V(6); PG8_BAR; PG8_MMA(1, 1, At, B1); PG8_BAR;
;     }
	s_waitcnt lgkmcnt(0)
	v_mfma_f32_16x16x32_bf16 v[128:131], v[148:151], v[168:171], v[128:131]
	v_mfma_f32_16x16x32_bf16 v[128:131], v[152:155], v[172:175], v[128:131]
	v_mfma_f32_16x16x32_bf16 v[120:123], v[148:151], v[176:179], v[120:123]
	v_mfma_f32_16x16x32_bf16 v[120:123], v[152:155], v[180:183], v[120:123]
	v_mfma_f32_16x16x32_bf16 v[112:115], v[148:151], v[184:187], v[112:115]
	v_mfma_f32_16x16x32_bf16 v[112:115], v[152:155], v[188:191], v[112:115]
	v_mfma_f32_16x16x32_bf16 v[104:107], v[148:151], v[192:195], v[104:107]
	v_mfma_f32_16x16x32_bf16 v[104:107], v[152:155], v[212:215], v[104:107]
	v_mfma_f32_16x16x32_bf16 v[124:127], v[156:159], v[168:171], v[124:127]
	v_mfma_f32_16x16x32_bf16 v[124:127], v[160:163], v[172:175], v[124:127]
	v_mfma_f32_16x16x32_bf16 v[116:119], v[156:159], v[176:179], v[116:119]
	v_mfma_f32_16x16x32_bf16 v[116:119], v[160:163], v[180:183], v[116:119]
	v_mfma_f32_16x16x32_bf16 v[108:111], v[156:159], v[184:187], v[108:111]
	v_mfma_f32_16x16x32_bf16 v[108:111], v[160:163], v[188:191], v[108:111]
	v_mfma_f32_16x16x32_bf16 v[100:103], v[156:159], v[192:195], v[100:103]
	v_mfma_f32_16x16x32_bf16 v[100:103], v[160:163], v[212:215], v[100:103]
	s_barrier
	s_setprio 0
	s_add_i32 s18, 0, 0x1c000
	s_add_i32 s19, s39, s25
	v_add_u32_e32 v147, s18, v144
	v_lshl_add_u64 v[142:143], v[142:143], 0, s[52:53]
	s_mov_b32 m0, s19
	ds_read_b128 v[216:219], v147
	ds_read_b128 v[220:223], v147 offset:1024
	ds_read_b128 v[224:227], v147 offset:2048
	ds_read_b128 v[228:231], v147 offset:3072
	global_load_lds_dwordx4 v[142:143], off
	v_lshl_add_u64 v[142:143], v[196:197], 0, s[52:53]
	s_add_i32 m0, s19, 0x2000
	s_nop 0
	global_load_lds_dwordx4 v[142:143], off
	s_setprio 1
	s_barrier
	s_waitcnt lgkmcnt(0)
	v_mfma_f32_16x16x32_bf16 v[96:99], v[216:219], v[168:171], v[96:99]
	v_mfma_f32_16x16x32_bf16 v[96:99], v[220:223], v[172:175], v[96:99]
	v_mfma_f32_16x16x32_bf16 v[88:91], v[216:219], v[176:179], v[88:91]
	v_mfma_f32_16x16x32_bf16 v[88:91], v[220:223], v[180:183], v[88:91]
	v_mfma_f32_16x16x32_bf16 v[80:83], v[216:219], v[184:187], v[80:83]
	v_mfma_f32_16x16x32_bf16 v[80:83], v[220:223], v[188:191], v[80:83]
	v_mfma_f32_16x16x32_bf16 v[72:75], v[216:219], v[192:195], v[72:75]
	v_mfma_f32_16x16x32_bf16 v[72:75], v[220:223], v[212:215], v[72:75]
	v_mfma_f32_16x16x32_bf16 v[92:95], v[224:227], v[168:171], v[92:95]
	v_mfma_f32_16x16x32_bf16 v[92:95], v[228:231], v[172:175], v[92:95]
	v_mfma_f32_16x16x32_bf16 v[84:87], v[224:227], v[176:179], v[84:87]
	v_mfma_f32_16x16x32_bf16 v[84:87], v[228:231], v[180:183], v[84:87]
	v_mfma_f32_16x16x32_bf16 v[76:79], v[224:227], v[184:187], v[76:79]
	v_mfma_f32_16x16x32_bf16 v[76:79], v[228:231], v[188:191], v[76:79]
	v_mfma_f32_16x16x32_bf16 v[68:71], v[224:227], v[192:195], v[68:71]
	v_mfma_f32_16x16x32_bf16 v[68:71], v[228:231], v[212:215], v[68:71]
	s_barrier
	s_setprio 0
	s_mov_b32 m0, s30
	v_lshl_add_u64 v[142:143], v[232:233], 0, s[52:53]
	ds_read_b128 v[168:171], v146 offset:49152
	ds_read_b128 v[172:175], v146 offset:50176
	ds_read_b128 v[176:179], v146 offset:51200
	ds_read_b128 v[180:183], v146 offset:52224
	ds_read_b128 v[184:187], v146 offset:53248
	ds_read_b128 v[188:191], v146 offset:54272
	ds_read_b128 v[192:195], v146 offset:55296
	ds_read_b128 v[212:215], v146 offset:56320
	global_load_lds_dwordx4 v[142:143], off
	v_lshl_add_u64 v[142:143], v[234:235], 0, s[52:53]
	s_mov_b32 m0, s31
	s_nop 0
	global_load_lds_dwordx4 v[142:143], off
	s_setprio 1
	s_barrier
	s_waitcnt lgkmcnt(0)
	v_mfma_f32_16x16x32_bf16 v[64:67], v[148:151], v[168:171], v[64:67]
	v_mfma_f32_16x16x32_bf16 v[64:67], v[152:155], v[172:175], v[64:67]
	v_mfma_f32_16x16x32_bf16 v[56:59], v[148:151], v[176:179], v[56:59]
	v_mfma_f32_16x16x32_bf16 v[56:59], v[152:155], v[180:183], v[56:59]
	v_mfma_f32_16x16x32_bf16 v[48:51], v[148:151], v[184:187], v[48:51]
	v_mfma_f32_16x16x32_bf16 v[48:51], v[152:155], v[188:191], v[48:51]
	v_mfma_f32_16x16x32_bf16 v[40:43], v[148:151], v[192:195], v[40:43]
	v_mfma_f32_16x16x32_bf16 v[40:43], v[152:155], v[212:215], v[40:43]
	v_mfma_f32_16x16x32_bf16 v[60:63], v[156:159], v[168:171], v[60:63]
	v_mfma_f32_16x16x32_bf16 v[60:63], v[160:163], v[172:175], v[60:63]
	v_mfma_f32_16x16x32_bf16 v[52:55], v[156:159], v[176:179], v[52:55]
	v_mfma_f32_16x16x32_bf16 v[52:55], v[160:163], v[180:183], v[52:55]
	v_mfma_f32_16x16x32_bf16 v[44:47], v[156:159], v[184:187], v[44:47]
	v_mfma_f32_16x16x32_bf16 v[44:47], v[160:163], v[188:191], v[44:47]
	v_mfma_f32_16x16x32_bf16 v[36:39], v[156:159], v[192:195], v[36:39]
	v_mfma_f32_16x16x32_bf16 v[36:39], v[160:163], v[212:215], v[36:39]
	s_barrier
	s_setprio 0
	s_add_u32 s16, s16, 0x80080
	s_addc_u32 s17, s17, 0
	s_add_i32 s18, s18, s25
	v_lshl_add_u64 v[142:143], s[16:17], 0, v[2:3]
	s_mov_b32 m0, s18
	s_nop 0
	global_load_lds_dwordx4 v[142:143], off
	v_lshl_add_u64 v[142:143], s[16:17], 0, v[0:1]
	s_add_i32 m0, s18, 0x2000
	s_nop 0
	global_load_lds_dwordx4 v[142:143], off
	s_waitcnt vmcnt(6)
	s_setprio 1
	s_barrier
	v_mfma_f32_16x16x32_bf16 v[32:35], v[216:219], v[168:171], v[32:35]
	v_mfma_f32_16x16x32_bf16 v[32:35], v[220:223], v[172:175], v[32:35]
	v_mfma_f32_16x16x32_bf16 v[24:27], v[216:219], v[176:179], v[24:27]
	v_mfma_f32_16x16x32_bf16 v[24:27], v[220:223], v[180:183], v[24:27]
	v_mfma_f32_16x16x32_bf16 v[16:19], v[216:219], v[184:187], v[16:19]
	v_mfma_f32_16x16x32_bf16 v[16:19], v[220:223], v[188:191], v[16:19]
	v_mfma_f32_16x16x32_bf16 v[8:11], v[216:219], v[192:195], v[8:11]
	v_mfma_f32_16x16x32_bf16 v[8:11], v[220:223], v[212:215], v[8:11]
	v_mfma_f32_16x16x32_bf16 v[28:31], v[224:227], v[168:171], v[28:31]
	v_mfma_f32_16x16x32_bf16 v[28:31], v[228:231], v[172:175], v[28:31]
	v_mfma_f32_16x16x32_bf16 v[20:23], v[224:227], v[176:179], v[20:23]
	v_mfma_f32_16x16x32_bf16 v[20:23], v[228:231], v[180:183], v[20:23]
	v_mfma_f32_16x16x32_bf16 v[12:15], v[224:227], v[184:187], v[12:15]
	v_mfma_f32_16x16x32_bf16 v[12:15], v[228:231], v[188:191], v[12:15]
	v_mfma_f32_16x16x32_bf16 v[4:7], v[224:227], v[192:195], v[4:7]
	v_mfma_f32_16x16x32_bf16 v[4:7], v[228:231], v[212:215], v[4:7]
	s_barrier
; #define PG8_WAIT_V(n) asm volatile("s_waitcnt vmcnt(" #n ")" ::: "memory")
; #define PG8_BAR __builtin_amdgcn_s_barrier()
; template <class Epi, class AddrA, class AddrB>
; __device__ __forceinline__ void gemm_phase(const Sched S, const int lda, const int ldb, const int K, const AddrA addrA,
;                                            const AddrB addrB, const Epi E) {
;     ...
;       PG8_STAGE(PG8_SB(1, 1), b3 + hstepB, voffB);
;       PG8_WAIT_V(6); PG8_BAR; PG8_MMA(1, 1, At, B1); PG8_BAR;
;     }
;   __device__ __forceinline__ void operator()(EPI_ARGS) const {
;     const size_t row0 = (size_t)u.pm * 256 + wr * 64 + fr;
;     const int col0 = u.pn * 256 + wc * 32 + 8 * fq;
; #pragma unroll
;     for (int ai = 0; ai < 2; ++ai)
; #pragma unroll
;       for (int bj = 0; bj < 2; ++bj) {
;         f32x4 x0[4], x1[4];
; #pragma unroll
;         for (int m = 0; m < 4; ++m) {
;           const size_t o = (row0 + ai * HALF + m * 16) * DM + col0 + bj * HALF;
;           x0[m] = *(const f32x4*)(xres + o);
;           x1[m] = *(const f32x4*)(xres + o + 4);
;         }
;         __builtin_amdgcn_sched_barrier(0);
; #pragma unroll
;         for (int m = 0; m < 4; ++m) {
;           const size_t o = (row0 + ai * HALF + m * 16) * DM + col0 + bj * HALF;
;           *(f32x4*)(hbuf + o) = acc[ai][bj][m][0] + x0[m] * ALPHA;
;           *(f32x4*)(hbuf + o + 4) = acc[ai][bj][m][1] + x1[m] * ALPHA;
;         }
;       }
	s_setprio 0
	s_add_i32 s38, s38, 2
	s_add_u32 s36, s36, 0x100
	s_addc_u32 s37, s37, 0
	s_add_u32 s14, s14, 0x100
	s_addc_u32 s15, s15, 0
	s_cmp_gt_u32 s38, 29
	s_cbranch_scc0 .LBB0_619
	s_ashr_i32 s13, s12, 31
	v_lshl_or_b32 v142, s34, 8, v145
	v_ashrrev_i32_e32 v143, 31, v142
	s_lshl_b64 s[12:13], s[12:13], 21
	v_lshlrev_b64 v[184:185], 2, v[142:143]
	v_lshl_add_u64 v[188:189], s[12:13], 0, v[136:137]
	v_lshl_add_u64 v[186:187], s[0:1], 0, v[184:185]
	v_or_b32_e32 v190, 0x20000, v188
	v_mov_b32_e32 v191, v189
	v_or_b32_e32 v192, 0x40000, v188
	v_mov_b32_e32 v193, v189
	v_or_b32_e32 v194, 0x60000, v188
	v_mov_b32_e32 v195, v189
	v_lshl_add_u64 v[142:143], v[186:187], 0, v[188:189]
	v_lshl_add_u64 v[160:161], v[186:187], 0, v[190:191]
	v_lshl_add_u64 v[172:173], v[186:187], 0, v[192:193]
	v_lshl_add_u64 v[180:181], v[186:187], 0, v[194:195]
	flat_load_dwordx4 v[148:151], v[142:143]
	flat_load_dwordx4 v[152:155], v[142:143] offset:16
	flat_load_dwordx4 v[156:159], v[160:161]
	s_nop 0
	flat_load_dwordx4 v[160:163], v[160:161] offset:16
	s_nop 0
	flat_load_dwordx4 v[168:171], v[172:173]
	s_nop 0
	flat_load_dwordx4 v[172:175], v[172:173] offset:16
	s_nop 0
	flat_load_dwordx4 v[176:179], v[180:181]
	s_nop 0
	flat_load_dwordx4 v[180:183], v[180:181] offset:16
	v_lshl_add_u64 v[184:185], s[48:49], 0, v[184:185]
	s_mov_b32 s14, 0x3fb504f3
	s_waitcnt vmcnt(0) lgkmcnt(0)
	v_pk_fma_f32 v[148:149], v[148:149], s[14:15], v[128:129] op_sel_hi:[1,0,1]
	v_lshl_add_u64 v[128:129], v[184:185], 0, v[188:189]
	v_pk_fma_f32 v[126:127], v[154:155], s[14:15], v[126:127] op_sel_hi:[1,0,1]
	v_pk_fma_f32 v[124:125], v[152:153], s[14:15], v[124:125] op_sel_hi:[1,0,1]
	global_store_dwordx4 v[128:129], v[124:127], off offset:16
	v_pk_fma_f32 v[118:119], v[162:163], s[14:15], v[118:119] op_sel_hi:[1,0,1]
	v_pk_fma_f32 v[116:117], v[160:161], s[14:15], v[116:117] op_sel_hi:[1,0,1]
	v_lshl_add_u64 v[124:125], v[184:185], 0, v[190:191]
	v_pk_fma_f32 v[122:123], v[158:159], s[14:15], v[122:123] op_sel_hi:[1,0,1]
	v_pk_fma_f32 v[120:121], v[156:157], s[14:15], v[120:121] op_sel_hi:[1,0,1]
	global_store_dwordx4 v[124:125], v[116:119], off offset:16
	v_pk_fma_f32 v[110:111], v[174:175], s[14:15], v[110:111] op_sel_hi:[1,0,1]
	v_pk_fma_f32 v[108:109], v[172:173], s[14:15], v[108:109] op_sel_hi:[1,0,1]
	v_lshl_add_u64 v[116:117], v[184:185], 0, v[192:193]
	s_mov_b64 s[12:13], 0x200
	v_pk_fma_f32 v[150:151], v[150:151], s[14:15], v[130:131] op_sel_hi:[1,0,1]
	global_store_dwordx4 v[124:125], v[120:123], off
	v_pk_fma_f32 v[114:115], v[170:171], s[14:15], v[114:115] op_sel_hi:[1,0,1]
	v_pk_fma_f32 v[112:113], v[168:169], s[14:15], v[112:113] op_sel_hi:[1,0,1]
	global_store_dwordx4 v[116:117], v[108:111], off offset:16
	v_pk_fma_f32 v[106:107], v[178:179], s[14:15], v[106:107] op_sel_hi:[1,0,1]
	v_pk_fma_f32 v[104:105], v[176:177], s[14:15], v[104:105] op_sel_hi:[1,0,1]
	v_lshl_add_u64 v[108:109], v[184:185], 0, v[194:195]
	v_pk_fma_f32 v[102:103], v[182:183], s[14:15], v[102:103] op_sel_hi:[1,0,1]
	v_pk_fma_f32 v[100:101], v[180:181], s[14:15], v[100:101] op_sel_hi:[1,0,1]
	v_lshl_add_u64 v[124:125], v[186:187], 0, s[12:13]
	global_store_dwordx4 v[128:129], v[148:151], off
	global_store_dwordx4 v[116:117], v[112:115], off
	global_store_dwordx4 v[108:109], v[104:107], off
	global_store_dwordx4 v[108:109], v[100:103], off offset:16
	v_lshl_add_u64 v[112:113], v[124:125], 0, v[190:191]
	v_lshl_add_u64 v[120:121], v[124:125], 0, v[192:193]
	v_lshl_add_u64 v[130:131], v[124:125], 0, v[194:195]
	flat_load_dwordx4 v[100:103], v[142:143] offset:512
	flat_load_dwordx4 v[104:107], v[142:143] offset:528
	flat_load_dwordx4 v[108:111], v[112:113]
	s_nop 0
	flat_load_dwordx4 v[112:115], v[112:113] offset:16
	s_nop 0
	flat_load_dwordx4 v[116:119], v[120:121]
	s_nop 0
	flat_load_dwordx4 v[120:123], v[120:121] offset:16
	s_nop 0
	flat_load_dwordx4 v[124:127], v[130:131]
	flat_load_dwordx4 v[148:151], v[130:131] offset:16
	s_mov_b32 s3, 0x100000
	s_waitcnt vmcnt(0) lgkmcnt(0)
	v_pk_fma_f32 v[96:97], v[100:101], s[14:15], v[96:97] op_sel_hi:[1,0,1]
	v_add_co_u32_e32 v100, vcc, s3, v142
	s_mov_b32 s5, 0x120000
	s_nop 0
	v_addc_co_u32_e32 v101, vcc, 0, v143, vcc
	v_pk_fma_f32 v[98:99], v[102:103], s[14:15], v[98:99] op_sel_hi:[1,0,1]
	v_add_co_u32_e32 v102, vcc, s5, v142
	v_lshl_add_u64 v[130:131], v[184:185], 0, s[12:13]
	v_pk_fma_f32 v[94:95], v[106:107], s[14:15], v[94:95] op_sel_hi:[1,0,1]
	v_pk_fma_f32 v[92:93], v[104:105], s[14:15], v[92:93] op_sel_hi:[1,0,1]
	v_addc_co_u32_e32 v103, vcc, 0, v143, vcc
	s_mov_b32 s12, 0x140000
	global_store_dwordx4 v[128:129], v[92:95], off offset:528
	v_pk_fma_f32 v[86:87], v[114:115], s[14:15], v[86:87] op_sel_hi:[1,0,1]
	v_pk_fma_f32 v[84:85], v[112:113], s[14:15], v[84:85] op_sel_hi:[1,0,1]
	v_lshl_add_u64 v[92:93], v[130:131], 0, v[190:191]
	v_add_co_u32_e32 v104, vcc, s12, v142
	global_store_dwordx4 v[92:93], v[84:87], off offset:16
	v_pk_fma_f32 v[78:79], v[122:123], s[14:15], v[78:79] op_sel_hi:[1,0,1]
	v_pk_fma_f32 v[76:77], v[120:121], s[14:15], v[76:77] op_sel_hi:[1,0,1]
	v_lshl_add_u64 v[84:85], v[130:131], 0, v[192:193]
	v_addc_co_u32_e32 v105, vcc, 0, v143, vcc
	s_mov_b32 s13, 0x160000
	v_pk_fma_f32 v[90:91], v[110:111], s[14:15], v[90:91] op_sel_hi:[1,0,1]
	v_pk_fma_f32 v[88:89], v[108:109], s[14:15], v[88:89] op_sel_hi:[1,0,1]
	v_pk_fma_f32 v[82:83], v[118:119], s[14:15], v[82:83] op_sel_hi:[1,0,1]
	v_pk_fma_f32 v[80:81], v[116:117], s[14:15], v[80:81] op_sel_hi:[1,0,1]
	global_store_dwordx4 v[84:85], v[76:79], off offset:16
	v_pk_fma_f32 v[74:75], v[126:127], s[14:15], v[74:75] op_sel_hi:[1,0,1]
	v_pk_fma_f32 v[72:73], v[124:125], s[14:15], v[72:73] op_sel_hi:[1,0,1]
	v_lshl_add_u64 v[76:77], v[130:131], 0, v[194:195]
	v_pk_fma_f32 v[70:71], v[150:151], s[14:15], v[70:71] op_sel_hi:[1,0,1]
	v_pk_fma_f32 v[68:69], v[148:149], s[14:15], v[68:69] op_sel_hi:[1,0,1]
	s_mov_b64 s[16:17], 0x100000
	s_mov_b64 s[18:19], 0x120000
	s_mov_b64 s[34:35], 0x140000
	s_mov_b64 s[36:37], 0x160000
	v_add_co_u32_e32 v106, vcc, s13, v142
	global_store_dwordx4 v[128:129], v[96:99], off offset:512
	global_store_dwordx4 v[92:93], v[88:91], off
	global_store_dwordx4 v[84:85], v[80:83], off
	global_store_dwordx4 v[76:77], v[72:75], off
	global_store_dwordx4 v[76:77], v[68:71], off offset:16
	v_lshl_add_u64 v[80:81], v[142:143], 0, s[18:19]
	v_lshl_add_u64 v[72:73], v[142:143], 0, s[16:17]
	v_lshl_add_u64 v[88:89], v[142:143], 0, s[34:35]
	v_lshl_add_u64 v[96:97], v[142:143], 0, s[36:37]
	v_addc_co_u32_e32 v107, vcc, 0, v143, vcc
	flat_load_dwordx4 v[68:71], v[100:101]
	s_nop 0
	flat_load_dwordx4 v[72:75], v[72:73] offset:16
	s_nop 0
	flat_load_dwordx4 v[76:79], v[102:103]
	s_nop 0
	flat_load_dwordx4 v[80:83], v[80:81] offset:16
	s_nop 0
	flat_load_dwordx4 v[84:87], v[104:105]
	s_nop 0
	flat_load_dwordx4 v[88:91], v[88:89] offset:16
	s_nop 0
	flat_load_dwordx4 v[92:95], v[106:107]
	s_nop 0
	flat_load_dwordx4 v[96:99], v[96:97] offset:16
	s_waitcnt vmcnt(0) lgkmcnt(0)
; #define PG8_WAIT_V(n) asm volatile("s_waitcnt vmcnt(" #n ")" ::: "memory")
; #define PG8_BAR __builtin_amdgcn_s_barrier()
; template <class Epi, class AddrA, class AddrB>
; __device__ __forceinline__ void gemm_phase(const Sched S, const int lda, const int ldb, const int K, const AddrA addrA,
;                                            const AddrB addrB, const Epi E) {
;     ...
;     E(acc, cur, wr, wc, fr, fq);
;     if (!has_next) break;
;     if (!(Epi::KEEP && cur.br + 1 < S.nbr)) {
; #pragma unroll
;       for (int a = 0; a < 2; ++a)
; #pragma unroll
;         for (int b = 0; b < 2; ++b)
; #pragma unroll
;           for (int m = 0; m < 4; ++m)
; #pragma unroll
;             for (int n = 0; n < 2; ++n) acc[a][b][m][n] = (f32x4){0.f, 0.f, 0.f, 0.f};
;     }
;     cur = nxt; cA = nA; cB = nB; ++ui;
;   }
;   PG8_WAIT_V(0);
;   if (wr == 0) PG8_BAR;
;   PG8_BAR;
;   __device__ __forceinline__ void operator()(EPI_ARGS) const {
;     ...
;     for (int ai = 0; ai < 2; ++ai)
; #pragma unroll
;       for (int bj = 0; bj < 2; ++bj) {
;         f32x4 x0[4], x1[4];
; #pragma unroll
;         for (int m = 0; m < 4; ++m) {
;           const size_t o = (row0 + ai * HALF + m * 16) * DM + col0 + bj * HALF;
;           x0[m] = *(const f32x4*)(xres + o);
;           x1[m] = *(const f32x4*)(xres + o + 4);
;         }
;         __builtin_amdgcn_sched_barrier(0);
; #pragma unroll
;         for (int m = 0; m < 4; ++m) {
;           const size_t o = (row0 + ai * HALF + m * 16) * DM + col0 + bj * HALF;
;           *(f32x4*)(hbuf + o) = acc[ai][bj][m][0] + x0[m] * ALPHA;
;           *(f32x4*)(hbuf + o + 4) = acc[ai][bj][m][1] + x1[m] * ALPHA;
;         }
	v_pk_fma_f32 v[66:67], v[70:71], s[14:15], v[66:67] op_sel_hi:[1,0,1]
	v_add_co_u32_e32 v70, vcc, s3, v128
	v_pk_fma_f32 v[64:65], v[68:69], s[14:15], v[64:65] op_sel_hi:[1,0,1]
	v_lshl_add_u64 v[68:69], v[128:129], 0, s[16:17]
	v_addc_co_u32_e32 v71, vcc, 0, v129, vcc
	v_pk_fma_f32 v[62:63], v[74:75], s[14:15], v[62:63] op_sel_hi:[1,0,1]
	v_pk_fma_f32 v[60:61], v[72:73], s[14:15], v[60:61] op_sel_hi:[1,0,1]
	global_store_dwordx4 v[68:69], v[60:63], off offset:16
	v_add_co_u32_e32 v68, vcc, s5, v128
	s_nop 0
	v_lshl_add_u64 v[60:61], v[128:129], 0, s[18:19]
	v_addc_co_u32_e32 v69, vcc, 0, v129, vcc
	v_add_co_u32_e32 v72, vcc, s12, v128
	v_pk_fma_f32 v[54:55], v[82:83], s[14:15], v[54:55] op_sel_hi:[1,0,1]
	v_pk_fma_f32 v[52:53], v[80:81], s[14:15], v[52:53] op_sel_hi:[1,0,1]
	v_addc_co_u32_e32 v73, vcc, 0, v129, vcc
	global_store_dwordx4 v[60:61], v[52:55], off offset:16
	v_pk_fma_f32 v[46:47], v[90:91], s[14:15], v[46:47] op_sel_hi:[1,0,1]
	v_pk_fma_f32 v[44:45], v[88:89], s[14:15], v[44:45] op_sel_hi:[1,0,1]
	v_lshl_add_u64 v[52:53], v[128:129], 0, s[34:35]
	v_add_co_u32_e32 v74, vcc, s13, v128
	v_pk_fma_f32 v[58:59], v[78:79], s[14:15], v[58:59] op_sel_hi:[1,0,1]
	v_pk_fma_f32 v[56:57], v[76:77], s[14:15], v[56:57] op_sel_hi:[1,0,1]
	v_pk_fma_f32 v[50:51], v[86:87], s[14:15], v[50:51] op_sel_hi:[1,0,1]
	v_pk_fma_f32 v[48:49], v[84:85], s[14:15], v[48:49] op_sel_hi:[1,0,1]
	global_store_dwordx4 v[52:53], v[44:47], off offset:16
	v_pk_fma_f32 v[42:43], v[94:95], s[14:15], v[42:43] op_sel_hi:[1,0,1]
	v_pk_fma_f32 v[40:41], v[92:93], s[14:15], v[40:41] op_sel_hi:[1,0,1]
	v_lshl_add_u64 v[44:45], v[128:129], 0, s[36:37]
	v_addc_co_u32_e32 v75, vcc, 0, v129, vcc
	v_pk_fma_f32 v[38:39], v[98:99], s[14:15], v[38:39] op_sel_hi:[1,0,1]
	v_pk_fma_f32 v[36:37], v[96:97], s[14:15], v[36:37] op_sel_hi:[1,0,1]
	s_mov_b64 s[12:13], 0x100200
	s_mov_b64 s[16:17], 0x120200
	s_mov_b64 s[18:19], 0x140200
	s_mov_b64 s[34:35], 0x160200
	global_store_dwordx4 v[70:71], v[64:67], off
	global_store_dwordx4 v[68:69], v[56:59], off
	global_store_dwordx4 v[72:73], v[48:51], off
	global_store_dwordx4 v[74:75], v[40:43], off
	global_store_dwordx4 v[44:45], v[36:39], off offset:16
	v_lshl_add_u64 v[44:45], v[142:143], 0, s[12:13]
	v_lshl_add_u64 v[48:49], v[142:143], 0, s[16:17]
	v_lshl_add_u64 v[60:61], v[142:143], 0, s[18:19]
	v_lshl_add_u64 v[64:65], v[142:143], 0, s[34:35]
	flat_load_dwordx4 v[36:39], v[100:101] offset:512
	flat_load_dwordx4 v[40:43], v[102:103] offset:512
	s_nop 0
	flat_load_dwordx4 v[44:47], v[44:45] offset:16
	s_nop 0
	flat_load_dwordx4 v[48:51], v[48:49] offset:16
	s_nop 0
	flat_load_dwordx4 v[52:55], v[104:105] offset:512
	flat_load_dwordx4 v[56:59], v[106:107] offset:512
	s_nop 0
	flat_load_dwordx4 v[60:63], v[60:61] offset:16
	s_nop 0
	flat_load_dwordx4 v[64:67], v[64:65] offset:16
	s_waitcnt vmcnt(0) lgkmcnt(0)
	v_pk_fma_f32 v[32:33], v[36:37], s[14:15], v[32:33] op_sel_hi:[1,0,1]
	v_lshl_add_u64 v[36:37], v[128:129], 0, s[12:13]
	v_pk_fma_f32 v[30:31], v[46:47], s[14:15], v[30:31] op_sel_hi:[1,0,1]
	v_pk_fma_f32 v[28:29], v[44:45], s[14:15], v[28:29] op_sel_hi:[1,0,1]
	global_store_dwordx4 v[36:37], v[28:31], off offset:16
	v_pk_fma_f32 v[22:23], v[50:51], s[14:15], v[22:23] op_sel_hi:[1,0,1]
	v_pk_fma_f32 v[20:21], v[48:49], s[14:15], v[20:21] op_sel_hi:[1,0,1]
	v_lshl_add_u64 v[28:29], v[128:129], 0, s[16:17]
	global_store_dwordx4 v[28:29], v[20:23], off offset:16
	v_pk_fma_f32 v[14:15], v[62:63], s[14:15], v[14:15] op_sel_hi:[1,0,1]
	v_pk_fma_f32 v[12:13], v[60:61], s[14:15], v[12:13] op_sel_hi:[1,0,1]
	v_lshl_add_u64 v[20:21], v[128:129], 0, s[18:19]
	v_pk_fma_f32 v[34:35], v[38:39], s[14:15], v[34:35] op_sel_hi:[1,0,1]
	v_pk_fma_f32 v[26:27], v[42:43], s[14:15], v[26:27] op_sel_hi:[1,0,1]
	v_pk_fma_f32 v[24:25], v[40:41], s[14:15], v[24:25] op_sel_hi:[1,0,1]
	v_pk_fma_f32 v[18:19], v[54:55], s[14:15], v[18:19] op_sel_hi:[1,0,1]
	v_pk_fma_f32 v[16:17], v[52:53], s[14:15], v[16:17] op_sel_hi:[1,0,1]
	global_store_dwordx4 v[20:21], v[12:15], off offset:16
	v_pk_fma_f32 v[10:11], v[58:59], s[14:15], v[10:11] op_sel_hi:[1,0,1]
	v_pk_fma_f32 v[8:9], v[56:57], s[14:15], v[8:9] op_sel_hi:[1,0,1]
	v_lshl_add_u64 v[12:13], v[128:129], 0, s[34:35]
	v_pk_fma_f32 v[6:7], v[66:67], s[14:15], v[6:7] op_sel_hi:[1,0,1]
	v_pk_fma_f32 v[4:5], v[64:65], s[14:15], v[4:5] op_sel_hi:[1,0,1]
	s_and_b64 vcc, exec, s[6:7]
	s_mov_b32 s34, s4
	s_mov_b32 s12, s2
	s_mov_b64 s[14:15], s[10:11]
	s_mov_b64 s[16:17], s[8:9]
	global_store_dwordx4 v[70:71], v[32:35], off offset:512
	global_store_dwordx4 v[68:69], v[24:27], off offset:512
	global_store_dwordx4 v[72:73], v[16:19], off offset:512
	global_store_dwordx4 v[74:75], v[8:11], off offset:512
	global_store_dwordx4 v[12:13], v[4:7], off offset:16
	s_cbranch_vccz .LBB0_616
	s_waitcnt vmcnt(0)
	s_cmpk_gt_u32 s20, 0xff
	s_cbranch_scc1 .LBB0_623
	s_barrier
